# plus: accumulator zeroing removed - first K-iteration MFMAs take SrcC=0 via out-of-line segment copies
# speedup vs baseline: 1.0210x; 1.0099x over previous
.LBB0_119:
	s_ashr_i32 s81, s80, 31
	s_lshl_b64 s[52:53], s[80:81], 19
	s_add_u32 s82, s12, s52
	s_addc_u32 s83, s13, s53
	s_and_b64 s[52:53], s[6:7], exec
	s_cselect_b32 s52, s83, s89
	s_cselect_b32 s53, s82, s88
	s_ashr_i32 s79, s78, 31
	s_lshl_b64 s[56:57], s[78:79], 19
	s_add_u32 s84, s14, s56
	s_addc_u32 s85, s15, s57
	s_and_b64 s[56:57], s[6:7], exec
	s_cselect_b32 s56, s85, s91
	s_cselect_b32 s57, s84, s90
	s_add_u32 s88, s88, 0x40080
	s_addc_u32 s89, s89, 0
	s_add_u32 s58, s90, 0x100
	v_mov_b32_e32 v0, 0
	s_addc_u32 s59, s91, 0
	s_mov_b32 s66, -2
	s_waitcnt lgkmcnt(0)
.LBB0_120:
	ds_read_b128 v[128:131], v178
	ds_read_b128 v[132:135], v178 offset:1024
	ds_read_b128 v[154:157], v178 offset:2048
	ds_read_b128 v[158:161], v178 offset:3072
	ds_read_b128 v[162:165], v179
	ds_read_b128 v[166:169], v179 offset:1024
	ds_read_b128 v[182:185], v179 offset:2048
	ds_read_b128 v[186:189], v179 offset:3072
	s_add_u32 s67, s88, 0xfffc0080
	s_addc_u32 s68, s89, -1
	s_cmp_eq_u32 s66, 12
	s_cselect_b32 s93, s52, s68
	s_cselect_b32 s92, s53, s67
	s_cselect_b32 s91, s56, s59
	s_cselect_b32 s90, s57, s58
	v_lshl_add_u64 v[170:171], s[88:89], 0, v[144:145]
	s_add_i32 m0, s17, 0xc000
	ds_read_b128 v[190:193], v180
	ds_read_b128 v[194:197], v180 offset:1024
	ds_read_b128 v[198:201], v180 offset:2048
	ds_read_b128 v[202:205], v180 offset:3072
	ds_read_b128 v[206:209], v180 offset:4096
	ds_read_b128 v[210:213], v180 offset:5120
	ds_read_b128 v[214:217], v180 offset:6144
	ds_read_b128 v[218:221], v180 offset:7168
	global_load_lds_dwordx4 v[170:171], off
	v_lshl_add_u64 v[170:171], s[88:89], 0, v[148:149]
	s_add_i32 m0, s17, 0xe000
	s_nop 0
	global_load_lds_dwordx4 v[170:171], off
	s_cmp_eq_u32 s66, -2
	s_waitcnt vmcnt(8)
	s_waitcnt lgkmcnt(0)
	s_barrier
	s_setprio 1
	s_cbranch_scc1 .Lzv_0_0
	v_mfma_f32_16x16x32_bf16 v[124:127], v[128:131], v[190:193], v[124:127]
	v_mfma_f32_16x16x32_bf16 v[124:127], v[132:135], v[194:197], v[124:127]
	v_mfma_f32_16x16x32_bf16 v[116:119], v[154:157], v[190:193], v[116:119]
	v_mfma_f32_16x16x32_bf16 v[116:119], v[158:161], v[194:197], v[116:119]
	v_mfma_f32_16x16x32_bf16 v[108:111], v[128:131], v[198:201], v[108:111]
	v_mfma_f32_16x16x32_bf16 v[108:111], v[132:135], v[202:205], v[108:111]
	v_mfma_f32_16x16x32_bf16 v[100:103], v[154:157], v[198:201], v[100:103]
	v_mfma_f32_16x16x32_bf16 v[100:103], v[158:161], v[202:205], v[100:103]
	v_mfma_f32_16x16x32_bf16 v[92:95], v[128:131], v[206:209], v[92:95]
	v_mfma_f32_16x16x32_bf16 v[92:95], v[132:135], v[210:213], v[92:95]
	v_mfma_f32_16x16x32_bf16 v[84:87], v[154:157], v[206:209], v[84:87]
	v_mfma_f32_16x16x32_bf16 v[84:87], v[158:161], v[210:213], v[84:87]
	v_mfma_f32_16x16x32_bf16 v[76:79], v[128:131], v[214:217], v[76:79]
	v_mfma_f32_16x16x32_bf16 v[76:79], v[132:135], v[218:221], v[76:79]
	v_mfma_f32_16x16x32_bf16 v[68:71], v[154:157], v[214:217], v[68:71]
	v_mfma_f32_16x16x32_bf16 v[68:71], v[158:161], v[218:221], v[68:71]
	v_mfma_f32_16x16x32_bf16 v[120:123], v[162:165], v[190:193], v[120:123]
	v_mfma_f32_16x16x32_bf16 v[120:123], v[166:169], v[194:197], v[120:123]
	v_mfma_f32_16x16x32_bf16 v[112:115], v[182:185], v[190:193], v[112:115]
	v_mfma_f32_16x16x32_bf16 v[112:115], v[186:189], v[194:197], v[112:115]
	v_mfma_f32_16x16x32_bf16 v[104:107], v[162:165], v[198:201], v[104:107]
	v_mfma_f32_16x16x32_bf16 v[104:107], v[166:169], v[202:205], v[104:107]
	v_mfma_f32_16x16x32_bf16 v[96:99], v[182:185], v[198:201], v[96:99]
	v_mfma_f32_16x16x32_bf16 v[96:99], v[186:189], v[202:205], v[96:99]
	v_mfma_f32_16x16x32_bf16 v[88:91], v[162:165], v[206:209], v[88:91]
	v_mfma_f32_16x16x32_bf16 v[88:91], v[166:169], v[210:213], v[88:91]
	v_mfma_f32_16x16x32_bf16 v[80:83], v[182:185], v[206:209], v[80:83]
	v_mfma_f32_16x16x32_bf16 v[80:83], v[186:189], v[210:213], v[80:83]
	v_mfma_f32_16x16x32_bf16 v[72:75], v[162:165], v[214:217], v[72:75]
	v_mfma_f32_16x16x32_bf16 v[72:75], v[166:169], v[218:221], v[72:75]
	s_setprio 3
	s_barrier
	v_mfma_f32_16x16x32_bf16 v[64:67], v[182:185], v[214:217], v[64:67]
	v_mfma_f32_16x16x32_bf16 v[64:67], v[186:189], v[218:221], v[64:67]
	s_setprio 0
.Lzj_0_0:
	s_add_i32 s67, s25, s16
	v_lshl_add_u64 v[170:171], s[90:91], 0, v[140:141]
	s_mov_b32 m0, s67
	ds_read_b128 v[190:193], v180 offset:16384
	ds_read_b128 v[194:197], v180 offset:17408
	ds_read_b128 v[198:201], v180 offset:18432
	ds_read_b128 v[202:205], v180 offset:19456
	ds_read_b128 v[206:209], v180 offset:20480
	ds_read_b128 v[210:213], v180 offset:21504
	ds_read_b128 v[214:217], v180 offset:22528
	ds_read_b128 v[218:221], v180 offset:23552
	global_load_lds_dwordx4 v[170:171], off
	s_add_i32 m0, s67, 0x2000
	s_add_u32 s68, s90, 0x40000
	v_lshl_add_u64 v[222:223], s[90:91], 0, v[136:137]
	s_addc_u32 s69, s91, 0
	s_add_i32 s67, s26, s16
	global_load_lds_dwordx4 v[222:223], off
	v_lshl_add_u64 v[224:225], s[68:69], 0, v[140:141]
	s_mov_b32 m0, s67
	v_lshl_add_u64 v[226:227], s[92:93], 0, v[138:139]
	global_load_lds_dwordx4 v[224:225], off
	v_lshl_add_u64 v[224:225], s[68:69], 0, v[136:137]
	s_add_i32 m0, s67, 0x2000
	s_nop 0
	global_load_lds_dwordx4 v[224:225], off
	v_lshl_add_u64 v[224:225], s[92:93], 0, v[142:143]
	s_mov_b32 m0, s17
	s_nop 0
	global_load_lds_dwordx4 v[224:225], off
	s_mov_b32 m0, s18
	s_nop 0
	global_load_lds_dwordx4 v[226:227], off
	s_cmp_eq_u32 s66, -2
	s_waitcnt vmcnt(8)
	s_waitcnt lgkmcnt(0)
	s_barrier
	s_setprio 1
	s_cbranch_scc1 .Lzv_0_1
	v_mfma_f32_16x16x32_bf16 v[60:63], v[128:131], v[190:193], v[60:63]
	v_mfma_f32_16x16x32_bf16 v[60:63], v[132:135], v[194:197], v[60:63]
	v_mfma_f32_16x16x32_bf16 v[52:55], v[154:157], v[190:193], v[52:55]
	v_mfma_f32_16x16x32_bf16 v[52:55], v[158:161], v[194:197], v[52:55]
	v_mfma_f32_16x16x32_bf16 v[44:47], v[128:131], v[198:201], v[44:47]
	v_mfma_f32_16x16x32_bf16 v[44:47], v[132:135], v[202:205], v[44:47]
	v_mfma_f32_16x16x32_bf16 v[36:39], v[154:157], v[198:201], v[36:39]
	v_mfma_f32_16x16x32_bf16 v[36:39], v[158:161], v[202:205], v[36:39]
	v_mfma_f32_16x16x32_bf16 v[28:31], v[128:131], v[206:209], v[28:31]
	v_mfma_f32_16x16x32_bf16 v[28:31], v[132:135], v[210:213], v[28:31]
	v_mfma_f32_16x16x32_bf16 v[20:23], v[154:157], v[206:209], v[20:23]
	v_mfma_f32_16x16x32_bf16 v[20:23], v[158:161], v[210:213], v[20:23]
	v_mfma_f32_16x16x32_bf16 v[12:15], v[128:131], v[214:217], v[12:15]
	v_mfma_f32_16x16x32_bf16 v[12:15], v[132:135], v[218:221], v[12:15]
	v_mfma_f32_16x16x32_bf16 v[4:7], v[154:157], v[214:217], v[4:7]
	v_mfma_f32_16x16x32_bf16 v[4:7], v[158:161], v[218:221], v[4:7]
	v_mfma_f32_16x16x32_bf16 v[56:59], v[162:165], v[190:193], v[56:59]
	v_mfma_f32_16x16x32_bf16 v[56:59], v[166:169], v[194:197], v[56:59]
	v_mfma_f32_16x16x32_bf16 v[48:51], v[182:185], v[190:193], v[48:51]
	v_mfma_f32_16x16x32_bf16 v[48:51], v[186:189], v[194:197], v[48:51]
	v_mfma_f32_16x16x32_bf16 v[40:43], v[162:165], v[198:201], v[40:43]
	v_mfma_f32_16x16x32_bf16 v[40:43], v[166:169], v[202:205], v[40:43]
	v_mfma_f32_16x16x32_bf16 v[32:35], v[182:185], v[198:201], v[32:35]
	v_mfma_f32_16x16x32_bf16 v[32:35], v[186:189], v[202:205], v[32:35]
	v_mfma_f32_16x16x32_bf16 v[24:27], v[162:165], v[206:209], v[24:27]
	v_mfma_f32_16x16x32_bf16 v[24:27], v[166:169], v[210:213], v[24:27]
	v_mfma_f32_16x16x32_bf16 v[16:19], v[182:185], v[206:209], v[16:19]
	v_mfma_f32_16x16x32_bf16 v[16:19], v[186:189], v[210:213], v[16:19]
	v_mfma_f32_16x16x32_bf16 v[8:11], v[162:165], v[214:217], v[8:11]
	v_mfma_f32_16x16x32_bf16 v[8:11], v[166:169], v[218:221], v[8:11]
	s_setprio 3
	s_barrier
	v_mfma_f32_16x16x32_bf16 v[0:3], v[182:185], v[214:217], v[0:3]
	v_mfma_f32_16x16x32_bf16 v[0:3], v[186:189], v[218:221], v[0:3]
	s_setprio 0
.Lzj_0_1:
	s_add_i32 s67, 0, 0x18000
	s_add_i32 s73, 0, 0x1c000
	v_add_u32_e32 v158, s67, v175
	v_add_u32_e32 v186, s73, v175
	ds_read_b128 v[128:131], v158
	ds_read_b128 v[132:135], v158 offset:1024
	ds_read_b128 v[154:157], v158 offset:2048
	ds_read_b128 v[158:161], v158 offset:3072
	ds_read_b128 v[162:165], v186
	ds_read_b128 v[166:169], v186 offset:1024
	ds_read_b128 v[182:185], v186 offset:2048
	ds_read_b128 v[186:189], v186 offset:3072
	s_add_u32 s68, s92, 0x40000
	s_addc_u32 s69, s93, 0
	s_mov_b32 m0, s19
	v_lshl_add_u64 v[228:229], s[68:69], 0, v[142:143]
	ds_read_b128 v[190:193], v180 offset:32768
	ds_read_b128 v[194:197], v180 offset:33792
	ds_read_b128 v[198:201], v180 offset:34816
	ds_read_b128 v[202:205], v180 offset:35840
	ds_read_b128 v[206:209], v180 offset:36864
	ds_read_b128 v[210:213], v180 offset:37888
	ds_read_b128 v[214:217], v180 offset:38912
	ds_read_b128 v[218:221], v180 offset:39936
	global_load_lds_dwordx4 v[228:229], off
	v_lshl_add_u64 v[228:229], s[68:69], 0, v[138:139]
	s_mov_b32 m0, s20
	s_nop 0
	global_load_lds_dwordx4 v[228:229], off
	s_waitcnt vmcnt(8)
	s_waitcnt lgkmcnt(0)
	s_barrier
	s_setprio 1
	v_mfma_f32_16x16x32_bf16 v[124:127], v[128:131], v[190:193], v[124:127]
	v_mfma_f32_16x16x32_bf16 v[124:127], v[132:135], v[194:197], v[124:127]
	v_mfma_f32_16x16x32_bf16 v[116:119], v[154:157], v[190:193], v[116:119]
	v_mfma_f32_16x16x32_bf16 v[116:119], v[158:161], v[194:197], v[116:119]
	v_mfma_f32_16x16x32_bf16 v[108:111], v[128:131], v[198:201], v[108:111]
	v_mfma_f32_16x16x32_bf16 v[108:111], v[132:135], v[202:205], v[108:111]
	v_mfma_f32_16x16x32_bf16 v[100:103], v[154:157], v[198:201], v[100:103]
	v_mfma_f32_16x16x32_bf16 v[100:103], v[158:161], v[202:205], v[100:103]
	v_mfma_f32_16x16x32_bf16 v[92:95], v[128:131], v[206:209], v[92:95]
	v_mfma_f32_16x16x32_bf16 v[92:95], v[132:135], v[210:213], v[92:95]
	v_mfma_f32_16x16x32_bf16 v[84:87], v[154:157], v[206:209], v[84:87]
	v_mfma_f32_16x16x32_bf16 v[84:87], v[158:161], v[210:213], v[84:87]
	v_mfma_f32_16x16x32_bf16 v[76:79], v[128:131], v[214:217], v[76:79]
	v_mfma_f32_16x16x32_bf16 v[76:79], v[132:135], v[218:221], v[76:79]
	v_mfma_f32_16x16x32_bf16 v[68:71], v[154:157], v[214:217], v[68:71]
	v_mfma_f32_16x16x32_bf16 v[68:71], v[158:161], v[218:221], v[68:71]
	v_mfma_f32_16x16x32_bf16 v[120:123], v[162:165], v[190:193], v[120:123]
	v_mfma_f32_16x16x32_bf16 v[120:123], v[166:169], v[194:197], v[120:123]
	v_mfma_f32_16x16x32_bf16 v[112:115], v[182:185], v[190:193], v[112:115]
	v_mfma_f32_16x16x32_bf16 v[112:115], v[186:189], v[194:197], v[112:115]
	v_mfma_f32_16x16x32_bf16 v[104:107], v[162:165], v[198:201], v[104:107]
	v_mfma_f32_16x16x32_bf16 v[104:107], v[166:169], v[202:205], v[104:107]
	v_mfma_f32_16x16x32_bf16 v[96:99], v[182:185], v[198:201], v[96:99]
	v_mfma_f32_16x16x32_bf16 v[96:99], v[186:189], v[202:205], v[96:99]
	v_mfma_f32_16x16x32_bf16 v[88:91], v[162:165], v[206:209], v[88:91]
	v_mfma_f32_16x16x32_bf16 v[88:91], v[166:169], v[210:213], v[88:91]
	v_mfma_f32_16x16x32_bf16 v[80:83], v[182:185], v[206:209], v[80:83]
	v_mfma_f32_16x16x32_bf16 v[80:83], v[186:189], v[210:213], v[80:83]
	v_mfma_f32_16x16x32_bf16 v[72:75], v[162:165], v[214:217], v[72:75]
	v_mfma_f32_16x16x32_bf16 v[72:75], v[166:169], v[218:221], v[72:75]
	s_setprio 3
	s_barrier
	v_mfma_f32_16x16x32_bf16 v[64:67], v[182:185], v[214:217], v[64:67]
	v_mfma_f32_16x16x32_bf16 v[64:67], v[186:189], v[218:221], v[64:67]
	s_setprio 0
	s_add_i32 s67, s67, s16
	v_lshl_add_u64 v[170:171], v[170:171], 0, s[74:75]
	s_mov_b32 m0, s67
	ds_read_b128 v[190:193], v180 offset:49152
	ds_read_b128 v[194:197], v180 offset:50176
	ds_read_b128 v[198:201], v180 offset:51200
	ds_read_b128 v[202:205], v180 offset:52224
	ds_read_b128 v[206:209], v180 offset:53248
	ds_read_b128 v[210:213], v180 offset:54272
	ds_read_b128 v[214:217], v180 offset:55296
	ds_read_b128 v[218:221], v180 offset:56320
	global_load_lds_dwordx4 v[170:171], off
	s_add_i32 m0, s67, 0x2000
	s_add_u32 s68, s90, 0x40080
	v_lshl_add_u64 v[170:171], v[222:223], 0, s[74:75]
	s_addc_u32 s69, s91, 0
	s_add_i32 s67, s73, s16
	global_load_lds_dwordx4 v[170:171], off
	v_lshl_add_u64 v[170:171], s[68:69], 0, v[140:141]
	s_mov_b32 m0, s67
	s_nop 0
	global_load_lds_dwordx4 v[170:171], off
	v_lshl_add_u64 v[170:171], s[68:69], 0, v[136:137]
	s_add_i32 m0, s67, 0x2000
	s_nop 0
	global_load_lds_dwordx4 v[170:171], off
	v_lshl_add_u64 v[170:171], v[224:225], 0, s[74:75]
	s_mov_b32 m0, s23
	s_nop 0
	global_load_lds_dwordx4 v[170:171], off
	v_lshl_add_u64 v[170:171], v[226:227], 0, s[74:75]
	s_mov_b32 m0, s24
	s_nop 0
	global_load_lds_dwordx4 v[170:171], off
	s_waitcnt vmcnt(8)
	s_waitcnt lgkmcnt(0)
	s_barrier
	s_setprio 1
	v_mfma_f32_16x16x32_bf16 v[60:63], v[128:131], v[190:193], v[60:63]
	v_mfma_f32_16x16x32_bf16 v[60:63], v[132:135], v[194:197], v[60:63]
	v_mfma_f32_16x16x32_bf16 v[52:55], v[154:157], v[190:193], v[52:55]
	v_mfma_f32_16x16x32_bf16 v[52:55], v[158:161], v[194:197], v[52:55]
	v_mfma_f32_16x16x32_bf16 v[44:47], v[128:131], v[198:201], v[44:47]
	v_mfma_f32_16x16x32_bf16 v[44:47], v[132:135], v[202:205], v[44:47]
	v_mfma_f32_16x16x32_bf16 v[36:39], v[154:157], v[198:201], v[36:39]
	v_mfma_f32_16x16x32_bf16 v[36:39], v[158:161], v[202:205], v[36:39]
	v_mfma_f32_16x16x32_bf16 v[28:31], v[128:131], v[206:209], v[28:31]
	v_mfma_f32_16x16x32_bf16 v[28:31], v[132:135], v[210:213], v[28:31]
	v_mfma_f32_16x16x32_bf16 v[20:23], v[154:157], v[206:209], v[20:23]
	v_mfma_f32_16x16x32_bf16 v[20:23], v[158:161], v[210:213], v[20:23]
	v_mfma_f32_16x16x32_bf16 v[12:15], v[128:131], v[214:217], v[12:15]
	v_mfma_f32_16x16x32_bf16 v[12:15], v[132:135], v[218:221], v[12:15]
	v_mfma_f32_16x16x32_bf16 v[4:7], v[154:157], v[214:217], v[4:7]
	v_mfma_f32_16x16x32_bf16 v[4:7], v[158:161], v[218:221], v[4:7]
	v_mfma_f32_16x16x32_bf16 v[56:59], v[162:165], v[190:193], v[56:59]
	v_mfma_f32_16x16x32_bf16 v[56:59], v[166:169], v[194:197], v[56:59]
	v_mfma_f32_16x16x32_bf16 v[48:51], v[182:185], v[190:193], v[48:51]
	v_mfma_f32_16x16x32_bf16 v[48:51], v[186:189], v[194:197], v[48:51]
	v_mfma_f32_16x16x32_bf16 v[40:43], v[162:165], v[198:201], v[40:43]
	v_mfma_f32_16x16x32_bf16 v[40:43], v[166:169], v[202:205], v[40:43]
	v_mfma_f32_16x16x32_bf16 v[32:35], v[182:185], v[198:201], v[32:35]
	v_mfma_f32_16x16x32_bf16 v[32:35], v[186:189], v[202:205], v[32:35]
	v_mfma_f32_16x16x32_bf16 v[24:27], v[162:165], v[206:209], v[24:27]
	v_mfma_f32_16x16x32_bf16 v[24:27], v[166:169], v[210:213], v[24:27]
	v_mfma_f32_16x16x32_bf16 v[16:19], v[182:185], v[206:209], v[16:19]
	v_mfma_f32_16x16x32_bf16 v[16:19], v[186:189], v[210:213], v[16:19]
	v_mfma_f32_16x16x32_bf16 v[8:11], v[162:165], v[214:217], v[8:11]
	v_mfma_f32_16x16x32_bf16 v[8:11], v[166:169], v[218:221], v[8:11]
	s_setprio 3
	s_barrier
	v_mfma_f32_16x16x32_bf16 v[0:3], v[182:185], v[214:217], v[0:3]
	v_mfma_f32_16x16x32_bf16 v[0:3], v[186:189], v[218:221], v[0:3]
	s_setprio 0
	s_add_i32 s66, s66, 2
	s_add_u32 s88, s88, 0x100
	s_addc_u32 s89, s89, 0
	s_add_u32 s58, s58, 0x100
	s_addc_u32 s59, s59, 0
	s_cmp_gt_u32 s66, 13
	s_cbranch_scc0 .LBB0_120
	s_branch .Lzskip_0
.Lzv_0_0:
	v_mfma_f32_16x16x32_bf16 v[124:127], v[128:131], v[190:193], 0
	v_mfma_f32_16x16x32_bf16 v[124:127], v[132:135], v[194:197], v[124:127]
	v_mfma_f32_16x16x32_bf16 v[116:119], v[154:157], v[190:193], 0
	v_mfma_f32_16x16x32_bf16 v[116:119], v[158:161], v[194:197], v[116:119]
	v_mfma_f32_16x16x32_bf16 v[108:111], v[128:131], v[198:201], 0
	v_mfma_f32_16x16x32_bf16 v[108:111], v[132:135], v[202:205], v[108:111]
	v_mfma_f32_16x16x32_bf16 v[100:103], v[154:157], v[198:201], 0
	v_mfma_f32_16x16x32_bf16 v[100:103], v[158:161], v[202:205], v[100:103]
	v_mfma_f32_16x16x32_bf16 v[92:95], v[128:131], v[206:209], 0
	v_mfma_f32_16x16x32_bf16 v[92:95], v[132:135], v[210:213], v[92:95]
	v_mfma_f32_16x16x32_bf16 v[84:87], v[154:157], v[206:209], 0
	v_mfma_f32_16x16x32_bf16 v[84:87], v[158:161], v[210:213], v[84:87]
	v_mfma_f32_16x16x32_bf16 v[76:79], v[128:131], v[214:217], 0
	v_mfma_f32_16x16x32_bf16 v[76:79], v[132:135], v[218:221], v[76:79]
	v_mfma_f32_16x16x32_bf16 v[68:71], v[154:157], v[214:217], 0
	v_mfma_f32_16x16x32_bf16 v[68:71], v[158:161], v[218:221], v[68:71]
	v_mfma_f32_16x16x32_bf16 v[120:123], v[162:165], v[190:193], 0
	v_mfma_f32_16x16x32_bf16 v[120:123], v[166:169], v[194:197], v[120:123]
	v_mfma_f32_16x16x32_bf16 v[112:115], v[182:185], v[190:193], 0
	v_mfma_f32_16x16x32_bf16 v[112:115], v[186:189], v[194:197], v[112:115]
	v_mfma_f32_16x16x32_bf16 v[104:107], v[162:165], v[198:201], 0
	v_mfma_f32_16x16x32_bf16 v[104:107], v[166:169], v[202:205], v[104:107]
	v_mfma_f32_16x16x32_bf16 v[96:99], v[182:185], v[198:201], 0
	v_mfma_f32_16x16x32_bf16 v[96:99], v[186:189], v[202:205], v[96:99]
	v_mfma_f32_16x16x32_bf16 v[88:91], v[162:165], v[206:209], 0
	v_mfma_f32_16x16x32_bf16 v[88:91], v[166:169], v[210:213], v[88:91]
	v_mfma_f32_16x16x32_bf16 v[80:83], v[182:185], v[206:209], 0
	v_mfma_f32_16x16x32_bf16 v[80:83], v[186:189], v[210:213], v[80:83]
	v_mfma_f32_16x16x32_bf16 v[72:75], v[162:165], v[214:217], 0
	v_mfma_f32_16x16x32_bf16 v[72:75], v[166:169], v[218:221], v[72:75]
	s_setprio 3
	s_barrier
	v_mfma_f32_16x16x32_bf16 v[64:67], v[182:185], v[214:217], 0
	v_mfma_f32_16x16x32_bf16 v[64:67], v[186:189], v[218:221], v[64:67]
	s_setprio 0
	s_branch .Lzj_0_0
.Lzv_0_1:
	v_mfma_f32_16x16x32_bf16 v[60:63], v[128:131], v[190:193], 0
	v_mfma_f32_16x16x32_bf16 v[60:63], v[132:135], v[194:197], v[60:63]
	v_mfma_f32_16x16x32_bf16 v[52:55], v[154:157], v[190:193], 0
	v_mfma_f32_16x16x32_bf16 v[52:55], v[158:161], v[194:197], v[52:55]
	v_mfma_f32_16x16x32_bf16 v[44:47], v[128:131], v[198:201], 0
	v_mfma_f32_16x16x32_bf16 v[44:47], v[132:135], v[202:205], v[44:47]
	v_mfma_f32_16x16x32_bf16 v[36:39], v[154:157], v[198:201], 0
	v_mfma_f32_16x16x32_bf16 v[36:39], v[158:161], v[202:205], v[36:39]
	v_mfma_f32_16x16x32_bf16 v[28:31], v[128:131], v[206:209], 0
	v_mfma_f32_16x16x32_bf16 v[28:31], v[132:135], v[210:213], v[28:31]
	v_mfma_f32_16x16x32_bf16 v[20:23], v[154:157], v[206:209], 0
	v_mfma_f32_16x16x32_bf16 v[20:23], v[158:161], v[210:213], v[20:23]
	v_mfma_f32_16x16x32_bf16 v[12:15], v[128:131], v[214:217], 0
	v_mfma_f32_16x16x32_bf16 v[12:15], v[132:135], v[218:221], v[12:15]
	v_mfma_f32_16x16x32_bf16 v[4:7], v[154:157], v[214:217], 0
	v_mfma_f32_16x16x32_bf16 v[4:7], v[158:161], v[218:221], v[4:7]
	v_mfma_f32_16x16x32_bf16 v[56:59], v[162:165], v[190:193], 0
	v_mfma_f32_16x16x32_bf16 v[56:59], v[166:169], v[194:197], v[56:59]
	v_mfma_f32_16x16x32_bf16 v[48:51], v[182:185], v[190:193], 0
	v_mfma_f32_16x16x32_bf16 v[48:51], v[186:189], v[194:197], v[48:51]
	v_mfma_f32_16x16x32_bf16 v[40:43], v[162:165], v[198:201], 0
	v_mfma_f32_16x16x32_bf16 v[40:43], v[166:169], v[202:205], v[40:43]
	v_mfma_f32_16x16x32_bf16 v[32:35], v[182:185], v[198:201], 0
	v_mfma_f32_16x16x32_bf16 v[32:35], v[186:189], v[202:205], v[32:35]
	v_mfma_f32_16x16x32_bf16 v[24:27], v[162:165], v[206:209], 0
	v_mfma_f32_16x16x32_bf16 v[24:27], v[166:169], v[210:213], v[24:27]
	v_mfma_f32_16x16x32_bf16 v[16:19], v[182:185], v[206:209], 0
	v_mfma_f32_16x16x32_bf16 v[16:19], v[186:189], v[210:213], v[16:19]
	v_mfma_f32_16x16x32_bf16 v[8:11], v[162:165], v[214:217], 0
	v_mfma_f32_16x16x32_bf16 v[8:11], v[166:169], v[218:221], v[8:11]
	s_setprio 3
	s_barrier
	v_mfma_f32_16x16x32_bf16 v[0:3], v[182:185], v[214:217], 0
	v_mfma_f32_16x16x32_bf16 v[0:3], v[186:189], v[218:221], v[0:3]
	s_setprio 0
	s_branch .Lzj_0_1
.Lzskip_0:
	s_and_b64 vcc, exec, s[76:77]
	s_cbranch_vccz .LBB0_123
	s_barrier

.LBB0_272:
	ds_read_b128 v[120:123], v245
	ds_read_b128 v[124:127], v245 offset:1024
	ds_read_b128 v[128:131], v245 offset:2048
	ds_read_b128 v[132:135], v245 offset:3072
	ds_read_b128 v[144:147], v246
	ds_read_b128 v[148:151], v246 offset:1024
	ds_read_b128 v[152:155], v246 offset:2048
	ds_read_b128 v[156:159], v246 offset:3072
	s_add_u32 s59, s86, 0xfff50080
	s_addc_u32 s66, s87, -1
	s_cmp_eq_u32 s58, 40
	s_cselect_b32 s91, s11, s66
	s_cselect_b32 s90, s10, s59
	s_cselect_b32 s89, s85, s57
	s_cselect_b32 s88, s84, s56
	v_lshl_add_u64 v[204:205], s[86:87], 0, v[200:201]
	s_add_i32 m0, s16, 0xc000
	ds_read_b128 v[160:163], v247
	ds_read_b128 v[164:167], v247 offset:1024
	ds_read_b128 v[168:171], v247 offset:2048
	ds_read_b128 v[172:175], v247 offset:3072
	ds_read_b128 v[176:179], v247 offset:4096
	ds_read_b128 v[180:183], v247 offset:5120
	ds_read_b128 v[184:187], v247 offset:6144
	ds_read_b128 v[188:191], v247 offset:7168
	global_load_lds_dwordx4 v[204:205], off
	v_lshl_add_u64 v[204:205], s[86:87], 0, v[202:203]
	s_add_i32 m0, s16, 0xe000
	s_nop 0
	global_load_lds_dwordx4 v[204:205], off
	s_cmp_eq_u32 s58, -2
	s_waitcnt vmcnt(8)
	s_waitcnt lgkmcnt(0)
	s_barrier
	s_setprio 1
	s_cbranch_scc1 .Lzv_1_0
	v_mfma_f32_16x16x32_bf16 v[140:143], v[120:123], v[160:163], v[140:143]
	v_mfma_f32_16x16x32_bf16 v[140:143], v[124:127], v[164:167], v[140:143]
	v_mfma_f32_16x16x32_bf16 v[136:139], v[128:131], v[160:163], v[136:139]
	v_mfma_f32_16x16x32_bf16 v[136:139], v[132:135], v[164:167], v[136:139]
	v_mfma_f32_16x16x32_bf16 v[108:111], v[120:123], v[168:171], v[108:111]
	v_mfma_f32_16x16x32_bf16 v[108:111], v[124:127], v[172:175], v[108:111]
	v_mfma_f32_16x16x32_bf16 v[104:107], v[128:131], v[168:171], v[104:107]
	v_mfma_f32_16x16x32_bf16 v[104:107], v[132:135], v[172:175], v[104:107]
	v_mfma_f32_16x16x32_bf16 v[92:95], v[120:123], v[176:179], v[92:95]
	v_mfma_f32_16x16x32_bf16 v[92:95], v[124:127], v[180:183], v[92:95]
	v_mfma_f32_16x16x32_bf16 v[88:91], v[128:131], v[176:179], v[88:91]
	v_mfma_f32_16x16x32_bf16 v[88:91], v[132:135], v[180:183], v[88:91]
	v_mfma_f32_16x16x32_bf16 v[76:79], v[120:123], v[184:187], v[76:79]
	v_mfma_f32_16x16x32_bf16 v[76:79], v[124:127], v[188:191], v[76:79]
	v_mfma_f32_16x16x32_bf16 v[72:75], v[128:131], v[184:187], v[72:75]
	v_mfma_f32_16x16x32_bf16 v[72:75], v[132:135], v[188:191], v[72:75]
	v_mfma_f32_16x16x32_bf16 v[116:119], v[144:147], v[160:163], v[116:119]
	v_mfma_f32_16x16x32_bf16 v[116:119], v[148:151], v[164:167], v[116:119]
	v_mfma_f32_16x16x32_bf16 v[112:115], v[152:155], v[160:163], v[112:115]
	v_mfma_f32_16x16x32_bf16 v[112:115], v[156:159], v[164:167], v[112:115]
	v_mfma_f32_16x16x32_bf16 v[100:103], v[144:147], v[168:171], v[100:103]
	v_mfma_f32_16x16x32_bf16 v[100:103], v[148:151], v[172:175], v[100:103]
	v_mfma_f32_16x16x32_bf16 v[96:99], v[152:155], v[168:171], v[96:99]
	v_mfma_f32_16x16x32_bf16 v[96:99], v[156:159], v[172:175], v[96:99]
	v_mfma_f32_16x16x32_bf16 v[84:87], v[144:147], v[176:179], v[84:87]
	v_mfma_f32_16x16x32_bf16 v[84:87], v[148:151], v[180:183], v[84:87]
	v_mfma_f32_16x16x32_bf16 v[80:83], v[152:155], v[176:179], v[80:83]
	v_mfma_f32_16x16x32_bf16 v[80:83], v[156:159], v[180:183], v[80:83]
	v_mfma_f32_16x16x32_bf16 v[68:71], v[144:147], v[184:187], v[68:71]
	v_mfma_f32_16x16x32_bf16 v[68:71], v[148:151], v[188:191], v[68:71]
	s_setprio 3
	s_barrier
	v_mfma_f32_16x16x32_bf16 v[64:67], v[152:155], v[184:187], v[64:67]
	v_mfma_f32_16x16x32_bf16 v[64:67], v[156:159], v[188:191], v[64:67]
	s_setprio 0
.Lzj_1_0:
	s_add_i32 s59, s26, s15
	v_lshl_add_u64 v[204:205], s[88:89], 0, v[194:195]
	s_mov_b32 m0, s59
	ds_read_b128 v[160:163], v247 offset:16384
	ds_read_b128 v[164:167], v247 offset:17408
	ds_read_b128 v[168:171], v247 offset:18432
	ds_read_b128 v[172:175], v247 offset:19456
	ds_read_b128 v[176:179], v247 offset:20480
	ds_read_b128 v[180:183], v247 offset:21504
	ds_read_b128 v[184:187], v247 offset:22528
	ds_read_b128 v[188:191], v247 offset:23552
	global_load_lds_dwordx4 v[204:205], off
	s_add_i32 m0, s59, 0x2000
	s_add_u32 s66, s88, 0xb0000
	v_lshl_add_u64 v[206:207], s[88:89], 0, v[198:199]
	s_addc_u32 s67, s89, 0
	s_add_i32 s59, s27, s15
	global_load_lds_dwordx4 v[206:207], off
	v_lshl_add_u64 v[208:209], s[66:67], 0, v[194:195]
	s_mov_b32 m0, s59
	v_lshl_add_u64 v[210:211], s[90:91], 0, v[196:197]
	global_load_lds_dwordx4 v[208:209], off
	v_lshl_add_u64 v[208:209], s[66:67], 0, v[198:199]
	s_add_i32 m0, s59, 0x2000
	s_nop 0
	global_load_lds_dwordx4 v[208:209], off
	v_lshl_add_u64 v[208:209], s[90:91], 0, v[192:193]
	s_mov_b32 m0, s16
	s_nop 0
	global_load_lds_dwordx4 v[208:209], off
	s_mov_b32 m0, s17
	s_nop 0
	global_load_lds_dwordx4 v[210:211], off
	s_cmp_eq_u32 s58, -2
	s_waitcnt vmcnt(8)
	s_waitcnt lgkmcnt(0)
	s_barrier
	s_setprio 1
	s_cbranch_scc1 .Lzv_1_1
	v_mfma_f32_16x16x32_bf16 v[60:63], v[120:123], v[160:163], v[60:63]
	v_mfma_f32_16x16x32_bf16 v[60:63], v[124:127], v[164:167], v[60:63]
	v_mfma_f32_16x16x32_bf16 v[56:59], v[128:131], v[160:163], v[56:59]
	v_mfma_f32_16x16x32_bf16 v[56:59], v[132:135], v[164:167], v[56:59]
	v_mfma_f32_16x16x32_bf16 v[44:47], v[120:123], v[168:171], v[44:47]
	v_mfma_f32_16x16x32_bf16 v[44:47], v[124:127], v[172:175], v[44:47]
	v_mfma_f32_16x16x32_bf16 v[40:43], v[128:131], v[168:171], v[40:43]
	v_mfma_f32_16x16x32_bf16 v[40:43], v[132:135], v[172:175], v[40:43]
	v_mfma_f32_16x16x32_bf16 v[28:31], v[120:123], v[176:179], v[28:31]
	v_mfma_f32_16x16x32_bf16 v[28:31], v[124:127], v[180:183], v[28:31]
	v_mfma_f32_16x16x32_bf16 v[24:27], v[128:131], v[176:179], v[24:27]
	v_mfma_f32_16x16x32_bf16 v[24:27], v[132:135], v[180:183], v[24:27]
	v_mfma_f32_16x16x32_bf16 v[12:15], v[120:123], v[184:187], v[12:15]
	v_mfma_f32_16x16x32_bf16 v[12:15], v[124:127], v[188:191], v[12:15]
	v_mfma_f32_16x16x32_bf16 v[8:11], v[128:131], v[184:187], v[8:11]
	v_mfma_f32_16x16x32_bf16 v[8:11], v[132:135], v[188:191], v[8:11]
	v_mfma_f32_16x16x32_bf16 v[52:55], v[144:147], v[160:163], v[52:55]
	v_mfma_f32_16x16x32_bf16 v[52:55], v[148:151], v[164:167], v[52:55]
	v_mfma_f32_16x16x32_bf16 v[48:51], v[152:155], v[160:163], v[48:51]
	v_mfma_f32_16x16x32_bf16 v[48:51], v[156:159], v[164:167], v[48:51]
	v_mfma_f32_16x16x32_bf16 v[36:39], v[144:147], v[168:171], v[36:39]
	v_mfma_f32_16x16x32_bf16 v[36:39], v[148:151], v[172:175], v[36:39]
	v_mfma_f32_16x16x32_bf16 v[32:35], v[152:155], v[168:171], v[32:35]
	v_mfma_f32_16x16x32_bf16 v[32:35], v[156:159], v[172:175], v[32:35]
	v_mfma_f32_16x16x32_bf16 v[20:23], v[144:147], v[176:179], v[20:23]
	v_mfma_f32_16x16x32_bf16 v[20:23], v[148:151], v[180:183], v[20:23]
	v_mfma_f32_16x16x32_bf16 v[16:19], v[152:155], v[176:179], v[16:19]
	v_mfma_f32_16x16x32_bf16 v[16:19], v[156:159], v[180:183], v[16:19]
	v_mfma_f32_16x16x32_bf16 v[4:7], v[144:147], v[184:187], v[4:7]
	v_mfma_f32_16x16x32_bf16 v[4:7], v[148:151], v[188:191], v[4:7]
	s_setprio 3
	s_barrier
	v_mfma_f32_16x16x32_bf16 v[0:3], v[152:155], v[184:187], v[0:3]
	v_mfma_f32_16x16x32_bf16 v[0:3], v[156:159], v[188:191], v[0:3]
	s_setprio 0
.Lzj_1_1:
	s_add_i32 s59, 0, 0x18000
	s_add_i32 s68, 0, 0x1c000
	v_add_u32_e32 v132, s59, v243
	v_add_u32_e32 v156, s68, v243
	ds_read_b128 v[120:123], v132
	ds_read_b128 v[124:127], v132 offset:1024
	ds_read_b128 v[128:131], v132 offset:2048
	ds_read_b128 v[132:135], v132 offset:3072
	ds_read_b128 v[144:147], v156
	ds_read_b128 v[148:151], v156 offset:1024
	ds_read_b128 v[152:155], v156 offset:2048
	ds_read_b128 v[156:159], v156 offset:3072
	s_add_u32 s66, s90, 0xb0000
	s_addc_u32 s67, s91, 0
	s_mov_b32 m0, s18
	v_lshl_add_u64 v[212:213], s[66:67], 0, v[192:193]
	ds_read_b128 v[160:163], v247 offset:32768
	ds_read_b128 v[164:167], v247 offset:33792
	ds_read_b128 v[168:171], v247 offset:34816
	ds_read_b128 v[172:175], v247 offset:35840
	ds_read_b128 v[176:179], v247 offset:36864
	ds_read_b128 v[180:183], v247 offset:37888
	ds_read_b128 v[184:187], v247 offset:38912
	ds_read_b128 v[188:191], v247 offset:39936
	global_load_lds_dwordx4 v[212:213], off
	v_lshl_add_u64 v[212:213], s[66:67], 0, v[196:197]
	s_mov_b32 m0, s19
	s_nop 0
	global_load_lds_dwordx4 v[212:213], off
	s_waitcnt vmcnt(8)
	s_waitcnt lgkmcnt(0)
	s_barrier
	s_setprio 1
	v_mfma_f32_16x16x32_bf16 v[140:143], v[120:123], v[160:163], v[140:143]
	v_mfma_f32_16x16x32_bf16 v[140:143], v[124:127], v[164:167], v[140:143]
	v_mfma_f32_16x16x32_bf16 v[136:139], v[128:131], v[160:163], v[136:139]
	v_mfma_f32_16x16x32_bf16 v[136:139], v[132:135], v[164:167], v[136:139]
	v_mfma_f32_16x16x32_bf16 v[108:111], v[120:123], v[168:171], v[108:111]
	v_mfma_f32_16x16x32_bf16 v[108:111], v[124:127], v[172:175], v[108:111]
	v_mfma_f32_16x16x32_bf16 v[104:107], v[128:131], v[168:171], v[104:107]
	v_mfma_f32_16x16x32_bf16 v[104:107], v[132:135], v[172:175], v[104:107]
	v_mfma_f32_16x16x32_bf16 v[92:95], v[120:123], v[176:179], v[92:95]
	v_mfma_f32_16x16x32_bf16 v[92:95], v[124:127], v[180:183], v[92:95]
	v_mfma_f32_16x16x32_bf16 v[88:91], v[128:131], v[176:179], v[88:91]
	v_mfma_f32_16x16x32_bf16 v[88:91], v[132:135], v[180:183], v[88:91]
	v_mfma_f32_16x16x32_bf16 v[76:79], v[120:123], v[184:187], v[76:79]
	v_mfma_f32_16x16x32_bf16 v[76:79], v[124:127], v[188:191], v[76:79]
	v_mfma_f32_16x16x32_bf16 v[72:75], v[128:131], v[184:187], v[72:75]
	v_mfma_f32_16x16x32_bf16 v[72:75], v[132:135], v[188:191], v[72:75]
	v_mfma_f32_16x16x32_bf16 v[116:119], v[144:147], v[160:163], v[116:119]
	v_mfma_f32_16x16x32_bf16 v[116:119], v[148:151], v[164:167], v[116:119]
	v_mfma_f32_16x16x32_bf16 v[112:115], v[152:155], v[160:163], v[112:115]
	v_mfma_f32_16x16x32_bf16 v[112:115], v[156:159], v[164:167], v[112:115]
	v_mfma_f32_16x16x32_bf16 v[100:103], v[144:147], v[168:171], v[100:103]
	v_mfma_f32_16x16x32_bf16 v[100:103], v[148:151], v[172:175], v[100:103]
	v_mfma_f32_16x16x32_bf16 v[96:99], v[152:155], v[168:171], v[96:99]
	v_mfma_f32_16x16x32_bf16 v[96:99], v[156:159], v[172:175], v[96:99]
	v_mfma_f32_16x16x32_bf16 v[84:87], v[144:147], v[176:179], v[84:87]
	v_mfma_f32_16x16x32_bf16 v[84:87], v[148:151], v[180:183], v[84:87]
	v_mfma_f32_16x16x32_bf16 v[80:83], v[152:155], v[176:179], v[80:83]
	v_mfma_f32_16x16x32_bf16 v[80:83], v[156:159], v[180:183], v[80:83]
	v_mfma_f32_16x16x32_bf16 v[68:71], v[144:147], v[184:187], v[68:71]
	v_mfma_f32_16x16x32_bf16 v[68:71], v[148:151], v[188:191], v[68:71]
	s_setprio 3
	s_barrier
	v_mfma_f32_16x16x32_bf16 v[64:67], v[152:155], v[184:187], v[64:67]
	v_mfma_f32_16x16x32_bf16 v[64:67], v[156:159], v[188:191], v[64:67]
	s_setprio 0
	s_add_i32 s59, s59, s15
	v_lshl_add_u64 v[204:205], v[204:205], 0, s[80:81]
	s_mov_b32 m0, s59
	ds_read_b128 v[160:163], v247 offset:49152
	ds_read_b128 v[164:167], v247 offset:50176
	ds_read_b128 v[168:171], v247 offset:51200
	ds_read_b128 v[172:175], v247 offset:52224
	ds_read_b128 v[176:179], v247 offset:53248
	ds_read_b128 v[180:183], v247 offset:54272
	ds_read_b128 v[184:187], v247 offset:55296
	ds_read_b128 v[188:191], v247 offset:56320
	global_load_lds_dwordx4 v[204:205], off
	s_add_i32 m0, s59, 0x2000
	s_add_u32 s66, s88, 0xb0080
	v_lshl_add_u64 v[204:205], v[206:207], 0, s[80:81]
	s_addc_u32 s67, s89, 0
	s_add_i32 s59, s68, s15
	global_load_lds_dwordx4 v[204:205], off
	v_lshl_add_u64 v[204:205], s[66:67], 0, v[194:195]
	s_mov_b32 m0, s59
	s_nop 0
	global_load_lds_dwordx4 v[204:205], off
	v_lshl_add_u64 v[204:205], s[66:67], 0, v[198:199]
	s_add_i32 m0, s59, 0x2000
	s_nop 0
	global_load_lds_dwordx4 v[204:205], off
	v_lshl_add_u64 v[204:205], v[208:209], 0, s[80:81]
	s_mov_b32 m0, s21
	s_nop 0
	global_load_lds_dwordx4 v[204:205], off
	v_lshl_add_u64 v[204:205], v[210:211], 0, s[80:81]
	s_mov_b32 m0, s22
	s_nop 0
	global_load_lds_dwordx4 v[204:205], off
	s_waitcnt vmcnt(8)
	s_waitcnt lgkmcnt(0)
	s_barrier
	s_setprio 1
	v_mfma_f32_16x16x32_bf16 v[60:63], v[120:123], v[160:163], v[60:63]
	v_mfma_f32_16x16x32_bf16 v[60:63], v[124:127], v[164:167], v[60:63]
	v_mfma_f32_16x16x32_bf16 v[56:59], v[128:131], v[160:163], v[56:59]
	v_mfma_f32_16x16x32_bf16 v[56:59], v[132:135], v[164:167], v[56:59]
	v_mfma_f32_16x16x32_bf16 v[44:47], v[120:123], v[168:171], v[44:47]
	v_mfma_f32_16x16x32_bf16 v[44:47], v[124:127], v[172:175], v[44:47]
	v_mfma_f32_16x16x32_bf16 v[40:43], v[128:131], v[168:171], v[40:43]
	v_mfma_f32_16x16x32_bf16 v[40:43], v[132:135], v[172:175], v[40:43]
	v_mfma_f32_16x16x32_bf16 v[28:31], v[120:123], v[176:179], v[28:31]
	v_mfma_f32_16x16x32_bf16 v[28:31], v[124:127], v[180:183], v[28:31]
	v_mfma_f32_16x16x32_bf16 v[24:27], v[128:131], v[176:179], v[24:27]
	v_mfma_f32_16x16x32_bf16 v[24:27], v[132:135], v[180:183], v[24:27]
	v_mfma_f32_16x16x32_bf16 v[12:15], v[120:123], v[184:187], v[12:15]
	v_mfma_f32_16x16x32_bf16 v[12:15], v[124:127], v[188:191], v[12:15]
	v_mfma_f32_16x16x32_bf16 v[8:11], v[128:131], v[184:187], v[8:11]
	v_mfma_f32_16x16x32_bf16 v[8:11], v[132:135], v[188:191], v[8:11]
	v_mfma_f32_16x16x32_bf16 v[52:55], v[144:147], v[160:163], v[52:55]
	v_mfma_f32_16x16x32_bf16 v[52:55], v[148:151], v[164:167], v[52:55]
	v_mfma_f32_16x16x32_bf16 v[48:51], v[152:155], v[160:163], v[48:51]
	v_mfma_f32_16x16x32_bf16 v[48:51], v[156:159], v[164:167], v[48:51]
	v_mfma_f32_16x16x32_bf16 v[36:39], v[144:147], v[168:171], v[36:39]
	v_mfma_f32_16x16x32_bf16 v[36:39], v[148:151], v[172:175], v[36:39]
	v_mfma_f32_16x16x32_bf16 v[32:35], v[152:155], v[168:171], v[32:35]
	v_mfma_f32_16x16x32_bf16 v[32:35], v[156:159], v[172:175], v[32:35]
	v_mfma_f32_16x16x32_bf16 v[20:23], v[144:147], v[176:179], v[20:23]
	v_mfma_f32_16x16x32_bf16 v[20:23], v[148:151], v[180:183], v[20:23]
	v_mfma_f32_16x16x32_bf16 v[16:19], v[152:155], v[176:179], v[16:19]
	v_mfma_f32_16x16x32_bf16 v[16:19], v[156:159], v[180:183], v[16:19]
	v_mfma_f32_16x16x32_bf16 v[4:7], v[144:147], v[184:187], v[4:7]
	v_mfma_f32_16x16x32_bf16 v[4:7], v[148:151], v[188:191], v[4:7]
	s_setprio 3
	s_barrier
	v_mfma_f32_16x16x32_bf16 v[0:3], v[152:155], v[184:187], v[0:3]
	v_mfma_f32_16x16x32_bf16 v[0:3], v[156:159], v[188:191], v[0:3]
	s_setprio 0
	s_add_i32 s58, s58, 2
	s_add_u32 s86, s86, 0x100
	s_addc_u32 s87, s87, 0
	s_add_u32 s56, s56, 0x100
	s_addc_u32 s57, s57, 0
	s_cmp_gt_u32 s58, 41
	s_cbranch_scc0 .LBB0_272
	s_branch .Lzskip_1
.Lzv_1_0:
	v_mfma_f32_16x16x32_bf16 v[140:143], v[120:123], v[160:163], 0
	v_mfma_f32_16x16x32_bf16 v[140:143], v[124:127], v[164:167], v[140:143]
	v_mfma_f32_16x16x32_bf16 v[136:139], v[128:131], v[160:163], 0
	v_mfma_f32_16x16x32_bf16 v[136:139], v[132:135], v[164:167], v[136:139]
	v_mfma_f32_16x16x32_bf16 v[108:111], v[120:123], v[168:171], 0
	v_mfma_f32_16x16x32_bf16 v[108:111], v[124:127], v[172:175], v[108:111]
	v_mfma_f32_16x16x32_bf16 v[104:107], v[128:131], v[168:171], 0
	v_mfma_f32_16x16x32_bf16 v[104:107], v[132:135], v[172:175], v[104:107]
	v_mfma_f32_16x16x32_bf16 v[92:95], v[120:123], v[176:179], 0
	v_mfma_f32_16x16x32_bf16 v[92:95], v[124:127], v[180:183], v[92:95]
	v_mfma_f32_16x16x32_bf16 v[88:91], v[128:131], v[176:179], 0
	v_mfma_f32_16x16x32_bf16 v[88:91], v[132:135], v[180:183], v[88:91]
	v_mfma_f32_16x16x32_bf16 v[76:79], v[120:123], v[184:187], 0
	v_mfma_f32_16x16x32_bf16 v[76:79], v[124:127], v[188:191], v[76:79]
	v_mfma_f32_16x16x32_bf16 v[72:75], v[128:131], v[184:187], 0
	v_mfma_f32_16x16x32_bf16 v[72:75], v[132:135], v[188:191], v[72:75]
	v_mfma_f32_16x16x32_bf16 v[116:119], v[144:147], v[160:163], 0
	v_mfma_f32_16x16x32_bf16 v[116:119], v[148:151], v[164:167], v[116:119]
	v_mfma_f32_16x16x32_bf16 v[112:115], v[152:155], v[160:163], 0
	v_mfma_f32_16x16x32_bf16 v[112:115], v[156:159], v[164:167], v[112:115]
	v_mfma_f32_16x16x32_bf16 v[100:103], v[144:147], v[168:171], 0
	v_mfma_f32_16x16x32_bf16 v[100:103], v[148:151], v[172:175], v[100:103]
	v_mfma_f32_16x16x32_bf16 v[96:99], v[152:155], v[168:171], 0
	v_mfma_f32_16x16x32_bf16 v[96:99], v[156:159], v[172:175], v[96:99]
	v_mfma_f32_16x16x32_bf16 v[84:87], v[144:147], v[176:179], 0
	v_mfma_f32_16x16x32_bf16 v[84:87], v[148:151], v[180:183], v[84:87]
	v_mfma_f32_16x16x32_bf16 v[80:83], v[152:155], v[176:179], 0
	v_mfma_f32_16x16x32_bf16 v[80:83], v[156:159], v[180:183], v[80:83]
	v_mfma_f32_16x16x32_bf16 v[68:71], v[144:147], v[184:187], 0
	v_mfma_f32_16x16x32_bf16 v[68:71], v[148:151], v[188:191], v[68:71]
	s_setprio 3
	s_barrier
	v_mfma_f32_16x16x32_bf16 v[64:67], v[152:155], v[184:187], 0
	v_mfma_f32_16x16x32_bf16 v[64:67], v[156:159], v[188:191], v[64:67]
	s_setprio 0
	s_branch .Lzj_1_0
.Lzv_1_1:
	v_mfma_f32_16x16x32_bf16 v[60:63], v[120:123], v[160:163], 0
	v_mfma_f32_16x16x32_bf16 v[60:63], v[124:127], v[164:167], v[60:63]
	v_mfma_f32_16x16x32_bf16 v[56:59], v[128:131], v[160:163], 0
	v_mfma_f32_16x16x32_bf16 v[56:59], v[132:135], v[164:167], v[56:59]
	v_mfma_f32_16x16x32_bf16 v[44:47], v[120:123], v[168:171], 0
	v_mfma_f32_16x16x32_bf16 v[44:47], v[124:127], v[172:175], v[44:47]
	v_mfma_f32_16x16x32_bf16 v[40:43], v[128:131], v[168:171], 0
	v_mfma_f32_16x16x32_bf16 v[40:43], v[132:135], v[172:175], v[40:43]
	v_mfma_f32_16x16x32_bf16 v[28:31], v[120:123], v[176:179], 0
	v_mfma_f32_16x16x32_bf16 v[28:31], v[124:127], v[180:183], v[28:31]
	v_mfma_f32_16x16x32_bf16 v[24:27], v[128:131], v[176:179], 0
	v_mfma_f32_16x16x32_bf16 v[24:27], v[132:135], v[180:183], v[24:27]
	v_mfma_f32_16x16x32_bf16 v[12:15], v[120:123], v[184:187], 0
	v_mfma_f32_16x16x32_bf16 v[12:15], v[124:127], v[188:191], v[12:15]
	v_mfma_f32_16x16x32_bf16 v[8:11], v[128:131], v[184:187], 0
	v_mfma_f32_16x16x32_bf16 v[8:11], v[132:135], v[188:191], v[8:11]
	v_mfma_f32_16x16x32_bf16 v[52:55], v[144:147], v[160:163], 0
	v_mfma_f32_16x16x32_bf16 v[52:55], v[148:151], v[164:167], v[52:55]
	v_mfma_f32_16x16x32_bf16 v[48:51], v[152:155], v[160:163], 0
	v_mfma_f32_16x16x32_bf16 v[48:51], v[156:159], v[164:167], v[48:51]
	v_mfma_f32_16x16x32_bf16 v[36:39], v[144:147], v[168:171], 0
	v_mfma_f32_16x16x32_bf16 v[36:39], v[148:151], v[172:175], v[36:39]
	v_mfma_f32_16x16x32_bf16 v[32:35], v[152:155], v[168:171], 0
	v_mfma_f32_16x16x32_bf16 v[32:35], v[156:159], v[172:175], v[32:35]
	v_mfma_f32_16x16x32_bf16 v[20:23], v[144:147], v[176:179], 0
	v_mfma_f32_16x16x32_bf16 v[20:23], v[148:151], v[180:183], v[20:23]
	v_mfma_f32_16x16x32_bf16 v[16:19], v[152:155], v[176:179], 0
	v_mfma_f32_16x16x32_bf16 v[16:19], v[156:159], v[180:183], v[16:19]
	v_mfma_f32_16x16x32_bf16 v[4:7], v[144:147], v[184:187], 0
	v_mfma_f32_16x16x32_bf16 v[4:7], v[148:151], v[188:191], v[4:7]
	s_setprio 3
	s_barrier
	v_mfma_f32_16x16x32_bf16 v[0:3], v[152:155], v[184:187], 0
	v_mfma_f32_16x16x32_bf16 v[0:3], v[156:159], v[188:191], v[0:3]
	s_setprio 0
	s_branch .Lzj_1_1
.Lzskip_1:
	s_and_b64 vcc, exec, s[82:83]
	s_cbranch_vccz .LBB0_275
	s_barrier

.LBB0_428:
	s_ashr_i32 s95, s94, 31
	s_lshl_b64 s[16:17], s[94:95], 19
	s_add_u32 s96, s12, s16
	s_addc_u32 s97, s13, s17
	s_and_b64 s[16:17], s[8:9], exec
	s_cselect_b32 s15, s97, s89
	s_cselect_b32 s16, s96, s88
	s_ashr_i32 s85, s84, 31
	s_lshl_b64 s[18:19], s[84:85], 19
	s_add_u32 s90, s54, s18
	s_addc_u32 s91, s55, s19
	s_and_b64 s[18:19], s[8:9], exec
	s_cselect_b32 s17, s91, s7
	s_cselect_b32 s18, s90, s6
	s_add_u32 s88, s88, 0x40080
	s_addc_u32 s89, s89, 0
	s_add_u32 s19, s6, 0x100
	v_mov_b32_e32 v0, 0
	s_addc_u32 s20, s7, 0
	s_mov_b32 s21, -2
	s_waitcnt lgkmcnt(0)
.LBB0_429:
	ds_read_b128 v[128:131], v203
	ds_read_b128 v[132:135], v203 offset:1024
	ds_read_b128 v[136:139], v203 offset:2048
	ds_read_b128 v[164:167], v203 offset:3072
	ds_read_b128 v[168:171], v204
	ds_read_b128 v[172:175], v204 offset:1024
	ds_read_b128 v[176:179], v204 offset:2048
	ds_read_b128 v[180:183], v204 offset:3072
	s_add_u32 s6, s88, 0xfffc0080
	s_addc_u32 s7, s89, -1
	s_cmp_eq_u32 s21, 12
	s_cselect_b32 vcc_hi, s15, s7
	s_cselect_b32 vcc_lo, s16, s6
	s_cselect_b32 s7, s17, s20
	s_cselect_b32 s6, s18, s19
	v_lshl_add_u64 v[196:197], s[88:89], 0, v[156:157]
	s_add_i32 m0, s58, 0xc000
	ds_read_b128 v[184:187], v205
	ds_read_b128 v[188:191], v205 offset:1024
	ds_read_b128 v[192:195], v205 offset:2048
	ds_read_b128 v[212:215], v205 offset:3072
	ds_read_b128 v[216:219], v205 offset:4096
	ds_read_b128 v[220:223], v205 offset:5120
	ds_read_b128 v[224:227], v205 offset:6144
	ds_read_b128 v[228:231], v205 offset:7168
	global_load_lds_dwordx4 v[196:197], off
	v_lshl_add_u64 v[196:197], s[88:89], 0, v[158:159]
	s_add_i32 m0, s58, 0xe000
	s_nop 0
	global_load_lds_dwordx4 v[196:197], off
	s_cmp_eq_u32 s21, -2
	s_waitcnt vmcnt(8)
	s_waitcnt lgkmcnt(0)
	s_barrier
	s_setprio 1
	s_cbranch_scc1 .Lzv_2_0
	v_mfma_f32_16x16x32_bf16 v[124:127], v[128:131], v[184:187], v[124:127]
	v_mfma_f32_16x16x32_bf16 v[124:127], v[132:135], v[188:191], v[124:127]
	v_mfma_f32_16x16x32_bf16 v[116:119], v[136:139], v[184:187], v[116:119]
	v_mfma_f32_16x16x32_bf16 v[116:119], v[164:167], v[188:191], v[116:119]
	v_mfma_f32_16x16x32_bf16 v[108:111], v[128:131], v[192:195], v[108:111]
	v_mfma_f32_16x16x32_bf16 v[108:111], v[132:135], v[212:215], v[108:111]
	v_mfma_f32_16x16x32_bf16 v[100:103], v[136:139], v[192:195], v[100:103]
	v_mfma_f32_16x16x32_bf16 v[100:103], v[164:167], v[212:215], v[100:103]
	v_mfma_f32_16x16x32_bf16 v[92:95], v[128:131], v[216:219], v[92:95]
	v_mfma_f32_16x16x32_bf16 v[92:95], v[132:135], v[220:223], v[92:95]
	v_mfma_f32_16x16x32_bf16 v[84:87], v[136:139], v[216:219], v[84:87]
	v_mfma_f32_16x16x32_bf16 v[84:87], v[164:167], v[220:223], v[84:87]
	v_mfma_f32_16x16x32_bf16 v[76:79], v[128:131], v[224:227], v[76:79]
	v_mfma_f32_16x16x32_bf16 v[76:79], v[132:135], v[228:231], v[76:79]
	v_mfma_f32_16x16x32_bf16 v[68:71], v[136:139], v[224:227], v[68:71]
	v_mfma_f32_16x16x32_bf16 v[68:71], v[164:167], v[228:231], v[68:71]
	v_mfma_f32_16x16x32_bf16 v[120:123], v[168:171], v[184:187], v[120:123]
	v_mfma_f32_16x16x32_bf16 v[120:123], v[172:175], v[188:191], v[120:123]
	v_mfma_f32_16x16x32_bf16 v[112:115], v[176:179], v[184:187], v[112:115]
	v_mfma_f32_16x16x32_bf16 v[112:115], v[180:183], v[188:191], v[112:115]
	v_mfma_f32_16x16x32_bf16 v[104:107], v[168:171], v[192:195], v[104:107]
	v_mfma_f32_16x16x32_bf16 v[104:107], v[172:175], v[212:215], v[104:107]
	v_mfma_f32_16x16x32_bf16 v[96:99], v[176:179], v[192:195], v[96:99]
	v_mfma_f32_16x16x32_bf16 v[96:99], v[180:183], v[212:215], v[96:99]
	v_mfma_f32_16x16x32_bf16 v[88:91], v[168:171], v[216:219], v[88:91]
	v_mfma_f32_16x16x32_bf16 v[88:91], v[172:175], v[220:223], v[88:91]
	v_mfma_f32_16x16x32_bf16 v[80:83], v[176:179], v[216:219], v[80:83]
	v_mfma_f32_16x16x32_bf16 v[80:83], v[180:183], v[220:223], v[80:83]
	v_mfma_f32_16x16x32_bf16 v[72:75], v[168:171], v[224:227], v[72:75]
	v_mfma_f32_16x16x32_bf16 v[72:75], v[172:175], v[228:231], v[72:75]
	s_setprio 3
	s_barrier
	v_mfma_f32_16x16x32_bf16 v[64:67], v[176:179], v[224:227], v[64:67]
	v_mfma_f32_16x16x32_bf16 v[64:67], v[180:183], v[228:231], v[64:67]
	s_setprio 0
.Lzj_2_0:
	s_add_i32 s22, s76, s57
	v_lshl_add_u64 v[196:197], s[6:7], 0, v[142:143]
	s_mov_b32 m0, s22
	ds_read_b128 v[184:187], v205 offset:16384
	ds_read_b128 v[188:191], v205 offset:17408
	ds_read_b128 v[192:195], v205 offset:18432
	ds_read_b128 v[212:215], v205 offset:19456
	ds_read_b128 v[216:219], v205 offset:20480
	ds_read_b128 v[220:223], v205 offset:21504
	ds_read_b128 v[224:227], v205 offset:22528
	ds_read_b128 v[228:231], v205 offset:23552
	global_load_lds_dwordx4 v[196:197], off
	s_add_i32 m0, s22, 0x2000
	s_add_u32 s22, s6, 0x40000
	v_lshl_add_u64 v[232:233], s[6:7], 0, v[146:147]
	s_addc_u32 s23, s7, 0
	s_add_i32 s24, s77, s57
	global_load_lds_dwordx4 v[232:233], off
	v_lshl_add_u64 v[234:235], s[22:23], 0, v[142:143]
	s_mov_b32 m0, s24
	v_lshl_add_u64 v[236:237], vcc, 0, v[144:145]
	global_load_lds_dwordx4 v[234:235], off
	v_lshl_add_u64 v[234:235], s[22:23], 0, v[146:147]
	s_add_i32 m0, s24, 0x2000
	s_nop 0
	global_load_lds_dwordx4 v[234:235], off
	v_lshl_add_u64 v[234:235], vcc, 0, v[140:141]
	s_mov_b32 m0, s58
	s_nop 0
	global_load_lds_dwordx4 v[234:235], off
	s_mov_b32 m0, s59
	s_nop 0
	global_load_lds_dwordx4 v[236:237], off
	s_cmp_eq_u32 s21, -2
	s_waitcnt vmcnt(8)
	s_waitcnt lgkmcnt(0)
	s_barrier
	s_setprio 1
	s_cbranch_scc1 .Lzv_2_1
	v_mfma_f32_16x16x32_bf16 v[60:63], v[128:131], v[184:187], v[60:63]
	v_mfma_f32_16x16x32_bf16 v[60:63], v[132:135], v[188:191], v[60:63]
	v_mfma_f32_16x16x32_bf16 v[52:55], v[136:139], v[184:187], v[52:55]
	v_mfma_f32_16x16x32_bf16 v[52:55], v[164:167], v[188:191], v[52:55]
	v_mfma_f32_16x16x32_bf16 v[44:47], v[128:131], v[192:195], v[44:47]
	v_mfma_f32_16x16x32_bf16 v[44:47], v[132:135], v[212:215], v[44:47]
	v_mfma_f32_16x16x32_bf16 v[36:39], v[136:139], v[192:195], v[36:39]
	v_mfma_f32_16x16x32_bf16 v[36:39], v[164:167], v[212:215], v[36:39]
	v_mfma_f32_16x16x32_bf16 v[28:31], v[128:131], v[216:219], v[28:31]
	v_mfma_f32_16x16x32_bf16 v[28:31], v[132:135], v[220:223], v[28:31]
	v_mfma_f32_16x16x32_bf16 v[20:23], v[136:139], v[216:219], v[20:23]
	v_mfma_f32_16x16x32_bf16 v[20:23], v[164:167], v[220:223], v[20:23]
	v_mfma_f32_16x16x32_bf16 v[12:15], v[128:131], v[224:227], v[12:15]
	v_mfma_f32_16x16x32_bf16 v[12:15], v[132:135], v[228:231], v[12:15]
	v_mfma_f32_16x16x32_bf16 v[4:7], v[136:139], v[224:227], v[4:7]
	v_mfma_f32_16x16x32_bf16 v[4:7], v[164:167], v[228:231], v[4:7]
	v_mfma_f32_16x16x32_bf16 v[56:59], v[168:171], v[184:187], v[56:59]
	v_mfma_f32_16x16x32_bf16 v[56:59], v[172:175], v[188:191], v[56:59]
	v_mfma_f32_16x16x32_bf16 v[48:51], v[176:179], v[184:187], v[48:51]
	v_mfma_f32_16x16x32_bf16 v[48:51], v[180:183], v[188:191], v[48:51]
	v_mfma_f32_16x16x32_bf16 v[40:43], v[168:171], v[192:195], v[40:43]
	v_mfma_f32_16x16x32_bf16 v[40:43], v[172:175], v[212:215], v[40:43]
	v_mfma_f32_16x16x32_bf16 v[32:35], v[176:179], v[192:195], v[32:35]
	v_mfma_f32_16x16x32_bf16 v[32:35], v[180:183], v[212:215], v[32:35]
	v_mfma_f32_16x16x32_bf16 v[24:27], v[168:171], v[216:219], v[24:27]
	v_mfma_f32_16x16x32_bf16 v[24:27], v[172:175], v[220:223], v[24:27]
	v_mfma_f32_16x16x32_bf16 v[16:19], v[176:179], v[216:219], v[16:19]
	v_mfma_f32_16x16x32_bf16 v[16:19], v[180:183], v[220:223], v[16:19]
	v_mfma_f32_16x16x32_bf16 v[8:11], v[168:171], v[224:227], v[8:11]
	v_mfma_f32_16x16x32_bf16 v[8:11], v[172:175], v[228:231], v[8:11]
	s_setprio 3
	s_barrier
	v_mfma_f32_16x16x32_bf16 v[0:3], v[176:179], v[224:227], v[0:3]
	v_mfma_f32_16x16x32_bf16 v[0:3], v[180:183], v[228:231], v[0:3]
	s_setprio 0
.Lzj_2_1:
	s_add_i32 s24, 0, 0x18000
	v_add_u32_e32 v150, s24, v200
	s_add_i32 s25, 0, 0x1c000
	ds_read_b128 v[128:131], v150
	ds_read_b128 v[132:135], v150 offset:1024
	ds_read_b128 v[136:139], v150 offset:2048
	ds_read_b128 v[164:167], v150 offset:3072
	v_add_u32_e32 v150, s25, v200
	ds_read_b128 v[168:171], v150
	ds_read_b128 v[172:175], v150 offset:1024
	ds_read_b128 v[176:179], v150 offset:2048
	ds_read_b128 v[180:183], v150 offset:3072
	s_add_u32 s22, vcc_lo, 0x40000
	s_addc_u32 s23, vcc_hi, 0
	s_mov_b32 m0, s66
	v_lshl_add_u64 v[238:239], s[22:23], 0, v[140:141]
	ds_read_b128 v[184:187], v205 offset:32768
	ds_read_b128 v[188:191], v205 offset:33792
	ds_read_b128 v[192:195], v205 offset:34816
	ds_read_b128 v[212:215], v205 offset:35840
	ds_read_b128 v[216:219], v205 offset:36864
	ds_read_b128 v[220:223], v205 offset:37888
	ds_read_b128 v[224:227], v205 offset:38912
	ds_read_b128 v[228:231], v205 offset:39936
	global_load_lds_dwordx4 v[238:239], off
	v_lshl_add_u64 v[238:239], s[22:23], 0, v[144:145]
	s_mov_b32 m0, s67
	s_nop 0
	global_load_lds_dwordx4 v[238:239], off
	s_waitcnt vmcnt(8)
	s_waitcnt lgkmcnt(0)
	s_barrier
	s_setprio 1
	v_mfma_f32_16x16x32_bf16 v[124:127], v[128:131], v[184:187], v[124:127]
	v_mfma_f32_16x16x32_bf16 v[124:127], v[132:135], v[188:191], v[124:127]
	v_mfma_f32_16x16x32_bf16 v[116:119], v[136:139], v[184:187], v[116:119]
	v_mfma_f32_16x16x32_bf16 v[116:119], v[164:167], v[188:191], v[116:119]
	v_mfma_f32_16x16x32_bf16 v[108:111], v[128:131], v[192:195], v[108:111]
	v_mfma_f32_16x16x32_bf16 v[108:111], v[132:135], v[212:215], v[108:111]
	v_mfma_f32_16x16x32_bf16 v[100:103], v[136:139], v[192:195], v[100:103]
	v_mfma_f32_16x16x32_bf16 v[100:103], v[164:167], v[212:215], v[100:103]
	v_mfma_f32_16x16x32_bf16 v[92:95], v[128:131], v[216:219], v[92:95]
	v_mfma_f32_16x16x32_bf16 v[92:95], v[132:135], v[220:223], v[92:95]
	v_mfma_f32_16x16x32_bf16 v[84:87], v[136:139], v[216:219], v[84:87]
	v_mfma_f32_16x16x32_bf16 v[84:87], v[164:167], v[220:223], v[84:87]
	v_mfma_f32_16x16x32_bf16 v[76:79], v[128:131], v[224:227], v[76:79]
	v_mfma_f32_16x16x32_bf16 v[76:79], v[132:135], v[228:231], v[76:79]
	v_mfma_f32_16x16x32_bf16 v[68:71], v[136:139], v[224:227], v[68:71]
	v_mfma_f32_16x16x32_bf16 v[68:71], v[164:167], v[228:231], v[68:71]
	v_mfma_f32_16x16x32_bf16 v[120:123], v[168:171], v[184:187], v[120:123]
	v_mfma_f32_16x16x32_bf16 v[120:123], v[172:175], v[188:191], v[120:123]
	v_mfma_f32_16x16x32_bf16 v[112:115], v[176:179], v[184:187], v[112:115]
	v_mfma_f32_16x16x32_bf16 v[112:115], v[180:183], v[188:191], v[112:115]
	v_mfma_f32_16x16x32_bf16 v[104:107], v[168:171], v[192:195], v[104:107]
	v_mfma_f32_16x16x32_bf16 v[104:107], v[172:175], v[212:215], v[104:107]
	v_mfma_f32_16x16x32_bf16 v[96:99], v[176:179], v[192:195], v[96:99]
	v_mfma_f32_16x16x32_bf16 v[96:99], v[180:183], v[212:215], v[96:99]
	v_mfma_f32_16x16x32_bf16 v[88:91], v[168:171], v[216:219], v[88:91]
	v_mfma_f32_16x16x32_bf16 v[88:91], v[172:175], v[220:223], v[88:91]
	v_mfma_f32_16x16x32_bf16 v[80:83], v[176:179], v[216:219], v[80:83]
	v_mfma_f32_16x16x32_bf16 v[80:83], v[180:183], v[220:223], v[80:83]
	v_mfma_f32_16x16x32_bf16 v[72:75], v[168:171], v[224:227], v[72:75]
	v_mfma_f32_16x16x32_bf16 v[72:75], v[172:175], v[228:231], v[72:75]
	s_setprio 3
	s_barrier
	v_mfma_f32_16x16x32_bf16 v[64:67], v[176:179], v[224:227], v[64:67]
	v_mfma_f32_16x16x32_bf16 v[64:67], v[180:183], v[228:231], v[64:67]
	s_setprio 0
	s_add_i32 s22, s24, s57
	v_lshl_add_u64 v[196:197], v[196:197], 0, s[80:81]
	s_mov_b32 m0, s22
	ds_read_b128 v[184:187], v205 offset:49152
	ds_read_b128 v[188:191], v205 offset:50176
	ds_read_b128 v[192:195], v205 offset:51200
	ds_read_b128 v[212:215], v205 offset:52224
	ds_read_b128 v[216:219], v205 offset:53248
	ds_read_b128 v[220:223], v205 offset:54272
	ds_read_b128 v[224:227], v205 offset:55296
	ds_read_b128 v[228:231], v205 offset:56320
	global_load_lds_dwordx4 v[196:197], off
	s_add_i32 m0, s22, 0x2000
	s_add_u32 s6, s6, 0x40080
	v_lshl_add_u64 v[196:197], v[232:233], 0, s[80:81]
	s_addc_u32 s7, s7, 0
	s_add_i32 s22, s25, s57
	global_load_lds_dwordx4 v[196:197], off
	v_lshl_add_u64 v[196:197], s[6:7], 0, v[142:143]
	s_mov_b32 m0, s22
	s_nop 0
	global_load_lds_dwordx4 v[196:197], off
	v_lshl_add_u64 v[196:197], s[6:7], 0, v[146:147]
	s_add_i32 m0, s22, 0x2000
	s_nop 0
	global_load_lds_dwordx4 v[196:197], off
	v_lshl_add_u64 v[196:197], v[234:235], 0, s[80:81]
	s_mov_b32 m0, s93
	s_nop 0
	global_load_lds_dwordx4 v[196:197], off
	v_lshl_add_u64 v[196:197], v[236:237], 0, s[80:81]
	s_mov_b32 m0, s69
	s_nop 0
	global_load_lds_dwordx4 v[196:197], off
	s_waitcnt vmcnt(8)
	s_waitcnt lgkmcnt(0)
	s_barrier
	s_setprio 1
	v_mfma_f32_16x16x32_bf16 v[60:63], v[128:131], v[184:187], v[60:63]
	v_mfma_f32_16x16x32_bf16 v[60:63], v[132:135], v[188:191], v[60:63]
	v_mfma_f32_16x16x32_bf16 v[52:55], v[136:139], v[184:187], v[52:55]
	v_mfma_f32_16x16x32_bf16 v[52:55], v[164:167], v[188:191], v[52:55]
	v_mfma_f32_16x16x32_bf16 v[44:47], v[128:131], v[192:195], v[44:47]
	v_mfma_f32_16x16x32_bf16 v[44:47], v[132:135], v[212:215], v[44:47]
	v_mfma_f32_16x16x32_bf16 v[36:39], v[136:139], v[192:195], v[36:39]
	v_mfma_f32_16x16x32_bf16 v[36:39], v[164:167], v[212:215], v[36:39]
	v_mfma_f32_16x16x32_bf16 v[28:31], v[128:131], v[216:219], v[28:31]
	v_mfma_f32_16x16x32_bf16 v[28:31], v[132:135], v[220:223], v[28:31]
	v_mfma_f32_16x16x32_bf16 v[20:23], v[136:139], v[216:219], v[20:23]
	v_mfma_f32_16x16x32_bf16 v[20:23], v[164:167], v[220:223], v[20:23]
	v_mfma_f32_16x16x32_bf16 v[12:15], v[128:131], v[224:227], v[12:15]
	v_mfma_f32_16x16x32_bf16 v[12:15], v[132:135], v[228:231], v[12:15]
	v_mfma_f32_16x16x32_bf16 v[4:7], v[136:139], v[224:227], v[4:7]
	v_mfma_f32_16x16x32_bf16 v[4:7], v[164:167], v[228:231], v[4:7]
	v_mfma_f32_16x16x32_bf16 v[56:59], v[168:171], v[184:187], v[56:59]
	v_mfma_f32_16x16x32_bf16 v[56:59], v[172:175], v[188:191], v[56:59]
	v_mfma_f32_16x16x32_bf16 v[48:51], v[176:179], v[184:187], v[48:51]
	v_mfma_f32_16x16x32_bf16 v[48:51], v[180:183], v[188:191], v[48:51]
	v_mfma_f32_16x16x32_bf16 v[40:43], v[168:171], v[192:195], v[40:43]
	v_mfma_f32_16x16x32_bf16 v[40:43], v[172:175], v[212:215], v[40:43]
	v_mfma_f32_16x16x32_bf16 v[32:35], v[176:179], v[192:195], v[32:35]
	v_mfma_f32_16x16x32_bf16 v[32:35], v[180:183], v[212:215], v[32:35]
	v_mfma_f32_16x16x32_bf16 v[24:27], v[168:171], v[216:219], v[24:27]
	v_mfma_f32_16x16x32_bf16 v[24:27], v[172:175], v[220:223], v[24:27]
	v_mfma_f32_16x16x32_bf16 v[16:19], v[176:179], v[216:219], v[16:19]
	v_mfma_f32_16x16x32_bf16 v[16:19], v[180:183], v[220:223], v[16:19]
	v_mfma_f32_16x16x32_bf16 v[8:11], v[168:171], v[224:227], v[8:11]
	v_mfma_f32_16x16x32_bf16 v[8:11], v[172:175], v[228:231], v[8:11]
	s_setprio 3
	s_barrier
	v_mfma_f32_16x16x32_bf16 v[0:3], v[176:179], v[224:227], v[0:3]
	v_mfma_f32_16x16x32_bf16 v[0:3], v[180:183], v[228:231], v[0:3]
	s_setprio 0
	s_add_i32 s21, s21, 2
	s_add_u32 s88, s88, 0x100
	s_addc_u32 s89, s89, 0
	s_add_u32 s19, s19, 0x100
	s_addc_u32 s20, s20, 0
	s_cmp_gt_u32 s21, 13
	s_cbranch_scc0 .LBB0_429
	s_branch .Lzskip_2
.Lzv_2_0:
	v_mfma_f32_16x16x32_bf16 v[124:127], v[128:131], v[184:187], 0
	v_mfma_f32_16x16x32_bf16 v[124:127], v[132:135], v[188:191], v[124:127]
	v_mfma_f32_16x16x32_bf16 v[116:119], v[136:139], v[184:187], 0
	v_mfma_f32_16x16x32_bf16 v[116:119], v[164:167], v[188:191], v[116:119]
	v_mfma_f32_16x16x32_bf16 v[108:111], v[128:131], v[192:195], 0
	v_mfma_f32_16x16x32_bf16 v[108:111], v[132:135], v[212:215], v[108:111]
	v_mfma_f32_16x16x32_bf16 v[100:103], v[136:139], v[192:195], 0
	v_mfma_f32_16x16x32_bf16 v[100:103], v[164:167], v[212:215], v[100:103]
	v_mfma_f32_16x16x32_bf16 v[92:95], v[128:131], v[216:219], 0
	v_mfma_f32_16x16x32_bf16 v[92:95], v[132:135], v[220:223], v[92:95]
	v_mfma_f32_16x16x32_bf16 v[84:87], v[136:139], v[216:219], 0
	v_mfma_f32_16x16x32_bf16 v[84:87], v[164:167], v[220:223], v[84:87]
	v_mfma_f32_16x16x32_bf16 v[76:79], v[128:131], v[224:227], 0
	v_mfma_f32_16x16x32_bf16 v[76:79], v[132:135], v[228:231], v[76:79]
	v_mfma_f32_16x16x32_bf16 v[68:71], v[136:139], v[224:227], 0
	v_mfma_f32_16x16x32_bf16 v[68:71], v[164:167], v[228:231], v[68:71]
	v_mfma_f32_16x16x32_bf16 v[120:123], v[168:171], v[184:187], 0
	v_mfma_f32_16x16x32_bf16 v[120:123], v[172:175], v[188:191], v[120:123]
	v_mfma_f32_16x16x32_bf16 v[112:115], v[176:179], v[184:187], 0
	v_mfma_f32_16x16x32_bf16 v[112:115], v[180:183], v[188:191], v[112:115]
	v_mfma_f32_16x16x32_bf16 v[104:107], v[168:171], v[192:195], 0
	v_mfma_f32_16x16x32_bf16 v[104:107], v[172:175], v[212:215], v[104:107]
	v_mfma_f32_16x16x32_bf16 v[96:99], v[176:179], v[192:195], 0
	v_mfma_f32_16x16x32_bf16 v[96:99], v[180:183], v[212:215], v[96:99]
	v_mfma_f32_16x16x32_bf16 v[88:91], v[168:171], v[216:219], 0
	v_mfma_f32_16x16x32_bf16 v[88:91], v[172:175], v[220:223], v[88:91]
	v_mfma_f32_16x16x32_bf16 v[80:83], v[176:179], v[216:219], 0
	v_mfma_f32_16x16x32_bf16 v[80:83], v[180:183], v[220:223], v[80:83]
	v_mfma_f32_16x16x32_bf16 v[72:75], v[168:171], v[224:227], 0
	v_mfma_f32_16x16x32_bf16 v[72:75], v[172:175], v[228:231], v[72:75]
	s_setprio 3
	s_barrier
	v_mfma_f32_16x16x32_bf16 v[64:67], v[176:179], v[224:227], 0
	v_mfma_f32_16x16x32_bf16 v[64:67], v[180:183], v[228:231], v[64:67]
	s_setprio 0
	s_branch .Lzj_2_0
.Lzv_2_1:
	v_mfma_f32_16x16x32_bf16 v[60:63], v[128:131], v[184:187], 0
	v_mfma_f32_16x16x32_bf16 v[60:63], v[132:135], v[188:191], v[60:63]
	v_mfma_f32_16x16x32_bf16 v[52:55], v[136:139], v[184:187], 0
	v_mfma_f32_16x16x32_bf16 v[52:55], v[164:167], v[188:191], v[52:55]
	v_mfma_f32_16x16x32_bf16 v[44:47], v[128:131], v[192:195], 0
	v_mfma_f32_16x16x32_bf16 v[44:47], v[132:135], v[212:215], v[44:47]
	v_mfma_f32_16x16x32_bf16 v[36:39], v[136:139], v[192:195], 0
	v_mfma_f32_16x16x32_bf16 v[36:39], v[164:167], v[212:215], v[36:39]
	v_mfma_f32_16x16x32_bf16 v[28:31], v[128:131], v[216:219], 0
	v_mfma_f32_16x16x32_bf16 v[28:31], v[132:135], v[220:223], v[28:31]
	v_mfma_f32_16x16x32_bf16 v[20:23], v[136:139], v[216:219], 0
	v_mfma_f32_16x16x32_bf16 v[20:23], v[164:167], v[220:223], v[20:23]
	v_mfma_f32_16x16x32_bf16 v[12:15], v[128:131], v[224:227], 0
	v_mfma_f32_16x16x32_bf16 v[12:15], v[132:135], v[228:231], v[12:15]
	v_mfma_f32_16x16x32_bf16 v[4:7], v[136:139], v[224:227], 0
	v_mfma_f32_16x16x32_bf16 v[4:7], v[164:167], v[228:231], v[4:7]
	v_mfma_f32_16x16x32_bf16 v[56:59], v[168:171], v[184:187], 0
	v_mfma_f32_16x16x32_bf16 v[56:59], v[172:175], v[188:191], v[56:59]
	v_mfma_f32_16x16x32_bf16 v[48:51], v[176:179], v[184:187], 0
	v_mfma_f32_16x16x32_bf16 v[48:51], v[180:183], v[188:191], v[48:51]
	v_mfma_f32_16x16x32_bf16 v[40:43], v[168:171], v[192:195], 0
	v_mfma_f32_16x16x32_bf16 v[40:43], v[172:175], v[212:215], v[40:43]
	v_mfma_f32_16x16x32_bf16 v[32:35], v[176:179], v[192:195], 0
	v_mfma_f32_16x16x32_bf16 v[32:35], v[180:183], v[212:215], v[32:35]
	v_mfma_f32_16x16x32_bf16 v[24:27], v[168:171], v[216:219], 0
	v_mfma_f32_16x16x32_bf16 v[24:27], v[172:175], v[220:223], v[24:27]
	v_mfma_f32_16x16x32_bf16 v[16:19], v[176:179], v[216:219], 0
	v_mfma_f32_16x16x32_bf16 v[16:19], v[180:183], v[220:223], v[16:19]
	v_mfma_f32_16x16x32_bf16 v[8:11], v[168:171], v[224:227], 0
	v_mfma_f32_16x16x32_bf16 v[8:11], v[172:175], v[228:231], v[8:11]
	s_setprio 3
	s_barrier
	v_mfma_f32_16x16x32_bf16 v[0:3], v[176:179], v[224:227], 0
	v_mfma_f32_16x16x32_bf16 v[0:3], v[180:183], v[228:231], v[0:3]
	s_setprio 0
	s_branch .Lzj_2_1

.LBB0_993:
	ds_read_b128 v[120:123], v245
	ds_read_b128 v[124:127], v245 offset:1024
	ds_read_b128 v[128:131], v245 offset:2048
	ds_read_b128 v[132:135], v245 offset:3072
	ds_read_b128 v[144:147], v246
	ds_read_b128 v[148:151], v246 offset:1024
	ds_read_b128 v[152:155], v246 offset:2048
	ds_read_b128 v[156:159], v246 offset:3072
	s_add_u32 s59, s82, 0xfffc0080
	s_addc_u32 s66, s83, -1
	s_cmp_eq_u32 s58, 12
	s_cselect_b32 s87, s53, s66
	s_cselect_b32 s86, s54, s59
	s_cselect_b32 s85, s51, s57
	s_cselect_b32 s84, s55, s56
	v_lshl_add_u64 v[204:205], s[82:83], 0, v[200:201]
	s_add_i32 m0, s16, 0xc000
	ds_read_b128 v[160:163], v247
	ds_read_b128 v[164:167], v247 offset:1024
	ds_read_b128 v[168:171], v247 offset:2048
	ds_read_b128 v[172:175], v247 offset:3072
	ds_read_b128 v[176:179], v247 offset:4096
	ds_read_b128 v[180:183], v247 offset:5120
	ds_read_b128 v[184:187], v247 offset:6144
	ds_read_b128 v[188:191], v247 offset:7168
	global_load_lds_dwordx4 v[204:205], off
	v_lshl_add_u64 v[204:205], s[82:83], 0, v[202:203]
	s_add_i32 m0, s16, 0xe000
	s_nop 0
	global_load_lds_dwordx4 v[204:205], off
	s_cmp_eq_u32 s58, -2
	s_waitcnt vmcnt(8)
	s_waitcnt lgkmcnt(0)
	s_barrier
	s_setprio 1
	s_cbranch_scc1 .Lzv_3_0
	v_mfma_f32_16x16x32_bf16 v[140:143], v[120:123], v[160:163], v[140:143]
	v_mfma_f32_16x16x32_bf16 v[140:143], v[124:127], v[164:167], v[140:143]
	v_mfma_f32_16x16x32_bf16 v[136:139], v[128:131], v[160:163], v[136:139]
	v_mfma_f32_16x16x32_bf16 v[136:139], v[132:135], v[164:167], v[136:139]
	v_mfma_f32_16x16x32_bf16 v[108:111], v[120:123], v[168:171], v[108:111]
	v_mfma_f32_16x16x32_bf16 v[108:111], v[124:127], v[172:175], v[108:111]
	v_mfma_f32_16x16x32_bf16 v[104:107], v[128:131], v[168:171], v[104:107]
	v_mfma_f32_16x16x32_bf16 v[104:107], v[132:135], v[172:175], v[104:107]
	v_mfma_f32_16x16x32_bf16 v[92:95], v[120:123], v[176:179], v[92:95]
	v_mfma_f32_16x16x32_bf16 v[92:95], v[124:127], v[180:183], v[92:95]
	v_mfma_f32_16x16x32_bf16 v[88:91], v[128:131], v[176:179], v[88:91]
	v_mfma_f32_16x16x32_bf16 v[88:91], v[132:135], v[180:183], v[88:91]
	v_mfma_f32_16x16x32_bf16 v[76:79], v[120:123], v[184:187], v[76:79]
	v_mfma_f32_16x16x32_bf16 v[76:79], v[124:127], v[188:191], v[76:79]
	v_mfma_f32_16x16x32_bf16 v[72:75], v[128:131], v[184:187], v[72:75]
	v_mfma_f32_16x16x32_bf16 v[72:75], v[132:135], v[188:191], v[72:75]
	v_mfma_f32_16x16x32_bf16 v[116:119], v[144:147], v[160:163], v[116:119]
	v_mfma_f32_16x16x32_bf16 v[116:119], v[148:151], v[164:167], v[116:119]
	v_mfma_f32_16x16x32_bf16 v[112:115], v[152:155], v[160:163], v[112:115]
	v_mfma_f32_16x16x32_bf16 v[112:115], v[156:159], v[164:167], v[112:115]
	v_mfma_f32_16x16x32_bf16 v[100:103], v[144:147], v[168:171], v[100:103]
	v_mfma_f32_16x16x32_bf16 v[100:103], v[148:151], v[172:175], v[100:103]
	v_mfma_f32_16x16x32_bf16 v[96:99], v[152:155], v[168:171], v[96:99]
	v_mfma_f32_16x16x32_bf16 v[96:99], v[156:159], v[172:175], v[96:99]
	v_mfma_f32_16x16x32_bf16 v[84:87], v[144:147], v[176:179], v[84:87]
	v_mfma_f32_16x16x32_bf16 v[84:87], v[148:151], v[180:183], v[84:87]
	v_mfma_f32_16x16x32_bf16 v[80:83], v[152:155], v[176:179], v[80:83]
	v_mfma_f32_16x16x32_bf16 v[80:83], v[156:159], v[180:183], v[80:83]
	v_mfma_f32_16x16x32_bf16 v[68:71], v[144:147], v[184:187], v[68:71]
	v_mfma_f32_16x16x32_bf16 v[68:71], v[148:151], v[188:191], v[68:71]
	s_setprio 3
	s_barrier
	v_mfma_f32_16x16x32_bf16 v[64:67], v[152:155], v[184:187], v[64:67]
	v_mfma_f32_16x16x32_bf16 v[64:67], v[156:159], v[188:191], v[64:67]
	s_setprio 0
.Lzj_3_0:
	s_add_i32 s59, s26, s15
	v_lshl_add_u64 v[204:205], s[84:85], 0, v[194:195]
	s_mov_b32 m0, s59
	ds_read_b128 v[160:163], v247 offset:16384
	ds_read_b128 v[164:167], v247 offset:17408
	ds_read_b128 v[168:171], v247 offset:18432
	ds_read_b128 v[172:175], v247 offset:19456
	ds_read_b128 v[176:179], v247 offset:20480
	ds_read_b128 v[180:183], v247 offset:21504
	ds_read_b128 v[184:187], v247 offset:22528
	ds_read_b128 v[188:191], v247 offset:23552
	global_load_lds_dwordx4 v[204:205], off
	s_add_i32 m0, s59, 0x2000
	s_add_u32 s66, s84, 0x40000
	v_lshl_add_u64 v[206:207], s[84:85], 0, v[198:199]
	s_addc_u32 s67, s85, 0
	s_add_i32 s59, s27, s15
	global_load_lds_dwordx4 v[206:207], off
	v_lshl_add_u64 v[208:209], s[66:67], 0, v[194:195]
	s_mov_b32 m0, s59
	v_lshl_add_u64 v[210:211], s[86:87], 0, v[196:197]
	global_load_lds_dwordx4 v[208:209], off
	v_lshl_add_u64 v[208:209], s[66:67], 0, v[198:199]
	s_add_i32 m0, s59, 0x2000
	s_nop 0
	global_load_lds_dwordx4 v[208:209], off
	v_lshl_add_u64 v[208:209], s[86:87], 0, v[192:193]
	s_mov_b32 m0, s16
	s_nop 0
	global_load_lds_dwordx4 v[208:209], off
	s_mov_b32 m0, s17
	s_nop 0
	global_load_lds_dwordx4 v[210:211], off
	s_cmp_eq_u32 s58, -2
	s_waitcnt vmcnt(8)
	s_waitcnt lgkmcnt(0)
	s_barrier
	s_setprio 1
	s_cbranch_scc1 .Lzv_3_1
	v_mfma_f32_16x16x32_bf16 v[60:63], v[120:123], v[160:163], v[60:63]
	v_mfma_f32_16x16x32_bf16 v[60:63], v[124:127], v[164:167], v[60:63]
	v_mfma_f32_16x16x32_bf16 v[56:59], v[128:131], v[160:163], v[56:59]
	v_mfma_f32_16x16x32_bf16 v[56:59], v[132:135], v[164:167], v[56:59]
	v_mfma_f32_16x16x32_bf16 v[44:47], v[120:123], v[168:171], v[44:47]
	v_mfma_f32_16x16x32_bf16 v[44:47], v[124:127], v[172:175], v[44:47]
	v_mfma_f32_16x16x32_bf16 v[40:43], v[128:131], v[168:171], v[40:43]
	v_mfma_f32_16x16x32_bf16 v[40:43], v[132:135], v[172:175], v[40:43]
	v_mfma_f32_16x16x32_bf16 v[28:31], v[120:123], v[176:179], v[28:31]
	v_mfma_f32_16x16x32_bf16 v[28:31], v[124:127], v[180:183], v[28:31]
	v_mfma_f32_16x16x32_bf16 v[24:27], v[128:131], v[176:179], v[24:27]
	v_mfma_f32_16x16x32_bf16 v[24:27], v[132:135], v[180:183], v[24:27]
	v_mfma_f32_16x16x32_bf16 v[12:15], v[120:123], v[184:187], v[12:15]
	v_mfma_f32_16x16x32_bf16 v[12:15], v[124:127], v[188:191], v[12:15]
	v_mfma_f32_16x16x32_bf16 v[8:11], v[128:131], v[184:187], v[8:11]
	v_mfma_f32_16x16x32_bf16 v[8:11], v[132:135], v[188:191], v[8:11]
	v_mfma_f32_16x16x32_bf16 v[52:55], v[144:147], v[160:163], v[52:55]
	v_mfma_f32_16x16x32_bf16 v[52:55], v[148:151], v[164:167], v[52:55]
	v_mfma_f32_16x16x32_bf16 v[48:51], v[152:155], v[160:163], v[48:51]
	v_mfma_f32_16x16x32_bf16 v[48:51], v[156:159], v[164:167], v[48:51]
	v_mfma_f32_16x16x32_bf16 v[36:39], v[144:147], v[168:171], v[36:39]
	v_mfma_f32_16x16x32_bf16 v[36:39], v[148:151], v[172:175], v[36:39]
	v_mfma_f32_16x16x32_bf16 v[32:35], v[152:155], v[168:171], v[32:35]
	v_mfma_f32_16x16x32_bf16 v[32:35], v[156:159], v[172:175], v[32:35]
	v_mfma_f32_16x16x32_bf16 v[20:23], v[144:147], v[176:179], v[20:23]
	v_mfma_f32_16x16x32_bf16 v[20:23], v[148:151], v[180:183], v[20:23]
	v_mfma_f32_16x16x32_bf16 v[16:19], v[152:155], v[176:179], v[16:19]
	v_mfma_f32_16x16x32_bf16 v[16:19], v[156:159], v[180:183], v[16:19]
	v_mfma_f32_16x16x32_bf16 v[4:7], v[144:147], v[184:187], v[4:7]
	v_mfma_f32_16x16x32_bf16 v[4:7], v[148:151], v[188:191], v[4:7]
	s_setprio 3
	s_barrier
	v_mfma_f32_16x16x32_bf16 v[0:3], v[152:155], v[184:187], v[0:3]
	v_mfma_f32_16x16x32_bf16 v[0:3], v[156:159], v[188:191], v[0:3]
	s_setprio 0
.Lzj_3_1:
	s_add_i32 s59, 0, 0x18000
	s_add_i32 s68, 0, 0x1c000
	v_add_u32_e32 v132, s59, v243
	v_add_u32_e32 v156, s68, v243
	ds_read_b128 v[120:123], v132
	ds_read_b128 v[124:127], v132 offset:1024
	ds_read_b128 v[128:131], v132 offset:2048
	ds_read_b128 v[132:135], v132 offset:3072
	ds_read_b128 v[144:147], v156
	ds_read_b128 v[148:151], v156 offset:1024
	ds_read_b128 v[152:155], v156 offset:2048
	ds_read_b128 v[156:159], v156 offset:3072
	s_add_u32 s66, s86, 0x40000
	s_addc_u32 s67, s87, 0
	s_mov_b32 m0, s18
	v_lshl_add_u64 v[212:213], s[66:67], 0, v[192:193]
	ds_read_b128 v[160:163], v247 offset:32768
	ds_read_b128 v[164:167], v247 offset:33792
	ds_read_b128 v[168:171], v247 offset:34816
	ds_read_b128 v[172:175], v247 offset:35840
	ds_read_b128 v[176:179], v247 offset:36864
	ds_read_b128 v[180:183], v247 offset:37888
	ds_read_b128 v[184:187], v247 offset:38912
	ds_read_b128 v[188:191], v247 offset:39936
	global_load_lds_dwordx4 v[212:213], off
	v_lshl_add_u64 v[212:213], s[66:67], 0, v[196:197]
	s_mov_b32 m0, s19
	s_nop 0
	global_load_lds_dwordx4 v[212:213], off
	s_waitcnt vmcnt(8)
	s_waitcnt lgkmcnt(0)
	s_barrier
	s_setprio 1
	v_mfma_f32_16x16x32_bf16 v[140:143], v[120:123], v[160:163], v[140:143]
	v_mfma_f32_16x16x32_bf16 v[140:143], v[124:127], v[164:167], v[140:143]
	v_mfma_f32_16x16x32_bf16 v[136:139], v[128:131], v[160:163], v[136:139]
	v_mfma_f32_16x16x32_bf16 v[136:139], v[132:135], v[164:167], v[136:139]
	v_mfma_f32_16x16x32_bf16 v[108:111], v[120:123], v[168:171], v[108:111]
	v_mfma_f32_16x16x32_bf16 v[108:111], v[124:127], v[172:175], v[108:111]
	v_mfma_f32_16x16x32_bf16 v[104:107], v[128:131], v[168:171], v[104:107]
	v_mfma_f32_16x16x32_bf16 v[104:107], v[132:135], v[172:175], v[104:107]
	v_mfma_f32_16x16x32_bf16 v[92:95], v[120:123], v[176:179], v[92:95]
	v_mfma_f32_16x16x32_bf16 v[92:95], v[124:127], v[180:183], v[92:95]
	v_mfma_f32_16x16x32_bf16 v[88:91], v[128:131], v[176:179], v[88:91]
	v_mfma_f32_16x16x32_bf16 v[88:91], v[132:135], v[180:183], v[88:91]
	v_mfma_f32_16x16x32_bf16 v[76:79], v[120:123], v[184:187], v[76:79]
	v_mfma_f32_16x16x32_bf16 v[76:79], v[124:127], v[188:191], v[76:79]
	v_mfma_f32_16x16x32_bf16 v[72:75], v[128:131], v[184:187], v[72:75]
	v_mfma_f32_16x16x32_bf16 v[72:75], v[132:135], v[188:191], v[72:75]
	v_mfma_f32_16x16x32_bf16 v[116:119], v[144:147], v[160:163], v[116:119]
	v_mfma_f32_16x16x32_bf16 v[116:119], v[148:151], v[164:167], v[116:119]
	v_mfma_f32_16x16x32_bf16 v[112:115], v[152:155], v[160:163], v[112:115]
	v_mfma_f32_16x16x32_bf16 v[112:115], v[156:159], v[164:167], v[112:115]
	v_mfma_f32_16x16x32_bf16 v[100:103], v[144:147], v[168:171], v[100:103]
	v_mfma_f32_16x16x32_bf16 v[100:103], v[148:151], v[172:175], v[100:103]
	v_mfma_f32_16x16x32_bf16 v[96:99], v[152:155], v[168:171], v[96:99]
	v_mfma_f32_16x16x32_bf16 v[96:99], v[156:159], v[172:175], v[96:99]
	v_mfma_f32_16x16x32_bf16 v[84:87], v[144:147], v[176:179], v[84:87]
	v_mfma_f32_16x16x32_bf16 v[84:87], v[148:151], v[180:183], v[84:87]
	v_mfma_f32_16x16x32_bf16 v[80:83], v[152:155], v[176:179], v[80:83]
	v_mfma_f32_16x16x32_bf16 v[80:83], v[156:159], v[180:183], v[80:83]
	v_mfma_f32_16x16x32_bf16 v[68:71], v[144:147], v[184:187], v[68:71]
	v_mfma_f32_16x16x32_bf16 v[68:71], v[148:151], v[188:191], v[68:71]
	s_setprio 3
	s_barrier
	v_mfma_f32_16x16x32_bf16 v[64:67], v[152:155], v[184:187], v[64:67]
	v_mfma_f32_16x16x32_bf16 v[64:67], v[156:159], v[188:191], v[64:67]
	s_setprio 0
	s_add_i32 s59, s59, s15
	v_lshl_add_u64 v[204:205], v[204:205], 0, s[46:47]
	s_mov_b32 m0, s59
	ds_read_b128 v[160:163], v247 offset:49152
	ds_read_b128 v[164:167], v247 offset:50176
	ds_read_b128 v[168:171], v247 offset:51200
	ds_read_b128 v[172:175], v247 offset:52224
	ds_read_b128 v[176:179], v247 offset:53248
	ds_read_b128 v[180:183], v247 offset:54272
	ds_read_b128 v[184:187], v247 offset:55296
	ds_read_b128 v[188:191], v247 offset:56320
	global_load_lds_dwordx4 v[204:205], off
	s_add_i32 m0, s59, 0x2000
	s_add_u32 s66, s84, 0x40080
	v_lshl_add_u64 v[204:205], v[206:207], 0, s[46:47]
	s_addc_u32 s67, s85, 0
	s_add_i32 s59, s68, s15
	global_load_lds_dwordx4 v[204:205], off
	v_lshl_add_u64 v[204:205], s[66:67], 0, v[194:195]
	s_mov_b32 m0, s59
	s_nop 0
	global_load_lds_dwordx4 v[204:205], off
	v_lshl_add_u64 v[204:205], s[66:67], 0, v[198:199]
	s_add_i32 m0, s59, 0x2000
	s_nop 0
	global_load_lds_dwordx4 v[204:205], off
	v_lshl_add_u64 v[204:205], v[208:209], 0, s[46:47]
	s_mov_b32 m0, s21
	s_nop 0
	global_load_lds_dwordx4 v[204:205], off
	v_lshl_add_u64 v[204:205], v[210:211], 0, s[46:47]
	s_mov_b32 m0, s22
	s_nop 0
	global_load_lds_dwordx4 v[204:205], off
	s_waitcnt vmcnt(8)
	s_waitcnt lgkmcnt(0)
	s_barrier
	s_setprio 1
	v_mfma_f32_16x16x32_bf16 v[60:63], v[120:123], v[160:163], v[60:63]
	v_mfma_f32_16x16x32_bf16 v[60:63], v[124:127], v[164:167], v[60:63]
	v_mfma_f32_16x16x32_bf16 v[56:59], v[128:131], v[160:163], v[56:59]
	v_mfma_f32_16x16x32_bf16 v[56:59], v[132:135], v[164:167], v[56:59]
	v_mfma_f32_16x16x32_bf16 v[44:47], v[120:123], v[168:171], v[44:47]
	v_mfma_f32_16x16x32_bf16 v[44:47], v[124:127], v[172:175], v[44:47]
	v_mfma_f32_16x16x32_bf16 v[40:43], v[128:131], v[168:171], v[40:43]
	v_mfma_f32_16x16x32_bf16 v[40:43], v[132:135], v[172:175], v[40:43]
	v_mfma_f32_16x16x32_bf16 v[28:31], v[120:123], v[176:179], v[28:31]
	v_mfma_f32_16x16x32_bf16 v[28:31], v[124:127], v[180:183], v[28:31]
	v_mfma_f32_16x16x32_bf16 v[24:27], v[128:131], v[176:179], v[24:27]
	v_mfma_f32_16x16x32_bf16 v[24:27], v[132:135], v[180:183], v[24:27]
	v_mfma_f32_16x16x32_bf16 v[12:15], v[120:123], v[184:187], v[12:15]
	v_mfma_f32_16x16x32_bf16 v[12:15], v[124:127], v[188:191], v[12:15]
	v_mfma_f32_16x16x32_bf16 v[8:11], v[128:131], v[184:187], v[8:11]
	v_mfma_f32_16x16x32_bf16 v[8:11], v[132:135], v[188:191], v[8:11]
	v_mfma_f32_16x16x32_bf16 v[52:55], v[144:147], v[160:163], v[52:55]
	v_mfma_f32_16x16x32_bf16 v[52:55], v[148:151], v[164:167], v[52:55]
	v_mfma_f32_16x16x32_bf16 v[48:51], v[152:155], v[160:163], v[48:51]
	v_mfma_f32_16x16x32_bf16 v[48:51], v[156:159], v[164:167], v[48:51]
	v_mfma_f32_16x16x32_bf16 v[36:39], v[144:147], v[168:171], v[36:39]
	v_mfma_f32_16x16x32_bf16 v[36:39], v[148:151], v[172:175], v[36:39]
	v_mfma_f32_16x16x32_bf16 v[32:35], v[152:155], v[168:171], v[32:35]
	v_mfma_f32_16x16x32_bf16 v[32:35], v[156:159], v[172:175], v[32:35]
	v_mfma_f32_16x16x32_bf16 v[20:23], v[144:147], v[176:179], v[20:23]
	v_mfma_f32_16x16x32_bf16 v[20:23], v[148:151], v[180:183], v[20:23]
	v_mfma_f32_16x16x32_bf16 v[16:19], v[152:155], v[176:179], v[16:19]
	v_mfma_f32_16x16x32_bf16 v[16:19], v[156:159], v[180:183], v[16:19]
	v_mfma_f32_16x16x32_bf16 v[4:7], v[144:147], v[184:187], v[4:7]
	v_mfma_f32_16x16x32_bf16 v[4:7], v[148:151], v[188:191], v[4:7]
	s_setprio 3
	s_barrier
	v_mfma_f32_16x16x32_bf16 v[0:3], v[152:155], v[184:187], v[0:3]
	v_mfma_f32_16x16x32_bf16 v[0:3], v[156:159], v[188:191], v[0:3]
	s_setprio 0
	s_add_i32 s58, s58, 2
	s_add_u32 s82, s82, 0x100
	s_addc_u32 s83, s83, 0
	s_add_u32 s56, s56, 0x100
	s_addc_u32 s57, s57, 0
	s_cmp_gt_u32 s58, 13
	s_cbranch_scc0 .LBB0_993
	s_branch .Lzskip_3

.Lzskip_3:
	s_and_b64 vcc, exec, s[48:49]
	s_cbranch_vccz .LBB0_996
	s_barrier

.LBB0_1147:
	s_ashr_i32 s49, s48, 31
	s_lshl_b64 s[50:51], s[48:49], 19
	s_add_u32 s50, s12, s50
	s_addc_u32 s51, s13, s51
	s_and_b64 s[52:53], s[4:5], exec
	s_cselect_b32 s49, s51, s79
	s_cselect_b32 s54, s50, s78
	s_ashr_i32 s47, s46, 31
	s_lshl_b64 s[52:53], s[46:47], 19
	s_add_u32 s52, s14, s52
	s_addc_u32 s53, s15, s53
	s_and_b64 s[58:59], s[4:5], exec
	s_cselect_b32 s47, s53, s81
	s_cselect_b32 s55, s52, s80
	s_add_u32 s78, s78, 0x40080
	s_addc_u32 s79, s79, 0
	s_add_u32 s58, s80, 0x100
	v_mov_b32_e32 v0, 0
	s_addc_u32 s59, s81, 0
	s_mov_b32 s66, -2
	s_waitcnt lgkmcnt(0)
.LBB0_1148:
	ds_read_b128 v[146:149], v174
	ds_read_b128 v[150:153], v174 offset:1024
	ds_read_b128 v[154:157], v174 offset:2048
	ds_read_b128 v[158:161], v174 offset:3072
	ds_read_b128 v[162:165], v175
	ds_read_b128 v[178:181], v175 offset:1024
	ds_read_b128 v[182:185], v175 offset:2048
	ds_read_b128 v[186:189], v175 offset:3072
	s_add_u32 s67, s78, 0xfffc0080
	s_addc_u32 s68, s79, -1
	s_cmp_eq_u32 s66, 12
	s_cselect_b32 s83, s49, s68
	s_cselect_b32 s82, s54, s67
	s_cselect_b32 s81, s47, s59
	s_cselect_b32 s80, s55, s58
	v_lshl_add_u64 v[166:167], s[78:79], 0, v[136:137]
	s_add_i32 m0, s17, 0xc000
	ds_read_b128 v[190:193], v176
	ds_read_b128 v[194:197], v176 offset:1024
	ds_read_b128 v[198:201], v176 offset:2048
	ds_read_b128 v[202:205], v176 offset:3072
	ds_read_b128 v[206:209], v176 offset:4096
	ds_read_b128 v[210:213], v176 offset:5120
	ds_read_b128 v[214:217], v176 offset:6144
	ds_read_b128 v[218:221], v176 offset:7168
	global_load_lds_dwordx4 v[166:167], off
	v_lshl_add_u64 v[166:167], s[78:79], 0, v[140:141]
	s_add_i32 m0, s17, 0xe000
	s_nop 0
	global_load_lds_dwordx4 v[166:167], off
	s_cmp_eq_u32 s66, -2
	s_waitcnt vmcnt(8)
	s_waitcnt lgkmcnt(0)
	s_barrier
	s_setprio 1
	s_cbranch_scc1 .Lzv_4_0
	v_mfma_f32_16x16x32_bf16 v[124:127], v[146:149], v[190:193], v[124:127]
	v_mfma_f32_16x16x32_bf16 v[124:127], v[150:153], v[194:197], v[124:127]
	v_mfma_f32_16x16x32_bf16 v[116:119], v[154:157], v[190:193], v[116:119]
	v_mfma_f32_16x16x32_bf16 v[116:119], v[158:161], v[194:197], v[116:119]
	v_mfma_f32_16x16x32_bf16 v[108:111], v[146:149], v[198:201], v[108:111]
	v_mfma_f32_16x16x32_bf16 v[108:111], v[150:153], v[202:205], v[108:111]
	v_mfma_f32_16x16x32_bf16 v[100:103], v[154:157], v[198:201], v[100:103]
	v_mfma_f32_16x16x32_bf16 v[100:103], v[158:161], v[202:205], v[100:103]
	v_mfma_f32_16x16x32_bf16 v[92:95], v[146:149], v[206:209], v[92:95]
	v_mfma_f32_16x16x32_bf16 v[92:95], v[150:153], v[210:213], v[92:95]
	v_mfma_f32_16x16x32_bf16 v[84:87], v[154:157], v[206:209], v[84:87]
	v_mfma_f32_16x16x32_bf16 v[84:87], v[158:161], v[210:213], v[84:87]
	v_mfma_f32_16x16x32_bf16 v[76:79], v[146:149], v[214:217], v[76:79]
	v_mfma_f32_16x16x32_bf16 v[76:79], v[150:153], v[218:221], v[76:79]
	v_mfma_f32_16x16x32_bf16 v[68:71], v[154:157], v[214:217], v[68:71]
	v_mfma_f32_16x16x32_bf16 v[68:71], v[158:161], v[218:221], v[68:71]
	v_mfma_f32_16x16x32_bf16 v[120:123], v[162:165], v[190:193], v[120:123]
	v_mfma_f32_16x16x32_bf16 v[120:123], v[178:181], v[194:197], v[120:123]
	v_mfma_f32_16x16x32_bf16 v[112:115], v[182:185], v[190:193], v[112:115]
	v_mfma_f32_16x16x32_bf16 v[112:115], v[186:189], v[194:197], v[112:115]
	v_mfma_f32_16x16x32_bf16 v[104:107], v[162:165], v[198:201], v[104:107]
	v_mfma_f32_16x16x32_bf16 v[104:107], v[178:181], v[202:205], v[104:107]
	v_mfma_f32_16x16x32_bf16 v[96:99], v[182:185], v[198:201], v[96:99]
	v_mfma_f32_16x16x32_bf16 v[96:99], v[186:189], v[202:205], v[96:99]
	v_mfma_f32_16x16x32_bf16 v[88:91], v[162:165], v[206:209], v[88:91]
	v_mfma_f32_16x16x32_bf16 v[88:91], v[178:181], v[210:213], v[88:91]
	v_mfma_f32_16x16x32_bf16 v[80:83], v[182:185], v[206:209], v[80:83]
	v_mfma_f32_16x16x32_bf16 v[80:83], v[186:189], v[210:213], v[80:83]
	v_mfma_f32_16x16x32_bf16 v[72:75], v[162:165], v[214:217], v[72:75]
	v_mfma_f32_16x16x32_bf16 v[72:75], v[178:181], v[218:221], v[72:75]
	s_setprio 3
	s_barrier
	v_mfma_f32_16x16x32_bf16 v[64:67], v[182:185], v[214:217], v[64:67]
	v_mfma_f32_16x16x32_bf16 v[64:67], v[186:189], v[218:221], v[64:67]
	s_setprio 0
.Lzj_4_0:
	s_add_i32 s67, s25, s16
	v_lshl_add_u64 v[166:167], s[80:81], 0, v[132:133]
	s_mov_b32 m0, s67
	ds_read_b128 v[190:193], v176 offset:16384
	ds_read_b128 v[194:197], v176 offset:17408
	ds_read_b128 v[198:201], v176 offset:18432
	ds_read_b128 v[202:205], v176 offset:19456
	ds_read_b128 v[206:209], v176 offset:20480
	ds_read_b128 v[210:213], v176 offset:21504
	ds_read_b128 v[214:217], v176 offset:22528
	ds_read_b128 v[218:221], v176 offset:23552
	global_load_lds_dwordx4 v[166:167], off
	s_add_i32 m0, s67, 0x2000
	s_add_u32 s68, s80, 0x40000
	v_lshl_add_u64 v[222:223], s[80:81], 0, v[128:129]
	s_addc_u32 s69, s81, 0
	s_add_i32 s67, s26, s16
	global_load_lds_dwordx4 v[222:223], off
	v_lshl_add_u64 v[224:225], s[68:69], 0, v[132:133]
	s_mov_b32 m0, s67
	v_lshl_add_u64 v[226:227], s[82:83], 0, v[130:131]
	global_load_lds_dwordx4 v[224:225], off
	v_lshl_add_u64 v[224:225], s[68:69], 0, v[128:129]
	s_add_i32 m0, s67, 0x2000
	s_nop 0
	global_load_lds_dwordx4 v[224:225], off
	v_lshl_add_u64 v[224:225], s[82:83], 0, v[134:135]
	s_mov_b32 m0, s17
	s_nop 0
	global_load_lds_dwordx4 v[224:225], off
	s_mov_b32 m0, s18
	s_nop 0
	global_load_lds_dwordx4 v[226:227], off
	s_cmp_eq_u32 s66, -2
	s_waitcnt vmcnt(8)
	s_waitcnt lgkmcnt(0)
	s_barrier
	s_setprio 1
	s_cbranch_scc1 .Lzv_4_1
	v_mfma_f32_16x16x32_bf16 v[60:63], v[146:149], v[190:193], v[60:63]
	v_mfma_f32_16x16x32_bf16 v[60:63], v[150:153], v[194:197], v[60:63]
	v_mfma_f32_16x16x32_bf16 v[52:55], v[154:157], v[190:193], v[52:55]
	v_mfma_f32_16x16x32_bf16 v[52:55], v[158:161], v[194:197], v[52:55]
	v_mfma_f32_16x16x32_bf16 v[44:47], v[146:149], v[198:201], v[44:47]
	v_mfma_f32_16x16x32_bf16 v[44:47], v[150:153], v[202:205], v[44:47]
	v_mfma_f32_16x16x32_bf16 v[36:39], v[154:157], v[198:201], v[36:39]
	v_mfma_f32_16x16x32_bf16 v[36:39], v[158:161], v[202:205], v[36:39]
	v_mfma_f32_16x16x32_bf16 v[28:31], v[146:149], v[206:209], v[28:31]
	v_mfma_f32_16x16x32_bf16 v[28:31], v[150:153], v[210:213], v[28:31]
	v_mfma_f32_16x16x32_bf16 v[20:23], v[154:157], v[206:209], v[20:23]
	v_mfma_f32_16x16x32_bf16 v[20:23], v[158:161], v[210:213], v[20:23]
	v_mfma_f32_16x16x32_bf16 v[12:15], v[146:149], v[214:217], v[12:15]
	v_mfma_f32_16x16x32_bf16 v[12:15], v[150:153], v[218:221], v[12:15]
	v_mfma_f32_16x16x32_bf16 v[4:7], v[154:157], v[214:217], v[4:7]
	v_mfma_f32_16x16x32_bf16 v[4:7], v[158:161], v[218:221], v[4:7]
	v_mfma_f32_16x16x32_bf16 v[56:59], v[162:165], v[190:193], v[56:59]
	v_mfma_f32_16x16x32_bf16 v[56:59], v[178:181], v[194:197], v[56:59]
	v_mfma_f32_16x16x32_bf16 v[48:51], v[182:185], v[190:193], v[48:51]
	v_mfma_f32_16x16x32_bf16 v[48:51], v[186:189], v[194:197], v[48:51]
	v_mfma_f32_16x16x32_bf16 v[40:43], v[162:165], v[198:201], v[40:43]
	v_mfma_f32_16x16x32_bf16 v[40:43], v[178:181], v[202:205], v[40:43]
	v_mfma_f32_16x16x32_bf16 v[32:35], v[182:185], v[198:201], v[32:35]
	v_mfma_f32_16x16x32_bf16 v[32:35], v[186:189], v[202:205], v[32:35]
	v_mfma_f32_16x16x32_bf16 v[24:27], v[162:165], v[206:209], v[24:27]
	v_mfma_f32_16x16x32_bf16 v[24:27], v[178:181], v[210:213], v[24:27]
	v_mfma_f32_16x16x32_bf16 v[16:19], v[182:185], v[206:209], v[16:19]
	v_mfma_f32_16x16x32_bf16 v[16:19], v[186:189], v[210:213], v[16:19]
	v_mfma_f32_16x16x32_bf16 v[8:11], v[162:165], v[214:217], v[8:11]
	v_mfma_f32_16x16x32_bf16 v[8:11], v[178:181], v[218:221], v[8:11]
	s_setprio 3
	s_barrier
	v_mfma_f32_16x16x32_bf16 v[0:3], v[182:185], v[214:217], v[0:3]
	v_mfma_f32_16x16x32_bf16 v[0:3], v[186:189], v[218:221], v[0:3]
	s_setprio 0
.Lzj_4_1:
	s_add_i32 s67, 0, 0x18000
	s_add_i32 s73, 0, 0x1c000
	v_add_u32_e32 v158, s67, v171
	v_add_u32_e32 v186, s73, v171
	ds_read_b128 v[146:149], v158
	ds_read_b128 v[150:153], v158 offset:1024
	ds_read_b128 v[154:157], v158 offset:2048
	ds_read_b128 v[158:161], v158 offset:3072
	ds_read_b128 v[162:165], v186
	ds_read_b128 v[178:181], v186 offset:1024
	ds_read_b128 v[182:185], v186 offset:2048
	ds_read_b128 v[186:189], v186 offset:3072
	s_add_u32 s68, s82, 0x40000
	s_addc_u32 s69, s83, 0
	s_mov_b32 m0, s19
	v_lshl_add_u64 v[228:229], s[68:69], 0, v[134:135]
	ds_read_b128 v[190:193], v176 offset:32768
	ds_read_b128 v[194:197], v176 offset:33792
	ds_read_b128 v[198:201], v176 offset:34816
	ds_read_b128 v[202:205], v176 offset:35840
	ds_read_b128 v[206:209], v176 offset:36864
	ds_read_b128 v[210:213], v176 offset:37888
	ds_read_b128 v[214:217], v176 offset:38912
	ds_read_b128 v[218:221], v176 offset:39936
	global_load_lds_dwordx4 v[228:229], off
	v_lshl_add_u64 v[228:229], s[68:69], 0, v[130:131]
	s_mov_b32 m0, s20
	s_nop 0
	global_load_lds_dwordx4 v[228:229], off
	s_waitcnt vmcnt(8)
	s_waitcnt lgkmcnt(0)
	s_barrier
	s_setprio 1
	v_mfma_f32_16x16x32_bf16 v[124:127], v[146:149], v[190:193], v[124:127]
	v_mfma_f32_16x16x32_bf16 v[124:127], v[150:153], v[194:197], v[124:127]
	v_mfma_f32_16x16x32_bf16 v[116:119], v[154:157], v[190:193], v[116:119]
	v_mfma_f32_16x16x32_bf16 v[116:119], v[158:161], v[194:197], v[116:119]
	v_mfma_f32_16x16x32_bf16 v[108:111], v[146:149], v[198:201], v[108:111]
	v_mfma_f32_16x16x32_bf16 v[108:111], v[150:153], v[202:205], v[108:111]
	v_mfma_f32_16x16x32_bf16 v[100:103], v[154:157], v[198:201], v[100:103]
	v_mfma_f32_16x16x32_bf16 v[100:103], v[158:161], v[202:205], v[100:103]
	v_mfma_f32_16x16x32_bf16 v[92:95], v[146:149], v[206:209], v[92:95]
	v_mfma_f32_16x16x32_bf16 v[92:95], v[150:153], v[210:213], v[92:95]
	v_mfma_f32_16x16x32_bf16 v[84:87], v[154:157], v[206:209], v[84:87]
	v_mfma_f32_16x16x32_bf16 v[84:87], v[158:161], v[210:213], v[84:87]
	v_mfma_f32_16x16x32_bf16 v[76:79], v[146:149], v[214:217], v[76:79]
	v_mfma_f32_16x16x32_bf16 v[76:79], v[150:153], v[218:221], v[76:79]
	v_mfma_f32_16x16x32_bf16 v[68:71], v[154:157], v[214:217], v[68:71]
	v_mfma_f32_16x16x32_bf16 v[68:71], v[158:161], v[218:221], v[68:71]
	v_mfma_f32_16x16x32_bf16 v[120:123], v[162:165], v[190:193], v[120:123]
	v_mfma_f32_16x16x32_bf16 v[120:123], v[178:181], v[194:197], v[120:123]
	v_mfma_f32_16x16x32_bf16 v[112:115], v[182:185], v[190:193], v[112:115]
	v_mfma_f32_16x16x32_bf16 v[112:115], v[186:189], v[194:197], v[112:115]
	v_mfma_f32_16x16x32_bf16 v[104:107], v[162:165], v[198:201], v[104:107]
	v_mfma_f32_16x16x32_bf16 v[104:107], v[178:181], v[202:205], v[104:107]
	v_mfma_f32_16x16x32_bf16 v[96:99], v[182:185], v[198:201], v[96:99]
	v_mfma_f32_16x16x32_bf16 v[96:99], v[186:189], v[202:205], v[96:99]
	v_mfma_f32_16x16x32_bf16 v[88:91], v[162:165], v[206:209], v[88:91]
	v_mfma_f32_16x16x32_bf16 v[88:91], v[178:181], v[210:213], v[88:91]
	v_mfma_f32_16x16x32_bf16 v[80:83], v[182:185], v[206:209], v[80:83]
	v_mfma_f32_16x16x32_bf16 v[80:83], v[186:189], v[210:213], v[80:83]
	v_mfma_f32_16x16x32_bf16 v[72:75], v[162:165], v[214:217], v[72:75]
	v_mfma_f32_16x16x32_bf16 v[72:75], v[178:181], v[218:221], v[72:75]
	s_setprio 3
	s_barrier
	v_mfma_f32_16x16x32_bf16 v[64:67], v[182:185], v[214:217], v[64:67]
	v_mfma_f32_16x16x32_bf16 v[64:67], v[186:189], v[218:221], v[64:67]
	s_setprio 0
	s_add_i32 s67, s67, s16
	v_lshl_add_u64 v[166:167], v[166:167], 0, s[10:11]
	s_mov_b32 m0, s67
	ds_read_b128 v[190:193], v176 offset:49152
	ds_read_b128 v[194:197], v176 offset:50176
	ds_read_b128 v[198:201], v176 offset:51200
	ds_read_b128 v[202:205], v176 offset:52224
	ds_read_b128 v[206:209], v176 offset:53248
	ds_read_b128 v[210:213], v176 offset:54272
	ds_read_b128 v[214:217], v176 offset:55296
	ds_read_b128 v[218:221], v176 offset:56320
	global_load_lds_dwordx4 v[166:167], off
	s_add_i32 m0, s67, 0x2000
	s_add_u32 s68, s80, 0x40080
	v_lshl_add_u64 v[166:167], v[222:223], 0, s[10:11]
	s_addc_u32 s69, s81, 0
	s_add_i32 s67, s73, s16
	global_load_lds_dwordx4 v[166:167], off
	v_lshl_add_u64 v[166:167], s[68:69], 0, v[132:133]
	s_mov_b32 m0, s67
	s_nop 0
	global_load_lds_dwordx4 v[166:167], off
	v_lshl_add_u64 v[166:167], s[68:69], 0, v[128:129]
	s_add_i32 m0, s67, 0x2000
	s_nop 0
	global_load_lds_dwordx4 v[166:167], off
	v_lshl_add_u64 v[166:167], v[224:225], 0, s[10:11]
	s_mov_b32 m0, s23
	s_nop 0
	global_load_lds_dwordx4 v[166:167], off
	v_lshl_add_u64 v[166:167], v[226:227], 0, s[10:11]
	s_mov_b32 m0, s24
	s_nop 0
	global_load_lds_dwordx4 v[166:167], off
	s_waitcnt vmcnt(8)
	s_waitcnt lgkmcnt(0)
	s_barrier
	s_setprio 1
	v_mfma_f32_16x16x32_bf16 v[60:63], v[146:149], v[190:193], v[60:63]
	v_mfma_f32_16x16x32_bf16 v[60:63], v[150:153], v[194:197], v[60:63]
	v_mfma_f32_16x16x32_bf16 v[52:55], v[154:157], v[190:193], v[52:55]
	v_mfma_f32_16x16x32_bf16 v[52:55], v[158:161], v[194:197], v[52:55]
	v_mfma_f32_16x16x32_bf16 v[44:47], v[146:149], v[198:201], v[44:47]
	v_mfma_f32_16x16x32_bf16 v[44:47], v[150:153], v[202:205], v[44:47]
	v_mfma_f32_16x16x32_bf16 v[36:39], v[154:157], v[198:201], v[36:39]
	v_mfma_f32_16x16x32_bf16 v[36:39], v[158:161], v[202:205], v[36:39]
	v_mfma_f32_16x16x32_bf16 v[28:31], v[146:149], v[206:209], v[28:31]
	v_mfma_f32_16x16x32_bf16 v[28:31], v[150:153], v[210:213], v[28:31]
	v_mfma_f32_16x16x32_bf16 v[20:23], v[154:157], v[206:209], v[20:23]
	v_mfma_f32_16x16x32_bf16 v[20:23], v[158:161], v[210:213], v[20:23]
	v_mfma_f32_16x16x32_bf16 v[12:15], v[146:149], v[214:217], v[12:15]
	v_mfma_f32_16x16x32_bf16 v[12:15], v[150:153], v[218:221], v[12:15]
	v_mfma_f32_16x16x32_bf16 v[4:7], v[154:157], v[214:217], v[4:7]
	v_mfma_f32_16x16x32_bf16 v[4:7], v[158:161], v[218:221], v[4:7]
	v_mfma_f32_16x16x32_bf16 v[56:59], v[162:165], v[190:193], v[56:59]
	v_mfma_f32_16x16x32_bf16 v[56:59], v[178:181], v[194:197], v[56:59]
	v_mfma_f32_16x16x32_bf16 v[48:51], v[182:185], v[190:193], v[48:51]
	v_mfma_f32_16x16x32_bf16 v[48:51], v[186:189], v[194:197], v[48:51]
	v_mfma_f32_16x16x32_bf16 v[40:43], v[162:165], v[198:201], v[40:43]
	v_mfma_f32_16x16x32_bf16 v[40:43], v[178:181], v[202:205], v[40:43]
	v_mfma_f32_16x16x32_bf16 v[32:35], v[182:185], v[198:201], v[32:35]
	v_mfma_f32_16x16x32_bf16 v[32:35], v[186:189], v[202:205], v[32:35]
	v_mfma_f32_16x16x32_bf16 v[24:27], v[162:165], v[206:209], v[24:27]
	v_mfma_f32_16x16x32_bf16 v[24:27], v[178:181], v[210:213], v[24:27]
	v_mfma_f32_16x16x32_bf16 v[16:19], v[182:185], v[206:209], v[16:19]
	v_mfma_f32_16x16x32_bf16 v[16:19], v[186:189], v[210:213], v[16:19]
	v_mfma_f32_16x16x32_bf16 v[8:11], v[162:165], v[214:217], v[8:11]
	v_mfma_f32_16x16x32_bf16 v[8:11], v[178:181], v[218:221], v[8:11]
	s_setprio 3
	s_barrier
	v_mfma_f32_16x16x32_bf16 v[0:3], v[182:185], v[214:217], v[0:3]
	v_mfma_f32_16x16x32_bf16 v[0:3], v[186:189], v[218:221], v[0:3]
	s_setprio 0
	s_add_i32 s66, s66, 2
	s_add_u32 s78, s78, 0x100
	s_addc_u32 s79, s79, 0
	s_add_u32 s58, s58, 0x100
	s_addc_u32 s59, s59, 0
	s_cmp_gt_u32 s66, 13
	s_cbranch_scc0 .LBB0_1148
	s_branch .Lzskip_4
.Lzv_4_0:
	v_mfma_f32_16x16x32_bf16 v[124:127], v[146:149], v[190:193], 0
	v_mfma_f32_16x16x32_bf16 v[124:127], v[150:153], v[194:197], v[124:127]
	v_mfma_f32_16x16x32_bf16 v[116:119], v[154:157], v[190:193], 0
	v_mfma_f32_16x16x32_bf16 v[116:119], v[158:161], v[194:197], v[116:119]
	v_mfma_f32_16x16x32_bf16 v[108:111], v[146:149], v[198:201], 0
	v_mfma_f32_16x16x32_bf16 v[108:111], v[150:153], v[202:205], v[108:111]
	v_mfma_f32_16x16x32_bf16 v[100:103], v[154:157], v[198:201], 0
	v_mfma_f32_16x16x32_bf16 v[100:103], v[158:161], v[202:205], v[100:103]
	v_mfma_f32_16x16x32_bf16 v[92:95], v[146:149], v[206:209], 0
	v_mfma_f32_16x16x32_bf16 v[92:95], v[150:153], v[210:213], v[92:95]
	v_mfma_f32_16x16x32_bf16 v[84:87], v[154:157], v[206:209], 0
	v_mfma_f32_16x16x32_bf16 v[84:87], v[158:161], v[210:213], v[84:87]
	v_mfma_f32_16x16x32_bf16 v[76:79], v[146:149], v[214:217], 0
	v_mfma_f32_16x16x32_bf16 v[76:79], v[150:153], v[218:221], v[76:79]
	v_mfma_f32_16x16x32_bf16 v[68:71], v[154:157], v[214:217], 0
	v_mfma_f32_16x16x32_bf16 v[68:71], v[158:161], v[218:221], v[68:71]
	v_mfma_f32_16x16x32_bf16 v[120:123], v[162:165], v[190:193], 0
	v_mfma_f32_16x16x32_bf16 v[120:123], v[178:181], v[194:197], v[120:123]
	v_mfma_f32_16x16x32_bf16 v[112:115], v[182:185], v[190:193], 0
	v_mfma_f32_16x16x32_bf16 v[112:115], v[186:189], v[194:197], v[112:115]
	v_mfma_f32_16x16x32_bf16 v[104:107], v[162:165], v[198:201], 0
	v_mfma_f32_16x16x32_bf16 v[104:107], v[178:181], v[202:205], v[104:107]
	v_mfma_f32_16x16x32_bf16 v[96:99], v[182:185], v[198:201], 0
	v_mfma_f32_16x16x32_bf16 v[96:99], v[186:189], v[202:205], v[96:99]
	v_mfma_f32_16x16x32_bf16 v[88:91], v[162:165], v[206:209], 0
	v_mfma_f32_16x16x32_bf16 v[88:91], v[178:181], v[210:213], v[88:91]
	v_mfma_f32_16x16x32_bf16 v[80:83], v[182:185], v[206:209], 0
	v_mfma_f32_16x16x32_bf16 v[80:83], v[186:189], v[210:213], v[80:83]
	v_mfma_f32_16x16x32_bf16 v[72:75], v[162:165], v[214:217], 0
	v_mfma_f32_16x16x32_bf16 v[72:75], v[178:181], v[218:221], v[72:75]
	s_setprio 3
	s_barrier
	v_mfma_f32_16x16x32_bf16 v[64:67], v[182:185], v[214:217], 0
	v_mfma_f32_16x16x32_bf16 v[64:67], v[186:189], v[218:221], v[64:67]
	s_setprio 0
	s_branch .Lzj_4_0
.Lzv_4_1:
	v_mfma_f32_16x16x32_bf16 v[60:63], v[146:149], v[190:193], 0
	v_mfma_f32_16x16x32_bf16 v[60:63], v[150:153], v[194:197], v[60:63]
	v_mfma_f32_16x16x32_bf16 v[52:55], v[154:157], v[190:193], 0
	v_mfma_f32_16x16x32_bf16 v[52:55], v[158:161], v[194:197], v[52:55]
	v_mfma_f32_16x16x32_bf16 v[44:47], v[146:149], v[198:201], 0
	v_mfma_f32_16x16x32_bf16 v[44:47], v[150:153], v[202:205], v[44:47]
	v_mfma_f32_16x16x32_bf16 v[36:39], v[154:157], v[198:201], 0
	v_mfma_f32_16x16x32_bf16 v[36:39], v[158:161], v[202:205], v[36:39]
	v_mfma_f32_16x16x32_bf16 v[28:31], v[146:149], v[206:209], 0
	v_mfma_f32_16x16x32_bf16 v[28:31], v[150:153], v[210:213], v[28:31]
	v_mfma_f32_16x16x32_bf16 v[20:23], v[154:157], v[206:209], 0
	v_mfma_f32_16x16x32_bf16 v[20:23], v[158:161], v[210:213], v[20:23]
	v_mfma_f32_16x16x32_bf16 v[12:15], v[146:149], v[214:217], 0
	v_mfma_f32_16x16x32_bf16 v[12:15], v[150:153], v[218:221], v[12:15]
	v_mfma_f32_16x16x32_bf16 v[4:7], v[154:157], v[214:217], 0
	v_mfma_f32_16x16x32_bf16 v[4:7], v[158:161], v[218:221], v[4:7]
	v_mfma_f32_16x16x32_bf16 v[56:59], v[162:165], v[190:193], 0
	v_mfma_f32_16x16x32_bf16 v[56:59], v[178:181], v[194:197], v[56:59]
	v_mfma_f32_16x16x32_bf16 v[48:51], v[182:185], v[190:193], 0
	v_mfma_f32_16x16x32_bf16 v[48:51], v[186:189], v[194:197], v[48:51]
	v_mfma_f32_16x16x32_bf16 v[40:43], v[162:165], v[198:201], 0
	v_mfma_f32_16x16x32_bf16 v[40:43], v[178:181], v[202:205], v[40:43]
	v_mfma_f32_16x16x32_bf16 v[32:35], v[182:185], v[198:201], 0
	v_mfma_f32_16x16x32_bf16 v[32:35], v[186:189], v[202:205], v[32:35]
	v_mfma_f32_16x16x32_bf16 v[24:27], v[162:165], v[206:209], 0
	v_mfma_f32_16x16x32_bf16 v[24:27], v[178:181], v[210:213], v[24:27]
	v_mfma_f32_16x16x32_bf16 v[16:19], v[182:185], v[206:209], 0
	v_mfma_f32_16x16x32_bf16 v[16:19], v[186:189], v[210:213], v[16:19]
	v_mfma_f32_16x16x32_bf16 v[8:11], v[162:165], v[214:217], 0
	v_mfma_f32_16x16x32_bf16 v[8:11], v[178:181], v[218:221], v[8:11]
	s_setprio 3
	s_barrier
	v_mfma_f32_16x16x32_bf16 v[0:3], v[182:185], v[214:217], 0
	v_mfma_f32_16x16x32_bf16 v[0:3], v[186:189], v[218:221], v[0:3]
	s_setprio 0
	s_branch .Lzj_4_1
.Lzskip_4:
	s_and_b64 vcc, exec, s[44:45]
	s_cbranch_vccz .LBB0_1151
	s_barrier

.LBB0_1299:
	ds_read_b128 v[120:123], v245
	ds_read_b128 v[124:127], v245 offset:1024
	ds_read_b128 v[128:131], v245 offset:2048
	ds_read_b128 v[132:135], v245 offset:3072
	ds_read_b128 v[144:147], v246
	ds_read_b128 v[148:151], v246 offset:1024
	ds_read_b128 v[152:155], v246 offset:2048
	ds_read_b128 v[156:159], v246 offset:3072
	s_add_u32 s66, s76, 0xfff50080
	s_addc_u32 s67, s77, -1
	s_cmp_eq_u32 s59, 40
	s_cselect_b32 s81, s9, s67
	s_cselect_b32 s80, s8, s66
	s_cselect_b32 s79, s53, s58
	s_cselect_b32 s78, s52, s55
	v_lshl_add_u64 v[204:205], s[76:77], 0, v[200:201]
	s_add_i32 m0, s16, 0xc000
	ds_read_b128 v[160:163], v247
	ds_read_b128 v[164:167], v247 offset:1024
	ds_read_b128 v[168:171], v247 offset:2048
	ds_read_b128 v[172:175], v247 offset:3072
	ds_read_b128 v[176:179], v247 offset:4096
	ds_read_b128 v[180:183], v247 offset:5120
	ds_read_b128 v[184:187], v247 offset:6144
	ds_read_b128 v[188:191], v247 offset:7168
	global_load_lds_dwordx4 v[204:205], off
	v_lshl_add_u64 v[204:205], s[76:77], 0, v[202:203]
	s_add_i32 m0, s16, 0xe000
	s_nop 0
	global_load_lds_dwordx4 v[204:205], off
	s_cmp_eq_u32 s59, -2
	s_waitcnt vmcnt(8)
	s_waitcnt lgkmcnt(0)
	s_barrier
	s_setprio 1
	s_cbranch_scc1 .Lzv_5_0
	v_mfma_f32_16x16x32_bf16 v[140:143], v[120:123], v[160:163], v[140:143]
	v_mfma_f32_16x16x32_bf16 v[140:143], v[124:127], v[164:167], v[140:143]
	v_mfma_f32_16x16x32_bf16 v[136:139], v[128:131], v[160:163], v[136:139]
	v_mfma_f32_16x16x32_bf16 v[136:139], v[132:135], v[164:167], v[136:139]
	v_mfma_f32_16x16x32_bf16 v[108:111], v[120:123], v[168:171], v[108:111]
	v_mfma_f32_16x16x32_bf16 v[108:111], v[124:127], v[172:175], v[108:111]
	v_mfma_f32_16x16x32_bf16 v[104:107], v[128:131], v[168:171], v[104:107]
	v_mfma_f32_16x16x32_bf16 v[104:107], v[132:135], v[172:175], v[104:107]
	v_mfma_f32_16x16x32_bf16 v[92:95], v[120:123], v[176:179], v[92:95]
	v_mfma_f32_16x16x32_bf16 v[92:95], v[124:127], v[180:183], v[92:95]
	v_mfma_f32_16x16x32_bf16 v[88:91], v[128:131], v[176:179], v[88:91]
	v_mfma_f32_16x16x32_bf16 v[88:91], v[132:135], v[180:183], v[88:91]
	v_mfma_f32_16x16x32_bf16 v[76:79], v[120:123], v[184:187], v[76:79]
	v_mfma_f32_16x16x32_bf16 v[76:79], v[124:127], v[188:191], v[76:79]
	v_mfma_f32_16x16x32_bf16 v[72:75], v[128:131], v[184:187], v[72:75]
	v_mfma_f32_16x16x32_bf16 v[72:75], v[132:135], v[188:191], v[72:75]
	v_mfma_f32_16x16x32_bf16 v[116:119], v[144:147], v[160:163], v[116:119]
	v_mfma_f32_16x16x32_bf16 v[116:119], v[148:151], v[164:167], v[116:119]
	v_mfma_f32_16x16x32_bf16 v[112:115], v[152:155], v[160:163], v[112:115]
	v_mfma_f32_16x16x32_bf16 v[112:115], v[156:159], v[164:167], v[112:115]
	v_mfma_f32_16x16x32_bf16 v[100:103], v[144:147], v[168:171], v[100:103]
	v_mfma_f32_16x16x32_bf16 v[100:103], v[148:151], v[172:175], v[100:103]
	v_mfma_f32_16x16x32_bf16 v[96:99], v[152:155], v[168:171], v[96:99]
	v_mfma_f32_16x16x32_bf16 v[96:99], v[156:159], v[172:175], v[96:99]
	v_mfma_f32_16x16x32_bf16 v[84:87], v[144:147], v[176:179], v[84:87]
	v_mfma_f32_16x16x32_bf16 v[84:87], v[148:151], v[180:183], v[84:87]
	v_mfma_f32_16x16x32_bf16 v[80:83], v[152:155], v[176:179], v[80:83]
	v_mfma_f32_16x16x32_bf16 v[80:83], v[156:159], v[180:183], v[80:83]
	v_mfma_f32_16x16x32_bf16 v[68:71], v[144:147], v[184:187], v[68:71]
	v_mfma_f32_16x16x32_bf16 v[68:71], v[148:151], v[188:191], v[68:71]
	s_setprio 3
	s_barrier
	v_mfma_f32_16x16x32_bf16 v[64:67], v[152:155], v[184:187], v[64:67]
	v_mfma_f32_16x16x32_bf16 v[64:67], v[156:159], v[188:191], v[64:67]
	s_setprio 0
.Lzj_5_0:
	s_add_i32 s66, s26, s15
	v_lshl_add_u64 v[204:205], s[78:79], 0, v[194:195]
	s_mov_b32 m0, s66
	ds_read_b128 v[160:163], v247 offset:16384
	ds_read_b128 v[164:167], v247 offset:17408
	ds_read_b128 v[168:171], v247 offset:18432
	ds_read_b128 v[172:175], v247 offset:19456
	ds_read_b128 v[176:179], v247 offset:20480
	ds_read_b128 v[180:183], v247 offset:21504
	ds_read_b128 v[184:187], v247 offset:22528
	ds_read_b128 v[188:191], v247 offset:23552
	global_load_lds_dwordx4 v[204:205], off
	s_add_i32 m0, s66, 0x2000
	s_add_u32 s66, s78, 0xb0000
	v_lshl_add_u64 v[206:207], s[78:79], 0, v[198:199]
	s_addc_u32 s67, s79, 0
	s_add_i32 s68, s27, s15
	global_load_lds_dwordx4 v[206:207], off
	v_lshl_add_u64 v[208:209], s[66:67], 0, v[194:195]
	s_mov_b32 m0, s68
	v_lshl_add_u64 v[210:211], s[80:81], 0, v[196:197]
	global_load_lds_dwordx4 v[208:209], off
	v_lshl_add_u64 v[208:209], s[66:67], 0, v[198:199]
	s_add_i32 m0, s68, 0x2000
	s_nop 0
	global_load_lds_dwordx4 v[208:209], off
	v_lshl_add_u64 v[208:209], s[80:81], 0, v[192:193]
	s_mov_b32 m0, s16
	s_nop 0
	global_load_lds_dwordx4 v[208:209], off
	s_mov_b32 m0, s17
	s_nop 0
	global_load_lds_dwordx4 v[210:211], off
	s_cmp_eq_u32 s59, -2
	s_waitcnt vmcnt(8)
	s_waitcnt lgkmcnt(0)
	s_barrier
	s_setprio 1
	s_cbranch_scc1 .Lzv_5_1
	v_mfma_f32_16x16x32_bf16 v[60:63], v[120:123], v[160:163], v[60:63]
	v_mfma_f32_16x16x32_bf16 v[60:63], v[124:127], v[164:167], v[60:63]
	v_mfma_f32_16x16x32_bf16 v[56:59], v[128:131], v[160:163], v[56:59]
	v_mfma_f32_16x16x32_bf16 v[56:59], v[132:135], v[164:167], v[56:59]
	v_mfma_f32_16x16x32_bf16 v[44:47], v[120:123], v[168:171], v[44:47]
	v_mfma_f32_16x16x32_bf16 v[44:47], v[124:127], v[172:175], v[44:47]
	v_mfma_f32_16x16x32_bf16 v[40:43], v[128:131], v[168:171], v[40:43]
	v_mfma_f32_16x16x32_bf16 v[40:43], v[132:135], v[172:175], v[40:43]
	v_mfma_f32_16x16x32_bf16 v[28:31], v[120:123], v[176:179], v[28:31]
	v_mfma_f32_16x16x32_bf16 v[28:31], v[124:127], v[180:183], v[28:31]
	v_mfma_f32_16x16x32_bf16 v[24:27], v[128:131], v[176:179], v[24:27]
	v_mfma_f32_16x16x32_bf16 v[24:27], v[132:135], v[180:183], v[24:27]
	v_mfma_f32_16x16x32_bf16 v[12:15], v[120:123], v[184:187], v[12:15]
	v_mfma_f32_16x16x32_bf16 v[12:15], v[124:127], v[188:191], v[12:15]
	v_mfma_f32_16x16x32_bf16 v[8:11], v[128:131], v[184:187], v[8:11]
	v_mfma_f32_16x16x32_bf16 v[8:11], v[132:135], v[188:191], v[8:11]
	v_mfma_f32_16x16x32_bf16 v[52:55], v[144:147], v[160:163], v[52:55]
	v_mfma_f32_16x16x32_bf16 v[52:55], v[148:151], v[164:167], v[52:55]
	v_mfma_f32_16x16x32_bf16 v[48:51], v[152:155], v[160:163], v[48:51]
	v_mfma_f32_16x16x32_bf16 v[48:51], v[156:159], v[164:167], v[48:51]
	v_mfma_f32_16x16x32_bf16 v[36:39], v[144:147], v[168:171], v[36:39]
	v_mfma_f32_16x16x32_bf16 v[36:39], v[148:151], v[172:175], v[36:39]
	v_mfma_f32_16x16x32_bf16 v[32:35], v[152:155], v[168:171], v[32:35]
	v_mfma_f32_16x16x32_bf16 v[32:35], v[156:159], v[172:175], v[32:35]
	v_mfma_f32_16x16x32_bf16 v[20:23], v[144:147], v[176:179], v[20:23]
	v_mfma_f32_16x16x32_bf16 v[20:23], v[148:151], v[180:183], v[20:23]
	v_mfma_f32_16x16x32_bf16 v[16:19], v[152:155], v[176:179], v[16:19]
	v_mfma_f32_16x16x32_bf16 v[16:19], v[156:159], v[180:183], v[16:19]
	v_mfma_f32_16x16x32_bf16 v[4:7], v[144:147], v[184:187], v[4:7]
	v_mfma_f32_16x16x32_bf16 v[4:7], v[148:151], v[188:191], v[4:7]
	s_setprio 3
	s_barrier
	v_mfma_f32_16x16x32_bf16 v[0:3], v[152:155], v[184:187], v[0:3]
	v_mfma_f32_16x16x32_bf16 v[0:3], v[156:159], v[188:191], v[0:3]
	s_setprio 0
.Lzj_5_1:
	s_add_i32 s68, 0, 0x18000
	s_add_i32 s69, 0, 0x1c000
	v_add_u32_e32 v132, s68, v243
	v_add_u32_e32 v156, s69, v243
	ds_read_b128 v[120:123], v132
	ds_read_b128 v[124:127], v132 offset:1024
	ds_read_b128 v[128:131], v132 offset:2048
	ds_read_b128 v[132:135], v132 offset:3072
	ds_read_b128 v[144:147], v156
	ds_read_b128 v[148:151], v156 offset:1024
	ds_read_b128 v[152:155], v156 offset:2048
	ds_read_b128 v[156:159], v156 offset:3072
	s_add_u32 s66, s80, 0xb0000
	s_addc_u32 s67, s81, 0
	s_mov_b32 m0, s18
	v_lshl_add_u64 v[212:213], s[66:67], 0, v[192:193]
	ds_read_b128 v[160:163], v247 offset:32768
	ds_read_b128 v[164:167], v247 offset:33792
	ds_read_b128 v[168:171], v247 offset:34816
	ds_read_b128 v[172:175], v247 offset:35840
	ds_read_b128 v[176:179], v247 offset:36864
	ds_read_b128 v[180:183], v247 offset:37888
	ds_read_b128 v[184:187], v247 offset:38912
	ds_read_b128 v[188:191], v247 offset:39936
	global_load_lds_dwordx4 v[212:213], off
	v_lshl_add_u64 v[212:213], s[66:67], 0, v[196:197]
	s_mov_b32 m0, s19
	s_nop 0
	global_load_lds_dwordx4 v[212:213], off
	s_waitcnt vmcnt(8)
	s_waitcnt lgkmcnt(0)
	s_barrier
	s_setprio 1
	v_mfma_f32_16x16x32_bf16 v[140:143], v[120:123], v[160:163], v[140:143]
	v_mfma_f32_16x16x32_bf16 v[140:143], v[124:127], v[164:167], v[140:143]
	v_mfma_f32_16x16x32_bf16 v[136:139], v[128:131], v[160:163], v[136:139]
	v_mfma_f32_16x16x32_bf16 v[136:139], v[132:135], v[164:167], v[136:139]
	v_mfma_f32_16x16x32_bf16 v[108:111], v[120:123], v[168:171], v[108:111]
	v_mfma_f32_16x16x32_bf16 v[108:111], v[124:127], v[172:175], v[108:111]
	v_mfma_f32_16x16x32_bf16 v[104:107], v[128:131], v[168:171], v[104:107]
	v_mfma_f32_16x16x32_bf16 v[104:107], v[132:135], v[172:175], v[104:107]
	v_mfma_f32_16x16x32_bf16 v[92:95], v[120:123], v[176:179], v[92:95]
	v_mfma_f32_16x16x32_bf16 v[92:95], v[124:127], v[180:183], v[92:95]
	v_mfma_f32_16x16x32_bf16 v[88:91], v[128:131], v[176:179], v[88:91]
	v_mfma_f32_16x16x32_bf16 v[88:91], v[132:135], v[180:183], v[88:91]
	v_mfma_f32_16x16x32_bf16 v[76:79], v[120:123], v[184:187], v[76:79]
	v_mfma_f32_16x16x32_bf16 v[76:79], v[124:127], v[188:191], v[76:79]
	v_mfma_f32_16x16x32_bf16 v[72:75], v[128:131], v[184:187], v[72:75]
	v_mfma_f32_16x16x32_bf16 v[72:75], v[132:135], v[188:191], v[72:75]
	v_mfma_f32_16x16x32_bf16 v[116:119], v[144:147], v[160:163], v[116:119]
	v_mfma_f32_16x16x32_bf16 v[116:119], v[148:151], v[164:167], v[116:119]
	v_mfma_f32_16x16x32_bf16 v[112:115], v[152:155], v[160:163], v[112:115]
	v_mfma_f32_16x16x32_bf16 v[112:115], v[156:159], v[164:167], v[112:115]
	v_mfma_f32_16x16x32_bf16 v[100:103], v[144:147], v[168:171], v[100:103]
	v_mfma_f32_16x16x32_bf16 v[100:103], v[148:151], v[172:175], v[100:103]
	v_mfma_f32_16x16x32_bf16 v[96:99], v[152:155], v[168:171], v[96:99]
	v_mfma_f32_16x16x32_bf16 v[96:99], v[156:159], v[172:175], v[96:99]
	v_mfma_f32_16x16x32_bf16 v[84:87], v[144:147], v[176:179], v[84:87]
	v_mfma_f32_16x16x32_bf16 v[84:87], v[148:151], v[180:183], v[84:87]
	v_mfma_f32_16x16x32_bf16 v[80:83], v[152:155], v[176:179], v[80:83]
	v_mfma_f32_16x16x32_bf16 v[80:83], v[156:159], v[180:183], v[80:83]
	v_mfma_f32_16x16x32_bf16 v[68:71], v[144:147], v[184:187], v[68:71]
	v_mfma_f32_16x16x32_bf16 v[68:71], v[148:151], v[188:191], v[68:71]
	s_setprio 3
	s_barrier
	v_mfma_f32_16x16x32_bf16 v[64:67], v[152:155], v[184:187], v[64:67]
	v_mfma_f32_16x16x32_bf16 v[64:67], v[156:159], v[188:191], v[64:67]
	s_setprio 0
	s_add_i32 s66, s68, s15
	v_lshl_add_u64 v[204:205], v[204:205], 0, s[48:49]
	s_mov_b32 m0, s66
	ds_read_b128 v[160:163], v247 offset:49152
	ds_read_b128 v[164:167], v247 offset:50176
	ds_read_b128 v[168:171], v247 offset:51200
	ds_read_b128 v[172:175], v247 offset:52224
	ds_read_b128 v[176:179], v247 offset:53248
	ds_read_b128 v[180:183], v247 offset:54272
	ds_read_b128 v[184:187], v247 offset:55296
	ds_read_b128 v[188:191], v247 offset:56320
	global_load_lds_dwordx4 v[204:205], off
	s_add_i32 m0, s66, 0x2000
	s_add_u32 s66, s78, 0xb0080
	v_lshl_add_u64 v[204:205], v[206:207], 0, s[48:49]
	s_addc_u32 s67, s79, 0
	s_add_i32 s68, s69, s15
	global_load_lds_dwordx4 v[204:205], off
	v_lshl_add_u64 v[204:205], s[66:67], 0, v[194:195]
	s_mov_b32 m0, s68
	s_nop 0
	global_load_lds_dwordx4 v[204:205], off
	v_lshl_add_u64 v[204:205], s[66:67], 0, v[198:199]
	s_add_i32 m0, s68, 0x2000
	s_nop 0
	global_load_lds_dwordx4 v[204:205], off
	v_lshl_add_u64 v[204:205], v[208:209], 0, s[48:49]
	s_mov_b32 m0, s21
	s_nop 0
	global_load_lds_dwordx4 v[204:205], off
	v_lshl_add_u64 v[204:205], v[210:211], 0, s[48:49]
	s_mov_b32 m0, s22
	s_nop 0
	global_load_lds_dwordx4 v[204:205], off
	s_waitcnt vmcnt(8)
	s_waitcnt lgkmcnt(0)
	s_barrier
	s_setprio 1
	v_mfma_f32_16x16x32_bf16 v[60:63], v[120:123], v[160:163], v[60:63]
	v_mfma_f32_16x16x32_bf16 v[60:63], v[124:127], v[164:167], v[60:63]
	v_mfma_f32_16x16x32_bf16 v[56:59], v[128:131], v[160:163], v[56:59]
	v_mfma_f32_16x16x32_bf16 v[56:59], v[132:135], v[164:167], v[56:59]
	v_mfma_f32_16x16x32_bf16 v[44:47], v[120:123], v[168:171], v[44:47]
	v_mfma_f32_16x16x32_bf16 v[44:47], v[124:127], v[172:175], v[44:47]
	v_mfma_f32_16x16x32_bf16 v[40:43], v[128:131], v[168:171], v[40:43]
	v_mfma_f32_16x16x32_bf16 v[40:43], v[132:135], v[172:175], v[40:43]
	v_mfma_f32_16x16x32_bf16 v[28:31], v[120:123], v[176:179], v[28:31]
	v_mfma_f32_16x16x32_bf16 v[28:31], v[124:127], v[180:183], v[28:31]
	v_mfma_f32_16x16x32_bf16 v[24:27], v[128:131], v[176:179], v[24:27]
	v_mfma_f32_16x16x32_bf16 v[24:27], v[132:135], v[180:183], v[24:27]
	v_mfma_f32_16x16x32_bf16 v[12:15], v[120:123], v[184:187], v[12:15]
	v_mfma_f32_16x16x32_bf16 v[12:15], v[124:127], v[188:191], v[12:15]
	v_mfma_f32_16x16x32_bf16 v[8:11], v[128:131], v[184:187], v[8:11]
	v_mfma_f32_16x16x32_bf16 v[8:11], v[132:135], v[188:191], v[8:11]
	v_mfma_f32_16x16x32_bf16 v[52:55], v[144:147], v[160:163], v[52:55]
	v_mfma_f32_16x16x32_bf16 v[52:55], v[148:151], v[164:167], v[52:55]
	v_mfma_f32_16x16x32_bf16 v[48:51], v[152:155], v[160:163], v[48:51]
	v_mfma_f32_16x16x32_bf16 v[48:51], v[156:159], v[164:167], v[48:51]
	v_mfma_f32_16x16x32_bf16 v[36:39], v[144:147], v[168:171], v[36:39]
	v_mfma_f32_16x16x32_bf16 v[36:39], v[148:151], v[172:175], v[36:39]
	v_mfma_f32_16x16x32_bf16 v[32:35], v[152:155], v[168:171], v[32:35]
	v_mfma_f32_16x16x32_bf16 v[32:35], v[156:159], v[172:175], v[32:35]
	v_mfma_f32_16x16x32_bf16 v[20:23], v[144:147], v[176:179], v[20:23]
	v_mfma_f32_16x16x32_bf16 v[20:23], v[148:151], v[180:183], v[20:23]
	v_mfma_f32_16x16x32_bf16 v[16:19], v[152:155], v[176:179], v[16:19]
	v_mfma_f32_16x16x32_bf16 v[16:19], v[156:159], v[180:183], v[16:19]
	v_mfma_f32_16x16x32_bf16 v[4:7], v[144:147], v[184:187], v[4:7]
	v_mfma_f32_16x16x32_bf16 v[4:7], v[148:151], v[188:191], v[4:7]
	s_setprio 3
	s_barrier
	v_mfma_f32_16x16x32_bf16 v[0:3], v[152:155], v[184:187], v[0:3]
	v_mfma_f32_16x16x32_bf16 v[0:3], v[156:159], v[188:191], v[0:3]
	s_setprio 0
	s_add_i32 s59, s59, 2
	s_add_u32 s76, s76, 0x100
	s_addc_u32 s77, s77, 0
	s_add_u32 s55, s55, 0x100
	s_addc_u32 s58, s58, 0
	s_cmp_gt_u32 s59, 41
	s_cbranch_scc0 .LBB0_1299
	s_branch .Lzskip_5

.Lzskip_5:
	s_and_b64 vcc, exec, s[50:51]
	s_cbranch_vccz .LBB0_1302
	s_barrier

.LBB0_1759:
	s_ashr_i32 s49, s48, 31
	s_lshl_b64 s[50:51], s[48:49], 19
	s_add_u32 s50, s12, s50
	s_addc_u32 s51, s13, s51
	s_and_b64 s[52:53], s[4:5], exec
	s_cselect_b32 s49, s51, s79
	s_cselect_b32 s54, s50, s78
	s_ashr_i32 s47, s46, 31
	s_lshl_b64 s[52:53], s[46:47], 19
	s_add_u32 s52, s14, s52
	s_addc_u32 s53, s15, s53
	s_and_b64 s[66:67], s[4:5], exec
	s_cselect_b32 s47, s53, s81
	s_cselect_b32 s55, s52, s80
	s_add_u32 s78, s78, 0x40080
	s_addc_u32 s79, s79, 0
	s_add_u32 s66, s80, 0x100
	v_mov_b32_e32 v0, 0
	s_addc_u32 s67, s81, 0
	s_mov_b32 s68, -2
	s_waitcnt lgkmcnt(0)
.LBB0_1760:
	ds_read_b128 v[128:131], v181
	ds_read_b128 v[132:135], v181 offset:1024
	ds_read_b128 v[136:139], v181 offset:2048
	ds_read_b128 v[160:163], v181 offset:3072
	ds_read_b128 v[164:167], v182
	ds_read_b128 v[168:171], v182 offset:1024
	ds_read_b128 v[186:189], v182 offset:2048
	ds_read_b128 v[190:193], v182 offset:3072
	s_add_u32 s69, s78, 0xfffc0080
	s_addc_u32 s73, s79, -1
	s_cmp_eq_u32 s68, 12
	s_cselect_b32 s83, s49, s73
	s_cselect_b32 s82, s54, s69
	s_cselect_b32 s81, s47, s67
	s_cselect_b32 s80, s55, s66
	v_lshl_add_u64 v[172:173], s[78:79], 0, v[152:153]
	s_add_i32 m0, s18, 0xc000
	ds_read_b128 v[194:197], v183
	ds_read_b128 v[198:201], v183 offset:1024
	ds_read_b128 v[202:205], v183 offset:2048
	ds_read_b128 v[206:209], v183 offset:3072
	ds_read_b128 v[210:213], v183 offset:4096
	ds_read_b128 v[214:217], v183 offset:5120
	ds_read_b128 v[218:221], v183 offset:6144
	ds_read_b128 v[222:225], v183 offset:7168
	global_load_lds_dwordx4 v[172:173], off
	v_lshl_add_u64 v[172:173], s[78:79], 0, v[154:155]
	s_add_i32 m0, s18, 0xe000
	s_nop 0
	global_load_lds_dwordx4 v[172:173], off
	s_cmp_eq_u32 s68, -2
	s_waitcnt vmcnt(8)
	s_waitcnt lgkmcnt(0)
	s_barrier
	s_setprio 1
	s_cbranch_scc1 .Lzv_8_0
	v_mfma_f32_16x16x32_bf16 v[124:127], v[128:131], v[194:197], v[124:127]
	v_mfma_f32_16x16x32_bf16 v[124:127], v[132:135], v[198:201], v[124:127]
	v_mfma_f32_16x16x32_bf16 v[120:123], v[136:139], v[194:197], v[120:123]
	v_mfma_f32_16x16x32_bf16 v[120:123], v[160:163], v[198:201], v[120:123]
	v_mfma_f32_16x16x32_bf16 v[108:111], v[128:131], v[202:205], v[108:111]
	v_mfma_f32_16x16x32_bf16 v[108:111], v[132:135], v[206:209], v[108:111]
	v_mfma_f32_16x16x32_bf16 v[104:107], v[136:139], v[202:205], v[104:107]
	v_mfma_f32_16x16x32_bf16 v[104:107], v[160:163], v[206:209], v[104:107]
	v_mfma_f32_16x16x32_bf16 v[92:95], v[128:131], v[210:213], v[92:95]
	v_mfma_f32_16x16x32_bf16 v[92:95], v[132:135], v[214:217], v[92:95]
	v_mfma_f32_16x16x32_bf16 v[88:91], v[136:139], v[210:213], v[88:91]
	v_mfma_f32_16x16x32_bf16 v[88:91], v[160:163], v[214:217], v[88:91]
	v_mfma_f32_16x16x32_bf16 v[76:79], v[128:131], v[218:221], v[76:79]
	v_mfma_f32_16x16x32_bf16 v[76:79], v[132:135], v[222:225], v[76:79]
	v_mfma_f32_16x16x32_bf16 v[72:75], v[136:139], v[218:221], v[72:75]
	v_mfma_f32_16x16x32_bf16 v[72:75], v[160:163], v[222:225], v[72:75]
	v_mfma_f32_16x16x32_bf16 v[116:119], v[164:167], v[194:197], v[116:119]
	v_mfma_f32_16x16x32_bf16 v[116:119], v[168:171], v[198:201], v[116:119]
	v_mfma_f32_16x16x32_bf16 v[112:115], v[186:189], v[194:197], v[112:115]
	v_mfma_f32_16x16x32_bf16 v[112:115], v[190:193], v[198:201], v[112:115]
	v_mfma_f32_16x16x32_bf16 v[100:103], v[164:167], v[202:205], v[100:103]
	v_mfma_f32_16x16x32_bf16 v[100:103], v[168:171], v[206:209], v[100:103]
	v_mfma_f32_16x16x32_bf16 v[96:99], v[186:189], v[202:205], v[96:99]
	v_mfma_f32_16x16x32_bf16 v[96:99], v[190:193], v[206:209], v[96:99]
	v_mfma_f32_16x16x32_bf16 v[84:87], v[164:167], v[210:213], v[84:87]
	v_mfma_f32_16x16x32_bf16 v[84:87], v[168:171], v[214:217], v[84:87]
	v_mfma_f32_16x16x32_bf16 v[80:83], v[186:189], v[210:213], v[80:83]
	v_mfma_f32_16x16x32_bf16 v[80:83], v[190:193], v[214:217], v[80:83]
	v_mfma_f32_16x16x32_bf16 v[68:71], v[164:167], v[218:221], v[68:71]
	v_mfma_f32_16x16x32_bf16 v[68:71], v[168:171], v[222:225], v[68:71]
	s_setprio 3
	s_barrier
	v_mfma_f32_16x16x32_bf16 v[64:67], v[186:189], v[218:221], v[64:67]
	v_mfma_f32_16x16x32_bf16 v[64:67], v[190:193], v[222:225], v[64:67]
	s_setprio 0
.Lzj_8_0:
	s_add_i32 s69, s25, s17
	v_lshl_add_u64 v[172:173], s[80:81], 0, v[142:143]
	s_mov_b32 m0, s69
	ds_read_b128 v[194:197], v183 offset:16384
	ds_read_b128 v[198:201], v183 offset:17408
	ds_read_b128 v[202:205], v183 offset:18432
	ds_read_b128 v[206:209], v183 offset:19456
	ds_read_b128 v[210:213], v183 offset:20480
	ds_read_b128 v[214:217], v183 offset:21504
	ds_read_b128 v[218:221], v183 offset:22528
	ds_read_b128 v[222:225], v183 offset:23552
	global_load_lds_dwordx4 v[172:173], off
	s_add_i32 m0, s69, 0x2000
	s_add_u32 s84, s80, 0x40000
	v_lshl_add_u64 v[226:227], s[80:81], 0, v[146:147]
	s_addc_u32 s85, s81, 0
	s_add_i32 s69, s26, s17
	global_load_lds_dwordx4 v[226:227], off
	v_lshl_add_u64 v[228:229], s[84:85], 0, v[142:143]
	s_mov_b32 m0, s69
	v_lshl_add_u64 v[230:231], s[82:83], 0, v[144:145]
	global_load_lds_dwordx4 v[228:229], off
	v_lshl_add_u64 v[228:229], s[84:85], 0, v[146:147]
	s_add_i32 m0, s69, 0x2000
	s_nop 0
	global_load_lds_dwordx4 v[228:229], off
	v_lshl_add_u64 v[228:229], s[82:83], 0, v[140:141]
	s_mov_b32 m0, s18
	s_nop 0
	global_load_lds_dwordx4 v[228:229], off
	s_mov_b32 m0, s19
	s_nop 0
	global_load_lds_dwordx4 v[230:231], off
	s_cmp_eq_u32 s68, -2
	s_waitcnt vmcnt(8)
	s_waitcnt lgkmcnt(0)
	s_barrier
	s_setprio 1
	s_cbranch_scc1 .Lzv_8_1
	v_mfma_f32_16x16x32_bf16 v[60:63], v[128:131], v[194:197], v[60:63]
	v_mfma_f32_16x16x32_bf16 v[60:63], v[132:135], v[198:201], v[60:63]
	v_mfma_f32_16x16x32_bf16 v[56:59], v[136:139], v[194:197], v[56:59]
	v_mfma_f32_16x16x32_bf16 v[56:59], v[160:163], v[198:201], v[56:59]
	v_mfma_f32_16x16x32_bf16 v[44:47], v[128:131], v[202:205], v[44:47]
	v_mfma_f32_16x16x32_bf16 v[44:47], v[132:135], v[206:209], v[44:47]
	v_mfma_f32_16x16x32_bf16 v[40:43], v[136:139], v[202:205], v[40:43]
	v_mfma_f32_16x16x32_bf16 v[40:43], v[160:163], v[206:209], v[40:43]
	v_mfma_f32_16x16x32_bf16 v[28:31], v[128:131], v[210:213], v[28:31]
	v_mfma_f32_16x16x32_bf16 v[28:31], v[132:135], v[214:217], v[28:31]
	v_mfma_f32_16x16x32_bf16 v[24:27], v[136:139], v[210:213], v[24:27]
	v_mfma_f32_16x16x32_bf16 v[24:27], v[160:163], v[214:217], v[24:27]
	v_mfma_f32_16x16x32_bf16 v[12:15], v[128:131], v[218:221], v[12:15]
	v_mfma_f32_16x16x32_bf16 v[12:15], v[132:135], v[222:225], v[12:15]
	v_mfma_f32_16x16x32_bf16 v[8:11], v[136:139], v[218:221], v[8:11]
	v_mfma_f32_16x16x32_bf16 v[8:11], v[160:163], v[222:225], v[8:11]
	v_mfma_f32_16x16x32_bf16 v[52:55], v[164:167], v[194:197], v[52:55]
	v_mfma_f32_16x16x32_bf16 v[52:55], v[168:171], v[198:201], v[52:55]
	v_mfma_f32_16x16x32_bf16 v[48:51], v[186:189], v[194:197], v[48:51]
	v_mfma_f32_16x16x32_bf16 v[48:51], v[190:193], v[198:201], v[48:51]
	v_mfma_f32_16x16x32_bf16 v[36:39], v[164:167], v[202:205], v[36:39]
	v_mfma_f32_16x16x32_bf16 v[36:39], v[168:171], v[206:209], v[36:39]
	v_mfma_f32_16x16x32_bf16 v[32:35], v[186:189], v[202:205], v[32:35]
	v_mfma_f32_16x16x32_bf16 v[32:35], v[190:193], v[206:209], v[32:35]
	v_mfma_f32_16x16x32_bf16 v[20:23], v[164:167], v[210:213], v[20:23]
	v_mfma_f32_16x16x32_bf16 v[20:23], v[168:171], v[214:217], v[20:23]
	v_mfma_f32_16x16x32_bf16 v[16:19], v[186:189], v[210:213], v[16:19]
	v_mfma_f32_16x16x32_bf16 v[16:19], v[190:193], v[214:217], v[16:19]
	v_mfma_f32_16x16x32_bf16 v[4:7], v[164:167], v[218:221], v[4:7]
	v_mfma_f32_16x16x32_bf16 v[4:7], v[168:171], v[222:225], v[4:7]
	s_setprio 3
	s_barrier
	v_mfma_f32_16x16x32_bf16 v[0:3], v[186:189], v[218:221], v[0:3]
	v_mfma_f32_16x16x32_bf16 v[0:3], v[190:193], v[222:225], v[0:3]
	s_setprio 0
.Lzj_8_1:
	s_add_i32 s69, 0, 0x18000
	v_add_u32_e32 v148, s69, v177
	s_add_i32 s73, 0, 0x1c000
	ds_read_b128 v[128:131], v148
	ds_read_b128 v[132:135], v148 offset:1024
	ds_read_b128 v[136:139], v148 offset:2048
	ds_read_b128 v[160:163], v148 offset:3072
	v_add_u32_e32 v148, s73, v177
	ds_read_b128 v[164:167], v148
	ds_read_b128 v[168:171], v148 offset:1024
	ds_read_b128 v[186:189], v148 offset:2048
	ds_read_b128 v[190:193], v148 offset:3072
	s_add_u32 s82, s82, 0x40000
	s_addc_u32 s83, s83, 0
	s_mov_b32 m0, s20
	v_lshl_add_u64 v[232:233], s[82:83], 0, v[140:141]
	ds_read_b128 v[194:197], v183 offset:32768
	ds_read_b128 v[198:201], v183 offset:33792
	ds_read_b128 v[202:205], v183 offset:34816
	ds_read_b128 v[206:209], v183 offset:35840
	ds_read_b128 v[210:213], v183 offset:36864
	ds_read_b128 v[214:217], v183 offset:37888
	ds_read_b128 v[218:221], v183 offset:38912
	ds_read_b128 v[222:225], v183 offset:39936
	global_load_lds_dwordx4 v[232:233], off
	v_lshl_add_u64 v[232:233], s[82:83], 0, v[144:145]
	s_mov_b32 m0, s21
	s_nop 0
	global_load_lds_dwordx4 v[232:233], off
	s_waitcnt vmcnt(8)
	s_waitcnt lgkmcnt(0)
	s_barrier
	s_setprio 1
	v_mfma_f32_16x16x32_bf16 v[124:127], v[128:131], v[194:197], v[124:127]
	v_mfma_f32_16x16x32_bf16 v[124:127], v[132:135], v[198:201], v[124:127]
	v_mfma_f32_16x16x32_bf16 v[120:123], v[136:139], v[194:197], v[120:123]
	v_mfma_f32_16x16x32_bf16 v[120:123], v[160:163], v[198:201], v[120:123]
	v_mfma_f32_16x16x32_bf16 v[108:111], v[128:131], v[202:205], v[108:111]
	v_mfma_f32_16x16x32_bf16 v[108:111], v[132:135], v[206:209], v[108:111]
	v_mfma_f32_16x16x32_bf16 v[104:107], v[136:139], v[202:205], v[104:107]
	v_mfma_f32_16x16x32_bf16 v[104:107], v[160:163], v[206:209], v[104:107]
	v_mfma_f32_16x16x32_bf16 v[92:95], v[128:131], v[210:213], v[92:95]
	v_mfma_f32_16x16x32_bf16 v[92:95], v[132:135], v[214:217], v[92:95]
	v_mfma_f32_16x16x32_bf16 v[88:91], v[136:139], v[210:213], v[88:91]
	v_mfma_f32_16x16x32_bf16 v[88:91], v[160:163], v[214:217], v[88:91]
	v_mfma_f32_16x16x32_bf16 v[76:79], v[128:131], v[218:221], v[76:79]
	v_mfma_f32_16x16x32_bf16 v[76:79], v[132:135], v[222:225], v[76:79]
	v_mfma_f32_16x16x32_bf16 v[72:75], v[136:139], v[218:221], v[72:75]
	v_mfma_f32_16x16x32_bf16 v[72:75], v[160:163], v[222:225], v[72:75]
	v_mfma_f32_16x16x32_bf16 v[116:119], v[164:167], v[194:197], v[116:119]
	v_mfma_f32_16x16x32_bf16 v[116:119], v[168:171], v[198:201], v[116:119]
	v_mfma_f32_16x16x32_bf16 v[112:115], v[186:189], v[194:197], v[112:115]
	v_mfma_f32_16x16x32_bf16 v[112:115], v[190:193], v[198:201], v[112:115]
	v_mfma_f32_16x16x32_bf16 v[100:103], v[164:167], v[202:205], v[100:103]
	v_mfma_f32_16x16x32_bf16 v[100:103], v[168:171], v[206:209], v[100:103]
	v_mfma_f32_16x16x32_bf16 v[96:99], v[186:189], v[202:205], v[96:99]
	v_mfma_f32_16x16x32_bf16 v[96:99], v[190:193], v[206:209], v[96:99]
	v_mfma_f32_16x16x32_bf16 v[84:87], v[164:167], v[210:213], v[84:87]
	v_mfma_f32_16x16x32_bf16 v[84:87], v[168:171], v[214:217], v[84:87]
	v_mfma_f32_16x16x32_bf16 v[80:83], v[186:189], v[210:213], v[80:83]
	v_mfma_f32_16x16x32_bf16 v[80:83], v[190:193], v[214:217], v[80:83]
	v_mfma_f32_16x16x32_bf16 v[68:71], v[164:167], v[218:221], v[68:71]
	v_mfma_f32_16x16x32_bf16 v[68:71], v[168:171], v[222:225], v[68:71]
	s_setprio 3
	s_barrier
	v_mfma_f32_16x16x32_bf16 v[64:67], v[186:189], v[218:221], v[64:67]
	v_mfma_f32_16x16x32_bf16 v[64:67], v[190:193], v[222:225], v[64:67]
	s_setprio 0
	s_add_i32 s69, s69, s17
	v_lshl_add_u64 v[172:173], v[172:173], 0, s[10:11]
	s_mov_b32 m0, s69
	ds_read_b128 v[194:197], v183 offset:49152
	ds_read_b128 v[198:201], v183 offset:50176
	ds_read_b128 v[202:205], v183 offset:51200
	ds_read_b128 v[206:209], v183 offset:52224
	ds_read_b128 v[210:213], v183 offset:53248
	ds_read_b128 v[214:217], v183 offset:54272
	ds_read_b128 v[218:221], v183 offset:55296
	ds_read_b128 v[222:225], v183 offset:56320
	global_load_lds_dwordx4 v[172:173], off
	s_add_i32 m0, s69, 0x2000
	s_add_u32 s80, s80, 0x40080
	v_lshl_add_u64 v[172:173], v[226:227], 0, s[10:11]
	s_addc_u32 s81, s81, 0
	s_add_i32 s69, s73, s17
	global_load_lds_dwordx4 v[172:173], off
	v_lshl_add_u64 v[172:173], s[80:81], 0, v[142:143]
	s_mov_b32 m0, s69
	s_nop 0
	global_load_lds_dwordx4 v[172:173], off
	v_lshl_add_u64 v[172:173], s[80:81], 0, v[146:147]
	s_add_i32 m0, s69, 0x2000
	s_nop 0
	global_load_lds_dwordx4 v[172:173], off
	v_lshl_add_u64 v[172:173], v[228:229], 0, s[10:11]
	s_mov_b32 m0, s23
	s_nop 0
	global_load_lds_dwordx4 v[172:173], off
	v_lshl_add_u64 v[172:173], v[230:231], 0, s[10:11]
	s_mov_b32 m0, s24
	s_nop 0
	global_load_lds_dwordx4 v[172:173], off
	s_waitcnt vmcnt(8)
	s_waitcnt lgkmcnt(0)
	s_barrier
	s_setprio 1
	v_mfma_f32_16x16x32_bf16 v[60:63], v[128:131], v[194:197], v[60:63]
	v_mfma_f32_16x16x32_bf16 v[60:63], v[132:135], v[198:201], v[60:63]
	v_mfma_f32_16x16x32_bf16 v[56:59], v[136:139], v[194:197], v[56:59]
	v_mfma_f32_16x16x32_bf16 v[56:59], v[160:163], v[198:201], v[56:59]
	v_mfma_f32_16x16x32_bf16 v[44:47], v[128:131], v[202:205], v[44:47]
	v_mfma_f32_16x16x32_bf16 v[44:47], v[132:135], v[206:209], v[44:47]
	v_mfma_f32_16x16x32_bf16 v[40:43], v[136:139], v[202:205], v[40:43]
	v_mfma_f32_16x16x32_bf16 v[40:43], v[160:163], v[206:209], v[40:43]
	v_mfma_f32_16x16x32_bf16 v[28:31], v[128:131], v[210:213], v[28:31]
	v_mfma_f32_16x16x32_bf16 v[28:31], v[132:135], v[214:217], v[28:31]
	v_mfma_f32_16x16x32_bf16 v[24:27], v[136:139], v[210:213], v[24:27]
	v_mfma_f32_16x16x32_bf16 v[24:27], v[160:163], v[214:217], v[24:27]
	v_mfma_f32_16x16x32_bf16 v[12:15], v[128:131], v[218:221], v[12:15]
	v_mfma_f32_16x16x32_bf16 v[12:15], v[132:135], v[222:225], v[12:15]
	v_mfma_f32_16x16x32_bf16 v[8:11], v[136:139], v[218:221], v[8:11]
	v_mfma_f32_16x16x32_bf16 v[8:11], v[160:163], v[222:225], v[8:11]
	v_mfma_f32_16x16x32_bf16 v[52:55], v[164:167], v[194:197], v[52:55]
	v_mfma_f32_16x16x32_bf16 v[52:55], v[168:171], v[198:201], v[52:55]
	v_mfma_f32_16x16x32_bf16 v[48:51], v[186:189], v[194:197], v[48:51]
	v_mfma_f32_16x16x32_bf16 v[48:51], v[190:193], v[198:201], v[48:51]
	v_mfma_f32_16x16x32_bf16 v[36:39], v[164:167], v[202:205], v[36:39]
	v_mfma_f32_16x16x32_bf16 v[36:39], v[168:171], v[206:209], v[36:39]
	v_mfma_f32_16x16x32_bf16 v[32:35], v[186:189], v[202:205], v[32:35]
	v_mfma_f32_16x16x32_bf16 v[32:35], v[190:193], v[206:209], v[32:35]
	v_mfma_f32_16x16x32_bf16 v[20:23], v[164:167], v[210:213], v[20:23]
	v_mfma_f32_16x16x32_bf16 v[20:23], v[168:171], v[214:217], v[20:23]
	v_mfma_f32_16x16x32_bf16 v[16:19], v[186:189], v[210:213], v[16:19]
	v_mfma_f32_16x16x32_bf16 v[16:19], v[190:193], v[214:217], v[16:19]
	v_mfma_f32_16x16x32_bf16 v[4:7], v[164:167], v[218:221], v[4:7]
	v_mfma_f32_16x16x32_bf16 v[4:7], v[168:171], v[222:225], v[4:7]
	s_setprio 3
	s_barrier
	v_mfma_f32_16x16x32_bf16 v[0:3], v[186:189], v[218:221], v[0:3]
	v_mfma_f32_16x16x32_bf16 v[0:3], v[190:193], v[222:225], v[0:3]
	s_setprio 0
	s_add_i32 s68, s68, 2
	s_add_u32 s78, s78, 0x100
	s_addc_u32 s79, s79, 0
	s_add_u32 s66, s66, 0x100
	s_addc_u32 s67, s67, 0
	s_cmp_gt_u32 s68, 13
	s_cbranch_scc0 .LBB0_1760
	s_branch .Lzskip_8
.Lzv_8_0:
	v_mfma_f32_16x16x32_bf16 v[124:127], v[128:131], v[194:197], 0
	v_mfma_f32_16x16x32_bf16 v[124:127], v[132:135], v[198:201], v[124:127]
	v_mfma_f32_16x16x32_bf16 v[120:123], v[136:139], v[194:197], 0
	v_mfma_f32_16x16x32_bf16 v[120:123], v[160:163], v[198:201], v[120:123]
	v_mfma_f32_16x16x32_bf16 v[108:111], v[128:131], v[202:205], 0
	v_mfma_f32_16x16x32_bf16 v[108:111], v[132:135], v[206:209], v[108:111]
	v_mfma_f32_16x16x32_bf16 v[104:107], v[136:139], v[202:205], 0
	v_mfma_f32_16x16x32_bf16 v[104:107], v[160:163], v[206:209], v[104:107]
	v_mfma_f32_16x16x32_bf16 v[92:95], v[128:131], v[210:213], 0
	v_mfma_f32_16x16x32_bf16 v[92:95], v[132:135], v[214:217], v[92:95]
	v_mfma_f32_16x16x32_bf16 v[88:91], v[136:139], v[210:213], 0
	v_mfma_f32_16x16x32_bf16 v[88:91], v[160:163], v[214:217], v[88:91]
	v_mfma_f32_16x16x32_bf16 v[76:79], v[128:131], v[218:221], 0
	v_mfma_f32_16x16x32_bf16 v[76:79], v[132:135], v[222:225], v[76:79]
	v_mfma_f32_16x16x32_bf16 v[72:75], v[136:139], v[218:221], 0
	v_mfma_f32_16x16x32_bf16 v[72:75], v[160:163], v[222:225], v[72:75]
	v_mfma_f32_16x16x32_bf16 v[116:119], v[164:167], v[194:197], 0
	v_mfma_f32_16x16x32_bf16 v[116:119], v[168:171], v[198:201], v[116:119]
	v_mfma_f32_16x16x32_bf16 v[112:115], v[186:189], v[194:197], 0
	v_mfma_f32_16x16x32_bf16 v[112:115], v[190:193], v[198:201], v[112:115]
	v_mfma_f32_16x16x32_bf16 v[100:103], v[164:167], v[202:205], 0
	v_mfma_f32_16x16x32_bf16 v[100:103], v[168:171], v[206:209], v[100:103]
	v_mfma_f32_16x16x32_bf16 v[96:99], v[186:189], v[202:205], 0
	v_mfma_f32_16x16x32_bf16 v[96:99], v[190:193], v[206:209], v[96:99]
	v_mfma_f32_16x16x32_bf16 v[84:87], v[164:167], v[210:213], 0
	v_mfma_f32_16x16x32_bf16 v[84:87], v[168:171], v[214:217], v[84:87]
	v_mfma_f32_16x16x32_bf16 v[80:83], v[186:189], v[210:213], 0
	v_mfma_f32_16x16x32_bf16 v[80:83], v[190:193], v[214:217], v[80:83]
	v_mfma_f32_16x16x32_bf16 v[68:71], v[164:167], v[218:221], 0
	v_mfma_f32_16x16x32_bf16 v[68:71], v[168:171], v[222:225], v[68:71]
	s_setprio 3
	s_barrier
	v_mfma_f32_16x16x32_bf16 v[64:67], v[186:189], v[218:221], 0
	v_mfma_f32_16x16x32_bf16 v[64:67], v[190:193], v[222:225], v[64:67]
	s_setprio 0
	s_branch .Lzj_8_0
.Lzv_8_1:
	v_mfma_f32_16x16x32_bf16 v[60:63], v[128:131], v[194:197], 0
	v_mfma_f32_16x16x32_bf16 v[60:63], v[132:135], v[198:201], v[60:63]
	v_mfma_f32_16x16x32_bf16 v[56:59], v[136:139], v[194:197], 0
	v_mfma_f32_16x16x32_bf16 v[56:59], v[160:163], v[198:201], v[56:59]
	v_mfma_f32_16x16x32_bf16 v[44:47], v[128:131], v[202:205], 0
	v_mfma_f32_16x16x32_bf16 v[44:47], v[132:135], v[206:209], v[44:47]
	v_mfma_f32_16x16x32_bf16 v[40:43], v[136:139], v[202:205], 0
	v_mfma_f32_16x16x32_bf16 v[40:43], v[160:163], v[206:209], v[40:43]
	v_mfma_f32_16x16x32_bf16 v[28:31], v[128:131], v[210:213], 0
	v_mfma_f32_16x16x32_bf16 v[28:31], v[132:135], v[214:217], v[28:31]
	v_mfma_f32_16x16x32_bf16 v[24:27], v[136:139], v[210:213], 0
	v_mfma_f32_16x16x32_bf16 v[24:27], v[160:163], v[214:217], v[24:27]
	v_mfma_f32_16x16x32_bf16 v[12:15], v[128:131], v[218:221], 0
	v_mfma_f32_16x16x32_bf16 v[12:15], v[132:135], v[222:225], v[12:15]
	v_mfma_f32_16x16x32_bf16 v[8:11], v[136:139], v[218:221], 0
	v_mfma_f32_16x16x32_bf16 v[8:11], v[160:163], v[222:225], v[8:11]
	v_mfma_f32_16x16x32_bf16 v[52:55], v[164:167], v[194:197], 0
	v_mfma_f32_16x16x32_bf16 v[52:55], v[168:171], v[198:201], v[52:55]
	v_mfma_f32_16x16x32_bf16 v[48:51], v[186:189], v[194:197], 0
	v_mfma_f32_16x16x32_bf16 v[48:51], v[190:193], v[198:201], v[48:51]
	v_mfma_f32_16x16x32_bf16 v[36:39], v[164:167], v[202:205], 0
	v_mfma_f32_16x16x32_bf16 v[36:39], v[168:171], v[206:209], v[36:39]
	v_mfma_f32_16x16x32_bf16 v[32:35], v[186:189], v[202:205], 0
	v_mfma_f32_16x16x32_bf16 v[32:35], v[190:193], v[206:209], v[32:35]
	v_mfma_f32_16x16x32_bf16 v[20:23], v[164:167], v[210:213], 0
	v_mfma_f32_16x16x32_bf16 v[20:23], v[168:171], v[214:217], v[20:23]
	v_mfma_f32_16x16x32_bf16 v[16:19], v[186:189], v[210:213], 0
	v_mfma_f32_16x16x32_bf16 v[16:19], v[190:193], v[214:217], v[16:19]
	v_mfma_f32_16x16x32_bf16 v[4:7], v[164:167], v[218:221], 0
	v_mfma_f32_16x16x32_bf16 v[4:7], v[168:171], v[222:225], v[4:7]
	s_setprio 3
	s_barrier
	v_mfma_f32_16x16x32_bf16 v[0:3], v[186:189], v[218:221], 0
	v_mfma_f32_16x16x32_bf16 v[0:3], v[190:193], v[222:225], v[0:3]
	s_setprio 0
	s_branch .Lzj_8_1

.LBB0_2037:
	ds_read_b128 v[120:123], v245
	ds_read_b128 v[124:127], v245 offset:1024
	ds_read_b128 v[128:131], v245 offset:2048
	ds_read_b128 v[132:135], v245 offset:3072
	ds_read_b128 v[144:147], v246
	ds_read_b128 v[148:151], v246 offset:1024
	ds_read_b128 v[152:155], v246 offset:2048
	ds_read_b128 v[156:159], v246 offset:3072
	s_add_u32 s67, s76, 0xfffc0080
	s_addc_u32 s68, s77, -1
	s_cmp_eq_u32 s66, 12
	s_cselect_b32 s81, s53, s68
	s_cselect_b32 s80, s54, s67
	s_cselect_b32 s79, s51, s57
	s_cselect_b32 s78, s55, s56
	v_lshl_add_u64 v[204:205], s[76:77], 0, v[200:201]
	s_add_i32 m0, s16, 0xc000
	ds_read_b128 v[160:163], v247
	ds_read_b128 v[164:167], v247 offset:1024
	ds_read_b128 v[168:171], v247 offset:2048
	ds_read_b128 v[172:175], v247 offset:3072
	ds_read_b128 v[176:179], v247 offset:4096
	ds_read_b128 v[180:183], v247 offset:5120
	ds_read_b128 v[184:187], v247 offset:6144
	ds_read_b128 v[188:191], v247 offset:7168
	global_load_lds_dwordx4 v[204:205], off
	v_lshl_add_u64 v[204:205], s[76:77], 0, v[202:203]
	s_add_i32 m0, s16, 0xe000
	s_nop 0
	global_load_lds_dwordx4 v[204:205], off
	s_cmp_eq_u32 s66, -2
	s_waitcnt vmcnt(8)
	s_waitcnt lgkmcnt(0)
	s_barrier
	s_setprio 1
	s_cbranch_scc1 .Lzv_9_0
	v_mfma_f32_16x16x32_bf16 v[140:143], v[120:123], v[160:163], v[140:143]
	v_mfma_f32_16x16x32_bf16 v[140:143], v[124:127], v[164:167], v[140:143]
	v_mfma_f32_16x16x32_bf16 v[136:139], v[128:131], v[160:163], v[136:139]
	v_mfma_f32_16x16x32_bf16 v[136:139], v[132:135], v[164:167], v[136:139]
	v_mfma_f32_16x16x32_bf16 v[108:111], v[120:123], v[168:171], v[108:111]
	v_mfma_f32_16x16x32_bf16 v[108:111], v[124:127], v[172:175], v[108:111]
	v_mfma_f32_16x16x32_bf16 v[104:107], v[128:131], v[168:171], v[104:107]
	v_mfma_f32_16x16x32_bf16 v[104:107], v[132:135], v[172:175], v[104:107]
	v_mfma_f32_16x16x32_bf16 v[92:95], v[120:123], v[176:179], v[92:95]
	v_mfma_f32_16x16x32_bf16 v[92:95], v[124:127], v[180:183], v[92:95]
	v_mfma_f32_16x16x32_bf16 v[88:91], v[128:131], v[176:179], v[88:91]
	v_mfma_f32_16x16x32_bf16 v[88:91], v[132:135], v[180:183], v[88:91]
	v_mfma_f32_16x16x32_bf16 v[76:79], v[120:123], v[184:187], v[76:79]
	v_mfma_f32_16x16x32_bf16 v[76:79], v[124:127], v[188:191], v[76:79]
	v_mfma_f32_16x16x32_bf16 v[72:75], v[128:131], v[184:187], v[72:75]
	v_mfma_f32_16x16x32_bf16 v[72:75], v[132:135], v[188:191], v[72:75]
	v_mfma_f32_16x16x32_bf16 v[116:119], v[144:147], v[160:163], v[116:119]
	v_mfma_f32_16x16x32_bf16 v[116:119], v[148:151], v[164:167], v[116:119]
	v_mfma_f32_16x16x32_bf16 v[112:115], v[152:155], v[160:163], v[112:115]
	v_mfma_f32_16x16x32_bf16 v[112:115], v[156:159], v[164:167], v[112:115]
	v_mfma_f32_16x16x32_bf16 v[100:103], v[144:147], v[168:171], v[100:103]
	v_mfma_f32_16x16x32_bf16 v[100:103], v[148:151], v[172:175], v[100:103]
	v_mfma_f32_16x16x32_bf16 v[96:99], v[152:155], v[168:171], v[96:99]
	v_mfma_f32_16x16x32_bf16 v[96:99], v[156:159], v[172:175], v[96:99]
	v_mfma_f32_16x16x32_bf16 v[84:87], v[144:147], v[176:179], v[84:87]
	v_mfma_f32_16x16x32_bf16 v[84:87], v[148:151], v[180:183], v[84:87]
	v_mfma_f32_16x16x32_bf16 v[80:83], v[152:155], v[176:179], v[80:83]
	v_mfma_f32_16x16x32_bf16 v[80:83], v[156:159], v[180:183], v[80:83]
	v_mfma_f32_16x16x32_bf16 v[68:71], v[144:147], v[184:187], v[68:71]
	v_mfma_f32_16x16x32_bf16 v[68:71], v[148:151], v[188:191], v[68:71]
	s_setprio 3
	s_barrier
	v_mfma_f32_16x16x32_bf16 v[64:67], v[152:155], v[184:187], v[64:67]
	v_mfma_f32_16x16x32_bf16 v[64:67], v[156:159], v[188:191], v[64:67]
	s_setprio 0
.Lzj_9_0:
	s_add_i32 s67, s26, s15
	v_lshl_add_u64 v[204:205], s[78:79], 0, v[194:195]
	s_mov_b32 m0, s67
	ds_read_b128 v[160:163], v247 offset:16384
	ds_read_b128 v[164:167], v247 offset:17408
	ds_read_b128 v[168:171], v247 offset:18432
	ds_read_b128 v[172:175], v247 offset:19456
	ds_read_b128 v[176:179], v247 offset:20480
	ds_read_b128 v[180:183], v247 offset:21504
	ds_read_b128 v[184:187], v247 offset:22528
	ds_read_b128 v[188:191], v247 offset:23552
	global_load_lds_dwordx4 v[204:205], off
	s_add_i32 m0, s67, 0x2000
	s_add_u32 s68, s78, 0x40000
	v_lshl_add_u64 v[206:207], s[78:79], 0, v[198:199]
	s_addc_u32 s69, s79, 0
	s_add_i32 s67, s27, s15
	global_load_lds_dwordx4 v[206:207], off
	v_lshl_add_u64 v[208:209], s[68:69], 0, v[194:195]
	s_mov_b32 m0, s67
	v_lshl_add_u64 v[210:211], s[80:81], 0, v[196:197]
	global_load_lds_dwordx4 v[208:209], off
	v_lshl_add_u64 v[208:209], s[68:69], 0, v[198:199]
	s_add_i32 m0, s67, 0x2000
	s_nop 0
	global_load_lds_dwordx4 v[208:209], off
	v_lshl_add_u64 v[208:209], s[80:81], 0, v[192:193]
	s_mov_b32 m0, s16
	s_nop 0
	global_load_lds_dwordx4 v[208:209], off
	s_mov_b32 m0, s17
	s_nop 0
	global_load_lds_dwordx4 v[210:211], off
	s_cmp_eq_u32 s66, -2
	s_waitcnt vmcnt(8)
	s_waitcnt lgkmcnt(0)
	s_barrier
	s_setprio 1
	s_cbranch_scc1 .Lzv_9_1
	v_mfma_f32_16x16x32_bf16 v[60:63], v[120:123], v[160:163], v[60:63]
	v_mfma_f32_16x16x32_bf16 v[60:63], v[124:127], v[164:167], v[60:63]
	v_mfma_f32_16x16x32_bf16 v[56:59], v[128:131], v[160:163], v[56:59]
	v_mfma_f32_16x16x32_bf16 v[56:59], v[132:135], v[164:167], v[56:59]
	v_mfma_f32_16x16x32_bf16 v[44:47], v[120:123], v[168:171], v[44:47]
	v_mfma_f32_16x16x32_bf16 v[44:47], v[124:127], v[172:175], v[44:47]
	v_mfma_f32_16x16x32_bf16 v[40:43], v[128:131], v[168:171], v[40:43]
	v_mfma_f32_16x16x32_bf16 v[40:43], v[132:135], v[172:175], v[40:43]
	v_mfma_f32_16x16x32_bf16 v[28:31], v[120:123], v[176:179], v[28:31]
	v_mfma_f32_16x16x32_bf16 v[28:31], v[124:127], v[180:183], v[28:31]
	v_mfma_f32_16x16x32_bf16 v[24:27], v[128:131], v[176:179], v[24:27]
	v_mfma_f32_16x16x32_bf16 v[24:27], v[132:135], v[180:183], v[24:27]
	v_mfma_f32_16x16x32_bf16 v[12:15], v[120:123], v[184:187], v[12:15]
	v_mfma_f32_16x16x32_bf16 v[12:15], v[124:127], v[188:191], v[12:15]
	v_mfma_f32_16x16x32_bf16 v[8:11], v[128:131], v[184:187], v[8:11]
	v_mfma_f32_16x16x32_bf16 v[8:11], v[132:135], v[188:191], v[8:11]
	v_mfma_f32_16x16x32_bf16 v[52:55], v[144:147], v[160:163], v[52:55]
	v_mfma_f32_16x16x32_bf16 v[52:55], v[148:151], v[164:167], v[52:55]
	v_mfma_f32_16x16x32_bf16 v[48:51], v[152:155], v[160:163], v[48:51]
	v_mfma_f32_16x16x32_bf16 v[48:51], v[156:159], v[164:167], v[48:51]
	v_mfma_f32_16x16x32_bf16 v[36:39], v[144:147], v[168:171], v[36:39]
	v_mfma_f32_16x16x32_bf16 v[36:39], v[148:151], v[172:175], v[36:39]
	v_mfma_f32_16x16x32_bf16 v[32:35], v[152:155], v[168:171], v[32:35]
	v_mfma_f32_16x16x32_bf16 v[32:35], v[156:159], v[172:175], v[32:35]
	v_mfma_f32_16x16x32_bf16 v[20:23], v[144:147], v[176:179], v[20:23]
	v_mfma_f32_16x16x32_bf16 v[20:23], v[148:151], v[180:183], v[20:23]
	v_mfma_f32_16x16x32_bf16 v[16:19], v[152:155], v[176:179], v[16:19]
	v_mfma_f32_16x16x32_bf16 v[16:19], v[156:159], v[180:183], v[16:19]
	v_mfma_f32_16x16x32_bf16 v[4:7], v[144:147], v[184:187], v[4:7]
	v_mfma_f32_16x16x32_bf16 v[4:7], v[148:151], v[188:191], v[4:7]
	s_setprio 3
	s_barrier
	v_mfma_f32_16x16x32_bf16 v[0:3], v[152:155], v[184:187], v[0:3]
	v_mfma_f32_16x16x32_bf16 v[0:3], v[156:159], v[188:191], v[0:3]
	s_setprio 0
.Lzj_9_1:
	s_add_i32 s67, 0, 0x18000
	s_add_i32 s75, 0, 0x1c000
	v_add_u32_e32 v132, s67, v243
	v_add_u32_e32 v156, s75, v243
	ds_read_b128 v[120:123], v132
	ds_read_b128 v[124:127], v132 offset:1024
	ds_read_b128 v[128:131], v132 offset:2048
	ds_read_b128 v[132:135], v132 offset:3072
	ds_read_b128 v[144:147], v156
	ds_read_b128 v[148:151], v156 offset:1024
	ds_read_b128 v[152:155], v156 offset:2048
	ds_read_b128 v[156:159], v156 offset:3072
	s_add_u32 s68, s80, 0x40000
	s_addc_u32 s69, s81, 0
	s_mov_b32 m0, s18
	v_lshl_add_u64 v[212:213], s[68:69], 0, v[192:193]
	ds_read_b128 v[160:163], v247 offset:32768
	ds_read_b128 v[164:167], v247 offset:33792
	ds_read_b128 v[168:171], v247 offset:34816
	ds_read_b128 v[172:175], v247 offset:35840
	ds_read_b128 v[176:179], v247 offset:36864
	ds_read_b128 v[180:183], v247 offset:37888
	ds_read_b128 v[184:187], v247 offset:38912
	ds_read_b128 v[188:191], v247 offset:39936
	global_load_lds_dwordx4 v[212:213], off
	v_lshl_add_u64 v[212:213], s[68:69], 0, v[196:197]
	s_mov_b32 m0, s19
	s_nop 0
	global_load_lds_dwordx4 v[212:213], off
	s_waitcnt vmcnt(8)
	s_waitcnt lgkmcnt(0)
	s_barrier
	s_setprio 1
	v_mfma_f32_16x16x32_bf16 v[140:143], v[120:123], v[160:163], v[140:143]
	v_mfma_f32_16x16x32_bf16 v[140:143], v[124:127], v[164:167], v[140:143]
	v_mfma_f32_16x16x32_bf16 v[136:139], v[128:131], v[160:163], v[136:139]
	v_mfma_f32_16x16x32_bf16 v[136:139], v[132:135], v[164:167], v[136:139]
	v_mfma_f32_16x16x32_bf16 v[108:111], v[120:123], v[168:171], v[108:111]
	v_mfma_f32_16x16x32_bf16 v[108:111], v[124:127], v[172:175], v[108:111]
	v_mfma_f32_16x16x32_bf16 v[104:107], v[128:131], v[168:171], v[104:107]
	v_mfma_f32_16x16x32_bf16 v[104:107], v[132:135], v[172:175], v[104:107]
	v_mfma_f32_16x16x32_bf16 v[92:95], v[120:123], v[176:179], v[92:95]
	v_mfma_f32_16x16x32_bf16 v[92:95], v[124:127], v[180:183], v[92:95]
	v_mfma_f32_16x16x32_bf16 v[88:91], v[128:131], v[176:179], v[88:91]
	v_mfma_f32_16x16x32_bf16 v[88:91], v[132:135], v[180:183], v[88:91]
	v_mfma_f32_16x16x32_bf16 v[76:79], v[120:123], v[184:187], v[76:79]
	v_mfma_f32_16x16x32_bf16 v[76:79], v[124:127], v[188:191], v[76:79]
	v_mfma_f32_16x16x32_bf16 v[72:75], v[128:131], v[184:187], v[72:75]
	v_mfma_f32_16x16x32_bf16 v[72:75], v[132:135], v[188:191], v[72:75]
	v_mfma_f32_16x16x32_bf16 v[116:119], v[144:147], v[160:163], v[116:119]
	v_mfma_f32_16x16x32_bf16 v[116:119], v[148:151], v[164:167], v[116:119]
	v_mfma_f32_16x16x32_bf16 v[112:115], v[152:155], v[160:163], v[112:115]
	v_mfma_f32_16x16x32_bf16 v[112:115], v[156:159], v[164:167], v[112:115]
	v_mfma_f32_16x16x32_bf16 v[100:103], v[144:147], v[168:171], v[100:103]
	v_mfma_f32_16x16x32_bf16 v[100:103], v[148:151], v[172:175], v[100:103]
	v_mfma_f32_16x16x32_bf16 v[96:99], v[152:155], v[168:171], v[96:99]
	v_mfma_f32_16x16x32_bf16 v[96:99], v[156:159], v[172:175], v[96:99]
	v_mfma_f32_16x16x32_bf16 v[84:87], v[144:147], v[176:179], v[84:87]
	v_mfma_f32_16x16x32_bf16 v[84:87], v[148:151], v[180:183], v[84:87]
	v_mfma_f32_16x16x32_bf16 v[80:83], v[152:155], v[176:179], v[80:83]
	v_mfma_f32_16x16x32_bf16 v[80:83], v[156:159], v[180:183], v[80:83]
	v_mfma_f32_16x16x32_bf16 v[68:71], v[144:147], v[184:187], v[68:71]
	v_mfma_f32_16x16x32_bf16 v[68:71], v[148:151], v[188:191], v[68:71]
	s_setprio 3
	s_barrier
	v_mfma_f32_16x16x32_bf16 v[64:67], v[152:155], v[184:187], v[64:67]
	v_mfma_f32_16x16x32_bf16 v[64:67], v[156:159], v[188:191], v[64:67]
	s_setprio 0
	s_add_i32 s67, s67, s15
	v_lshl_add_u64 v[204:205], v[204:205], 0, s[46:47]
	s_mov_b32 m0, s67
	ds_read_b128 v[160:163], v247 offset:49152
	ds_read_b128 v[164:167], v247 offset:50176
	ds_read_b128 v[168:171], v247 offset:51200
	ds_read_b128 v[172:175], v247 offset:52224
	ds_read_b128 v[176:179], v247 offset:53248
	ds_read_b128 v[180:183], v247 offset:54272
	ds_read_b128 v[184:187], v247 offset:55296
	ds_read_b128 v[188:191], v247 offset:56320
	global_load_lds_dwordx4 v[204:205], off
	s_add_i32 m0, s67, 0x2000
	s_add_u32 s68, s78, 0x40080
	v_lshl_add_u64 v[204:205], v[206:207], 0, s[46:47]
	s_addc_u32 s69, s79, 0
	s_add_i32 s67, s75, s15
	global_load_lds_dwordx4 v[204:205], off
	v_lshl_add_u64 v[204:205], s[68:69], 0, v[194:195]
	s_mov_b32 m0, s67
	s_nop 0
	global_load_lds_dwordx4 v[204:205], off
	v_lshl_add_u64 v[204:205], s[68:69], 0, v[198:199]
	s_add_i32 m0, s67, 0x2000
	s_nop 0
	global_load_lds_dwordx4 v[204:205], off
	v_lshl_add_u64 v[204:205], v[208:209], 0, s[46:47]
	s_mov_b32 m0, s21
	s_nop 0
	global_load_lds_dwordx4 v[204:205], off
	v_lshl_add_u64 v[204:205], v[210:211], 0, s[46:47]
	s_mov_b32 m0, s22
	s_nop 0
	global_load_lds_dwordx4 v[204:205], off
	s_waitcnt vmcnt(8)
	s_waitcnt lgkmcnt(0)
	s_barrier
	s_setprio 1
	v_mfma_f32_16x16x32_bf16 v[60:63], v[120:123], v[160:163], v[60:63]
	v_mfma_f32_16x16x32_bf16 v[60:63], v[124:127], v[164:167], v[60:63]
	v_mfma_f32_16x16x32_bf16 v[56:59], v[128:131], v[160:163], v[56:59]
	v_mfma_f32_16x16x32_bf16 v[56:59], v[132:135], v[164:167], v[56:59]
	v_mfma_f32_16x16x32_bf16 v[44:47], v[120:123], v[168:171], v[44:47]
	v_mfma_f32_16x16x32_bf16 v[44:47], v[124:127], v[172:175], v[44:47]
	v_mfma_f32_16x16x32_bf16 v[40:43], v[128:131], v[168:171], v[40:43]
	v_mfma_f32_16x16x32_bf16 v[40:43], v[132:135], v[172:175], v[40:43]
	v_mfma_f32_16x16x32_bf16 v[28:31], v[120:123], v[176:179], v[28:31]
	v_mfma_f32_16x16x32_bf16 v[28:31], v[124:127], v[180:183], v[28:31]
	v_mfma_f32_16x16x32_bf16 v[24:27], v[128:131], v[176:179], v[24:27]
	v_mfma_f32_16x16x32_bf16 v[24:27], v[132:135], v[180:183], v[24:27]
	v_mfma_f32_16x16x32_bf16 v[12:15], v[120:123], v[184:187], v[12:15]
	v_mfma_f32_16x16x32_bf16 v[12:15], v[124:127], v[188:191], v[12:15]
	v_mfma_f32_16x16x32_bf16 v[8:11], v[128:131], v[184:187], v[8:11]
	v_mfma_f32_16x16x32_bf16 v[8:11], v[132:135], v[188:191], v[8:11]
	v_mfma_f32_16x16x32_bf16 v[52:55], v[144:147], v[160:163], v[52:55]
	v_mfma_f32_16x16x32_bf16 v[52:55], v[148:151], v[164:167], v[52:55]
	v_mfma_f32_16x16x32_bf16 v[48:51], v[152:155], v[160:163], v[48:51]
	v_mfma_f32_16x16x32_bf16 v[48:51], v[156:159], v[164:167], v[48:51]
	v_mfma_f32_16x16x32_bf16 v[36:39], v[144:147], v[168:171], v[36:39]
	v_mfma_f32_16x16x32_bf16 v[36:39], v[148:151], v[172:175], v[36:39]
	v_mfma_f32_16x16x32_bf16 v[32:35], v[152:155], v[168:171], v[32:35]
	v_mfma_f32_16x16x32_bf16 v[32:35], v[156:159], v[172:175], v[32:35]
	v_mfma_f32_16x16x32_bf16 v[20:23], v[144:147], v[176:179], v[20:23]
	v_mfma_f32_16x16x32_bf16 v[20:23], v[148:151], v[180:183], v[20:23]
	v_mfma_f32_16x16x32_bf16 v[16:19], v[152:155], v[176:179], v[16:19]
	v_mfma_f32_16x16x32_bf16 v[16:19], v[156:159], v[180:183], v[16:19]
	v_mfma_f32_16x16x32_bf16 v[4:7], v[144:147], v[184:187], v[4:7]
	v_mfma_f32_16x16x32_bf16 v[4:7], v[148:151], v[188:191], v[4:7]
	s_setprio 3
	s_barrier
	v_mfma_f32_16x16x32_bf16 v[0:3], v[152:155], v[184:187], v[0:3]
	v_mfma_f32_16x16x32_bf16 v[0:3], v[156:159], v[188:191], v[0:3]
	s_setprio 0
	s_add_i32 s66, s66, 2
	s_add_u32 s76, s76, 0x100
	s_addc_u32 s77, s77, 0
	s_add_u32 s56, s56, 0x100
	s_addc_u32 s57, s57, 0
	s_cmp_gt_u32 s66, 13
	s_cbranch_scc0 .LBB0_2037
	s_branch .Lzskip_9

.LBB0_2191:
	s_ashr_i32 s47, s46, 31
	s_lshl_b64 s[48:49], s[46:47], 19
	s_add_u32 s48, s12, s48
	s_addc_u32 s49, s13, s49
	s_and_b64 s[50:51], s[4:5], exec
	s_cselect_b32 s47, s49, s59
	s_cselect_b32 s53, s48, s58
	s_ashr_i32 s45, s44, 31
	s_lshl_b64 s[50:51], s[44:45], 19
	s_add_u32 s50, s14, s50
	s_addc_u32 s51, s15, s51
	s_and_b64 s[66:67], s[4:5], exec
	s_cselect_b32 s45, s51, s73
	s_cselect_b32 s66, s50, s72
	s_add_u32 s58, s58, 0x40080
	s_addc_u32 s59, s59, 0
	s_add_u32 s67, s72, 0x100
	v_mov_b32_e32 v0, 0
	s_addc_u32 s68, s73, 0
	s_mov_b32 s69, -2
	s_waitcnt lgkmcnt(0)
.LBB0_2192:
	ds_read_b128 v[146:149], v174
	ds_read_b128 v[150:153], v174 offset:1024
	ds_read_b128 v[154:157], v174 offset:2048
	ds_read_b128 v[158:161], v174 offset:3072
	ds_read_b128 v[162:165], v175
	ds_read_b128 v[178:181], v175 offset:1024
	ds_read_b128 v[182:185], v175 offset:2048
	ds_read_b128 v[186:189], v175 offset:3072
	s_add_u32 s70, s58, 0xfffc0080
	s_addc_u32 s71, s59, -1
	s_cmp_eq_u32 s69, 12
	s_cselect_b32 s73, s47, s71
	s_cselect_b32 s72, s53, s70
	s_cselect_b32 s71, s45, s68
	s_cselect_b32 s70, s66, s67
	v_lshl_add_u64 v[166:167], s[58:59], 0, v[136:137]
	s_add_i32 m0, s17, 0xc000
	ds_read_b128 v[190:193], v176
	ds_read_b128 v[194:197], v176 offset:1024
	ds_read_b128 v[198:201], v176 offset:2048
	ds_read_b128 v[202:205], v176 offset:3072
	ds_read_b128 v[206:209], v176 offset:4096
	ds_read_b128 v[210:213], v176 offset:5120
	ds_read_b128 v[214:217], v176 offset:6144
	ds_read_b128 v[218:221], v176 offset:7168
	global_load_lds_dwordx4 v[166:167], off
	v_lshl_add_u64 v[166:167], s[58:59], 0, v[140:141]
	s_add_i32 m0, s17, 0xe000
	s_nop 0
	global_load_lds_dwordx4 v[166:167], off
	s_cmp_eq_u32 s69, -2
	s_waitcnt vmcnt(8)
	s_waitcnt lgkmcnt(0)
	s_barrier
	s_setprio 1
	s_cbranch_scc1 .Lzv_10_0
	v_mfma_f32_16x16x32_bf16 v[124:127], v[146:149], v[190:193], v[124:127]
	v_mfma_f32_16x16x32_bf16 v[124:127], v[150:153], v[194:197], v[124:127]
	v_mfma_f32_16x16x32_bf16 v[116:119], v[154:157], v[190:193], v[116:119]
	v_mfma_f32_16x16x32_bf16 v[116:119], v[158:161], v[194:197], v[116:119]
	v_mfma_f32_16x16x32_bf16 v[108:111], v[146:149], v[198:201], v[108:111]
	v_mfma_f32_16x16x32_bf16 v[108:111], v[150:153], v[202:205], v[108:111]
	v_mfma_f32_16x16x32_bf16 v[100:103], v[154:157], v[198:201], v[100:103]
	v_mfma_f32_16x16x32_bf16 v[100:103], v[158:161], v[202:205], v[100:103]
	v_mfma_f32_16x16x32_bf16 v[92:95], v[146:149], v[206:209], v[92:95]
	v_mfma_f32_16x16x32_bf16 v[92:95], v[150:153], v[210:213], v[92:95]
	v_mfma_f32_16x16x32_bf16 v[84:87], v[154:157], v[206:209], v[84:87]
	v_mfma_f32_16x16x32_bf16 v[84:87], v[158:161], v[210:213], v[84:87]
	v_mfma_f32_16x16x32_bf16 v[76:79], v[146:149], v[214:217], v[76:79]
	v_mfma_f32_16x16x32_bf16 v[76:79], v[150:153], v[218:221], v[76:79]
	v_mfma_f32_16x16x32_bf16 v[68:71], v[154:157], v[214:217], v[68:71]
	v_mfma_f32_16x16x32_bf16 v[68:71], v[158:161], v[218:221], v[68:71]
	v_mfma_f32_16x16x32_bf16 v[120:123], v[162:165], v[190:193], v[120:123]
	v_mfma_f32_16x16x32_bf16 v[120:123], v[178:181], v[194:197], v[120:123]
	v_mfma_f32_16x16x32_bf16 v[112:115], v[182:185], v[190:193], v[112:115]
	v_mfma_f32_16x16x32_bf16 v[112:115], v[186:189], v[194:197], v[112:115]
	v_mfma_f32_16x16x32_bf16 v[104:107], v[162:165], v[198:201], v[104:107]
	v_mfma_f32_16x16x32_bf16 v[104:107], v[178:181], v[202:205], v[104:107]
	v_mfma_f32_16x16x32_bf16 v[96:99], v[182:185], v[198:201], v[96:99]
	v_mfma_f32_16x16x32_bf16 v[96:99], v[186:189], v[202:205], v[96:99]
	v_mfma_f32_16x16x32_bf16 v[88:91], v[162:165], v[206:209], v[88:91]
	v_mfma_f32_16x16x32_bf16 v[88:91], v[178:181], v[210:213], v[88:91]
	v_mfma_f32_16x16x32_bf16 v[80:83], v[182:185], v[206:209], v[80:83]
	v_mfma_f32_16x16x32_bf16 v[80:83], v[186:189], v[210:213], v[80:83]
	v_mfma_f32_16x16x32_bf16 v[72:75], v[162:165], v[214:217], v[72:75]
	v_mfma_f32_16x16x32_bf16 v[72:75], v[178:181], v[218:221], v[72:75]
	s_setprio 3
	s_barrier
	v_mfma_f32_16x16x32_bf16 v[64:67], v[182:185], v[214:217], v[64:67]
	v_mfma_f32_16x16x32_bf16 v[64:67], v[186:189], v[218:221], v[64:67]
	s_setprio 0
.Lzj_10_0:
	s_add_i32 s74, s26, s16
	v_lshl_add_u64 v[166:167], s[70:71], 0, v[132:133]
	s_mov_b32 m0, s74
	ds_read_b128 v[190:193], v176 offset:16384
	ds_read_b128 v[194:197], v176 offset:17408
	ds_read_b128 v[198:201], v176 offset:18432
	ds_read_b128 v[202:205], v176 offset:19456
	ds_read_b128 v[206:209], v176 offset:20480
	ds_read_b128 v[210:213], v176 offset:21504
	ds_read_b128 v[214:217], v176 offset:22528
	ds_read_b128 v[218:221], v176 offset:23552
	global_load_lds_dwordx4 v[166:167], off
	s_add_i32 m0, s74, 0x2000
	s_add_u32 s74, s70, 0x40000
	v_lshl_add_u64 v[222:223], s[70:71], 0, v[128:129]
	s_addc_u32 s75, s71, 0
	s_add_i32 s76, s27, s16
	global_load_lds_dwordx4 v[222:223], off
	v_lshl_add_u64 v[224:225], s[74:75], 0, v[132:133]
	s_mov_b32 m0, s76
	v_lshl_add_u64 v[226:227], s[72:73], 0, v[130:131]
	global_load_lds_dwordx4 v[224:225], off
	v_lshl_add_u64 v[224:225], s[74:75], 0, v[128:129]
	s_add_i32 m0, s76, 0x2000
	s_nop 0
	global_load_lds_dwordx4 v[224:225], off
	v_lshl_add_u64 v[224:225], s[72:73], 0, v[134:135]
	s_mov_b32 m0, s17
	s_nop 0
	global_load_lds_dwordx4 v[224:225], off
	s_mov_b32 m0, s18
	s_nop 0
	global_load_lds_dwordx4 v[226:227], off
	s_cmp_eq_u32 s69, -2
	s_waitcnt vmcnt(8)
	s_waitcnt lgkmcnt(0)
	s_barrier
	s_setprio 1
	s_cbranch_scc1 .Lzv_10_1
	v_mfma_f32_16x16x32_bf16 v[60:63], v[146:149], v[190:193], v[60:63]
	v_mfma_f32_16x16x32_bf16 v[60:63], v[150:153], v[194:197], v[60:63]
	v_mfma_f32_16x16x32_bf16 v[52:55], v[154:157], v[190:193], v[52:55]
	v_mfma_f32_16x16x32_bf16 v[52:55], v[158:161], v[194:197], v[52:55]
	v_mfma_f32_16x16x32_bf16 v[44:47], v[146:149], v[198:201], v[44:47]
	v_mfma_f32_16x16x32_bf16 v[44:47], v[150:153], v[202:205], v[44:47]
	v_mfma_f32_16x16x32_bf16 v[36:39], v[154:157], v[198:201], v[36:39]
	v_mfma_f32_16x16x32_bf16 v[36:39], v[158:161], v[202:205], v[36:39]
	v_mfma_f32_16x16x32_bf16 v[28:31], v[146:149], v[206:209], v[28:31]
	v_mfma_f32_16x16x32_bf16 v[28:31], v[150:153], v[210:213], v[28:31]
	v_mfma_f32_16x16x32_bf16 v[20:23], v[154:157], v[206:209], v[20:23]
	v_mfma_f32_16x16x32_bf16 v[20:23], v[158:161], v[210:213], v[20:23]
	v_mfma_f32_16x16x32_bf16 v[12:15], v[146:149], v[214:217], v[12:15]
	v_mfma_f32_16x16x32_bf16 v[12:15], v[150:153], v[218:221], v[12:15]
	v_mfma_f32_16x16x32_bf16 v[4:7], v[154:157], v[214:217], v[4:7]
	v_mfma_f32_16x16x32_bf16 v[4:7], v[158:161], v[218:221], v[4:7]
	v_mfma_f32_16x16x32_bf16 v[56:59], v[162:165], v[190:193], v[56:59]
	v_mfma_f32_16x16x32_bf16 v[56:59], v[178:181], v[194:197], v[56:59]
	v_mfma_f32_16x16x32_bf16 v[48:51], v[182:185], v[190:193], v[48:51]
	v_mfma_f32_16x16x32_bf16 v[48:51], v[186:189], v[194:197], v[48:51]
	v_mfma_f32_16x16x32_bf16 v[40:43], v[162:165], v[198:201], v[40:43]
	v_mfma_f32_16x16x32_bf16 v[40:43], v[178:181], v[202:205], v[40:43]
	v_mfma_f32_16x16x32_bf16 v[32:35], v[182:185], v[198:201], v[32:35]
	v_mfma_f32_16x16x32_bf16 v[32:35], v[186:189], v[202:205], v[32:35]
	v_mfma_f32_16x16x32_bf16 v[24:27], v[162:165], v[206:209], v[24:27]
	v_mfma_f32_16x16x32_bf16 v[24:27], v[178:181], v[210:213], v[24:27]
	v_mfma_f32_16x16x32_bf16 v[16:19], v[182:185], v[206:209], v[16:19]
	v_mfma_f32_16x16x32_bf16 v[16:19], v[186:189], v[210:213], v[16:19]
	v_mfma_f32_16x16x32_bf16 v[8:11], v[162:165], v[214:217], v[8:11]
	v_mfma_f32_16x16x32_bf16 v[8:11], v[178:181], v[218:221], v[8:11]
	s_setprio 3
	s_barrier
	v_mfma_f32_16x16x32_bf16 v[0:3], v[182:185], v[214:217], v[0:3]
	v_mfma_f32_16x16x32_bf16 v[0:3], v[186:189], v[218:221], v[0:3]
	s_setprio 0
.Lzj_10_1:
	s_add_i32 s74, 0, 0x18000
	s_add_i32 s75, 0, 0x1c000
	v_add_u32_e32 v158, s74, v171
	v_add_u32_e32 v186, s75, v171
	ds_read_b128 v[146:149], v158
	ds_read_b128 v[150:153], v158 offset:1024
	ds_read_b128 v[154:157], v158 offset:2048
	ds_read_b128 v[158:161], v158 offset:3072
	ds_read_b128 v[162:165], v186
	ds_read_b128 v[178:181], v186 offset:1024
	ds_read_b128 v[182:185], v186 offset:2048
	ds_read_b128 v[186:189], v186 offset:3072
	s_add_u32 s72, s72, 0x40000
	s_addc_u32 s73, s73, 0
	s_mov_b32 m0, s19
	v_lshl_add_u64 v[228:229], s[72:73], 0, v[134:135]
	ds_read_b128 v[190:193], v176 offset:32768
	ds_read_b128 v[194:197], v176 offset:33792
	ds_read_b128 v[198:201], v176 offset:34816
	ds_read_b128 v[202:205], v176 offset:35840
	ds_read_b128 v[206:209], v176 offset:36864
	ds_read_b128 v[210:213], v176 offset:37888
	ds_read_b128 v[214:217], v176 offset:38912
	ds_read_b128 v[218:221], v176 offset:39936
	global_load_lds_dwordx4 v[228:229], off
	v_lshl_add_u64 v[228:229], s[72:73], 0, v[130:131]
	s_mov_b32 m0, s20
	s_nop 0
	global_load_lds_dwordx4 v[228:229], off
	s_waitcnt vmcnt(8)
	s_waitcnt lgkmcnt(0)
	s_barrier
	s_setprio 1
	v_mfma_f32_16x16x32_bf16 v[124:127], v[146:149], v[190:193], v[124:127]
	v_mfma_f32_16x16x32_bf16 v[124:127], v[150:153], v[194:197], v[124:127]
	v_mfma_f32_16x16x32_bf16 v[116:119], v[154:157], v[190:193], v[116:119]
	v_mfma_f32_16x16x32_bf16 v[116:119], v[158:161], v[194:197], v[116:119]
	v_mfma_f32_16x16x32_bf16 v[108:111], v[146:149], v[198:201], v[108:111]
	v_mfma_f32_16x16x32_bf16 v[108:111], v[150:153], v[202:205], v[108:111]
	v_mfma_f32_16x16x32_bf16 v[100:103], v[154:157], v[198:201], v[100:103]
	v_mfma_f32_16x16x32_bf16 v[100:103], v[158:161], v[202:205], v[100:103]
	v_mfma_f32_16x16x32_bf16 v[92:95], v[146:149], v[206:209], v[92:95]
	v_mfma_f32_16x16x32_bf16 v[92:95], v[150:153], v[210:213], v[92:95]
	v_mfma_f32_16x16x32_bf16 v[84:87], v[154:157], v[206:209], v[84:87]
	v_mfma_f32_16x16x32_bf16 v[84:87], v[158:161], v[210:213], v[84:87]
	v_mfma_f32_16x16x32_bf16 v[76:79], v[146:149], v[214:217], v[76:79]
	v_mfma_f32_16x16x32_bf16 v[76:79], v[150:153], v[218:221], v[76:79]
	v_mfma_f32_16x16x32_bf16 v[68:71], v[154:157], v[214:217], v[68:71]
	v_mfma_f32_16x16x32_bf16 v[68:71], v[158:161], v[218:221], v[68:71]
	v_mfma_f32_16x16x32_bf16 v[120:123], v[162:165], v[190:193], v[120:123]
	v_mfma_f32_16x16x32_bf16 v[120:123], v[178:181], v[194:197], v[120:123]
	v_mfma_f32_16x16x32_bf16 v[112:115], v[182:185], v[190:193], v[112:115]
	v_mfma_f32_16x16x32_bf16 v[112:115], v[186:189], v[194:197], v[112:115]
	v_mfma_f32_16x16x32_bf16 v[104:107], v[162:165], v[198:201], v[104:107]
	v_mfma_f32_16x16x32_bf16 v[104:107], v[178:181], v[202:205], v[104:107]
	v_mfma_f32_16x16x32_bf16 v[96:99], v[182:185], v[198:201], v[96:99]
	v_mfma_f32_16x16x32_bf16 v[96:99], v[186:189], v[202:205], v[96:99]
	v_mfma_f32_16x16x32_bf16 v[88:91], v[162:165], v[206:209], v[88:91]
	v_mfma_f32_16x16x32_bf16 v[88:91], v[178:181], v[210:213], v[88:91]
	v_mfma_f32_16x16x32_bf16 v[80:83], v[182:185], v[206:209], v[80:83]
	v_mfma_f32_16x16x32_bf16 v[80:83], v[186:189], v[210:213], v[80:83]
	v_mfma_f32_16x16x32_bf16 v[72:75], v[162:165], v[214:217], v[72:75]
	v_mfma_f32_16x16x32_bf16 v[72:75], v[178:181], v[218:221], v[72:75]
	s_setprio 3
	s_barrier
	v_mfma_f32_16x16x32_bf16 v[64:67], v[182:185], v[214:217], v[64:67]
	v_mfma_f32_16x16x32_bf16 v[64:67], v[186:189], v[218:221], v[64:67]
	s_setprio 0
	s_add_i32 s72, s74, s16
	v_lshl_add_u64 v[166:167], v[166:167], 0, s[10:11]
	s_mov_b32 m0, s72
	ds_read_b128 v[190:193], v176 offset:49152
	ds_read_b128 v[194:197], v176 offset:50176
	ds_read_b128 v[198:201], v176 offset:51200
	ds_read_b128 v[202:205], v176 offset:52224
	ds_read_b128 v[206:209], v176 offset:53248
	ds_read_b128 v[210:213], v176 offset:54272
	ds_read_b128 v[214:217], v176 offset:55296
	ds_read_b128 v[218:221], v176 offset:56320
	global_load_lds_dwordx4 v[166:167], off
	s_add_i32 m0, s72, 0x2000
	s_add_u32 s70, s70, 0x40080
	v_lshl_add_u64 v[166:167], v[222:223], 0, s[10:11]
	s_addc_u32 s71, s71, 0
	s_add_i32 s72, s75, s16
	global_load_lds_dwordx4 v[166:167], off
	v_lshl_add_u64 v[166:167], s[70:71], 0, v[132:133]
	s_mov_b32 m0, s72
	s_nop 0
	global_load_lds_dwordx4 v[166:167], off
	v_lshl_add_u64 v[166:167], s[70:71], 0, v[128:129]
	s_add_i32 m0, s72, 0x2000
	s_nop 0
	global_load_lds_dwordx4 v[166:167], off
	v_lshl_add_u64 v[166:167], v[224:225], 0, s[10:11]
	s_mov_b32 m0, s23
	s_nop 0
	global_load_lds_dwordx4 v[166:167], off
	v_lshl_add_u64 v[166:167], v[226:227], 0, s[10:11]
	s_mov_b32 m0, s24
	s_nop 0
	global_load_lds_dwordx4 v[166:167], off
	s_waitcnt vmcnt(8)
	s_waitcnt lgkmcnt(0)
	s_barrier
	s_setprio 1
	v_mfma_f32_16x16x32_bf16 v[60:63], v[146:149], v[190:193], v[60:63]
	v_mfma_f32_16x16x32_bf16 v[60:63], v[150:153], v[194:197], v[60:63]
	v_mfma_f32_16x16x32_bf16 v[52:55], v[154:157], v[190:193], v[52:55]
	v_mfma_f32_16x16x32_bf16 v[52:55], v[158:161], v[194:197], v[52:55]
	v_mfma_f32_16x16x32_bf16 v[44:47], v[146:149], v[198:201], v[44:47]
	v_mfma_f32_16x16x32_bf16 v[44:47], v[150:153], v[202:205], v[44:47]
	v_mfma_f32_16x16x32_bf16 v[36:39], v[154:157], v[198:201], v[36:39]
	v_mfma_f32_16x16x32_bf16 v[36:39], v[158:161], v[202:205], v[36:39]
	v_mfma_f32_16x16x32_bf16 v[28:31], v[146:149], v[206:209], v[28:31]
	v_mfma_f32_16x16x32_bf16 v[28:31], v[150:153], v[210:213], v[28:31]
	v_mfma_f32_16x16x32_bf16 v[20:23], v[154:157], v[206:209], v[20:23]
	v_mfma_f32_16x16x32_bf16 v[20:23], v[158:161], v[210:213], v[20:23]
	v_mfma_f32_16x16x32_bf16 v[12:15], v[146:149], v[214:217], v[12:15]
	v_mfma_f32_16x16x32_bf16 v[12:15], v[150:153], v[218:221], v[12:15]
	v_mfma_f32_16x16x32_bf16 v[4:7], v[154:157], v[214:217], v[4:7]
	v_mfma_f32_16x16x32_bf16 v[4:7], v[158:161], v[218:221], v[4:7]
	v_mfma_f32_16x16x32_bf16 v[56:59], v[162:165], v[190:193], v[56:59]
	v_mfma_f32_16x16x32_bf16 v[56:59], v[178:181], v[194:197], v[56:59]
	v_mfma_f32_16x16x32_bf16 v[48:51], v[182:185], v[190:193], v[48:51]
	v_mfma_f32_16x16x32_bf16 v[48:51], v[186:189], v[194:197], v[48:51]
	v_mfma_f32_16x16x32_bf16 v[40:43], v[162:165], v[198:201], v[40:43]
	v_mfma_f32_16x16x32_bf16 v[40:43], v[178:181], v[202:205], v[40:43]
	v_mfma_f32_16x16x32_bf16 v[32:35], v[182:185], v[198:201], v[32:35]
	v_mfma_f32_16x16x32_bf16 v[32:35], v[186:189], v[202:205], v[32:35]
	v_mfma_f32_16x16x32_bf16 v[24:27], v[162:165], v[206:209], v[24:27]
	v_mfma_f32_16x16x32_bf16 v[24:27], v[178:181], v[210:213], v[24:27]
	v_mfma_f32_16x16x32_bf16 v[16:19], v[182:185], v[206:209], v[16:19]
	v_mfma_f32_16x16x32_bf16 v[16:19], v[186:189], v[210:213], v[16:19]
	v_mfma_f32_16x16x32_bf16 v[8:11], v[162:165], v[214:217], v[8:11]
	v_mfma_f32_16x16x32_bf16 v[8:11], v[178:181], v[218:221], v[8:11]
	s_setprio 3
	s_barrier
	v_mfma_f32_16x16x32_bf16 v[0:3], v[182:185], v[214:217], v[0:3]
	v_mfma_f32_16x16x32_bf16 v[0:3], v[186:189], v[218:221], v[0:3]
	s_setprio 0
	s_add_i32 s69, s69, 2
	s_add_u32 s58, s58, 0x100
	s_addc_u32 s59, s59, 0
	s_add_u32 s67, s67, 0x100
	s_addc_u32 s68, s68, 0
	s_cmp_gt_u32 s69, 13
	s_cbranch_scc0 .LBB0_2192
	s_branch .Lzskip_10

.Lzskip_10:
	s_and_b64 vcc, exec, s[42:43]
	s_cbranch_vccz .LBB0_2195
	s_barrier

.LBB0_2341:
	ds_read_b128 v[128:131], v197
	ds_read_b128 v[132:135], v197 offset:1024
	ds_read_b128 v[136:139], v197 offset:2048
	ds_read_b128 v[140:143], v197 offset:3072
	ds_read_b128 v[144:147], v198
	ds_read_b128 v[148:151], v198 offset:1024
	ds_read_b128 v[152:155], v198 offset:2048
	ds_read_b128 v[156:159], v198 offset:3072
	s_add_u32 s18, s16, 0xfff50080
	s_addc_u32 s19, s17, -1
	s_cmp_eq_u32 s45, 40
	s_cselect_b32 s21, s5, s19
	s_cselect_b32 s20, s4, s18
	s_cselect_b32 s19, s15, s44
	s_cselect_b32 s18, s14, s43
	v_lshl_add_u64 v[192:193], s[16:17], 0, v[172:173]
	s_add_i32 m0, s25, 0xc000
	ds_read_b128 v[160:163], v199
	ds_read_b128 v[180:183], v199 offset:1024
	ds_read_b128 v[184:187], v199 offset:2048
	ds_read_b128 v[188:191], v199 offset:3072
	ds_read_b128 v[200:203], v199 offset:4096
	ds_read_b128 v[204:207], v199 offset:5120
	ds_read_b128 v[208:211], v199 offset:6144
	ds_read_b128 v[212:215], v199 offset:7168
	global_load_lds_dwordx4 v[192:193], off
	v_lshl_add_u64 v[192:193], s[16:17], 0, v[174:175]
	s_add_i32 m0, s25, 0xe000
	s_nop 0
	global_load_lds_dwordx4 v[192:193], off
	s_cmp_eq_u32 s45, -2
	s_waitcnt vmcnt(8)
	s_waitcnt lgkmcnt(0)
	s_barrier
	s_setprio 1
	s_cbranch_scc1 .Lzv_11_0
	v_mfma_f32_16x16x32_bf16 v[124:127], v[128:131], v[160:163], v[124:127]
	v_mfma_f32_16x16x32_bf16 v[124:127], v[132:135], v[180:183], v[124:127]
	v_mfma_f32_16x16x32_bf16 v[120:123], v[136:139], v[160:163], v[120:123]
	v_mfma_f32_16x16x32_bf16 v[120:123], v[140:143], v[180:183], v[120:123]
	v_mfma_f32_16x16x32_bf16 v[108:111], v[128:131], v[184:187], v[108:111]
	v_mfma_f32_16x16x32_bf16 v[108:111], v[132:135], v[188:191], v[108:111]
	v_mfma_f32_16x16x32_bf16 v[104:107], v[136:139], v[184:187], v[104:107]
	v_mfma_f32_16x16x32_bf16 v[104:107], v[140:143], v[188:191], v[104:107]
	v_mfma_f32_16x16x32_bf16 v[96:99], v[128:131], v[200:203], v[96:99]
	v_mfma_f32_16x16x32_bf16 v[96:99], v[132:135], v[204:207], v[96:99]
	v_mfma_f32_16x16x32_bf16 v[88:91], v[136:139], v[200:203], v[88:91]
	v_mfma_f32_16x16x32_bf16 v[88:91], v[140:143], v[204:207], v[88:91]
	v_mfma_f32_16x16x32_bf16 v[80:83], v[128:131], v[208:211], v[80:83]
	v_mfma_f32_16x16x32_bf16 v[80:83], v[132:135], v[212:215], v[80:83]
	v_mfma_f32_16x16x32_bf16 v[72:75], v[136:139], v[208:211], v[72:75]
	v_mfma_f32_16x16x32_bf16 v[72:75], v[140:143], v[212:215], v[72:75]
	v_mfma_f32_16x16x32_bf16 v[116:119], v[144:147], v[160:163], v[116:119]
	v_mfma_f32_16x16x32_bf16 v[116:119], v[148:151], v[180:183], v[116:119]
	v_mfma_f32_16x16x32_bf16 v[112:115], v[152:155], v[160:163], v[112:115]
	v_mfma_f32_16x16x32_bf16 v[112:115], v[156:159], v[180:183], v[112:115]
	v_mfma_f32_16x16x32_bf16 v[100:103], v[144:147], v[184:187], v[100:103]
	v_mfma_f32_16x16x32_bf16 v[100:103], v[148:151], v[188:191], v[100:103]
	v_mfma_f32_16x16x32_bf16 v[92:95], v[152:155], v[184:187], v[92:95]
	v_mfma_f32_16x16x32_bf16 v[92:95], v[156:159], v[188:191], v[92:95]
	v_mfma_f32_16x16x32_bf16 v[84:87], v[144:147], v[200:203], v[84:87]
	v_mfma_f32_16x16x32_bf16 v[84:87], v[148:151], v[204:207], v[84:87]
	v_mfma_f32_16x16x32_bf16 v[76:79], v[152:155], v[200:203], v[76:79]
	v_mfma_f32_16x16x32_bf16 v[76:79], v[156:159], v[204:207], v[76:79]
	v_mfma_f32_16x16x32_bf16 v[68:71], v[144:147], v[208:211], v[68:71]
	v_mfma_f32_16x16x32_bf16 v[68:71], v[148:151], v[212:215], v[68:71]
	s_setprio 3
	s_barrier
	v_mfma_f32_16x16x32_bf16 v[64:67], v[152:155], v[208:211], v[64:67]
	v_mfma_f32_16x16x32_bf16 v[64:67], v[156:159], v[212:215], v[64:67]
	s_setprio 0
.Lzj_11_0:
	s_add_i32 s46, s37, s24
	v_lshl_add_u64 v[192:193], s[18:19], 0, v[166:167]
	s_mov_b32 m0, s46
	ds_read_b128 v[160:163], v199 offset:16384
	ds_read_b128 v[180:183], v199 offset:17408
	ds_read_b128 v[184:187], v199 offset:18432
	ds_read_b128 v[188:191], v199 offset:19456
	ds_read_b128 v[200:203], v199 offset:20480
	ds_read_b128 v[204:207], v199 offset:21504
	ds_read_b128 v[208:211], v199 offset:22528
	ds_read_b128 v[212:215], v199 offset:23552
	global_load_lds_dwordx4 v[192:193], off
	s_add_i32 m0, s46, 0x2000
	s_add_u32 s46, s18, 0xb0000
	v_lshl_add_u64 v[216:217], s[18:19], 0, v[170:171]
	s_addc_u32 s47, s19, 0
	s_add_i32 s48, s38, s24
	global_load_lds_dwordx4 v[216:217], off
	v_lshl_add_u64 v[218:219], s[46:47], 0, v[166:167]
	s_mov_b32 m0, s48
	v_lshl_add_u64 v[220:221], s[20:21], 0, v[168:169]
	global_load_lds_dwordx4 v[218:219], off
	v_lshl_add_u64 v[218:219], s[46:47], 0, v[170:171]
	s_add_i32 m0, s48, 0x2000
	s_nop 0
	global_load_lds_dwordx4 v[218:219], off
	v_lshl_add_u64 v[218:219], s[20:21], 0, v[164:165]
	s_mov_b32 m0, s25
	s_nop 0
	global_load_lds_dwordx4 v[218:219], off
	s_mov_b32 m0, s26
	s_nop 0
	global_load_lds_dwordx4 v[220:221], off
	s_cmp_eq_u32 s45, -2
	s_waitcnt vmcnt(8)
	s_waitcnt lgkmcnt(0)
	s_barrier
	s_setprio 1
	s_cbranch_scc1 .Lzv_11_1
	v_mfma_f32_16x16x32_bf16 v[60:63], v[128:131], v[160:163], v[60:63]
	v_mfma_f32_16x16x32_bf16 v[60:63], v[132:135], v[180:183], v[60:63]
	v_mfma_f32_16x16x32_bf16 v[56:59], v[136:139], v[160:163], v[56:59]
	v_mfma_f32_16x16x32_bf16 v[56:59], v[140:143], v[180:183], v[56:59]
	v_mfma_f32_16x16x32_bf16 v[48:51], v[128:131], v[184:187], v[48:51]
	v_mfma_f32_16x16x32_bf16 v[48:51], v[132:135], v[188:191], v[48:51]
	v_mfma_f32_16x16x32_bf16 v[40:43], v[136:139], v[184:187], v[40:43]
	v_mfma_f32_16x16x32_bf16 v[40:43], v[140:143], v[188:191], v[40:43]
	v_mfma_f32_16x16x32_bf16 v[32:35], v[128:131], v[200:203], v[32:35]
	v_mfma_f32_16x16x32_bf16 v[32:35], v[132:135], v[204:207], v[32:35]
	v_mfma_f32_16x16x32_bf16 v[24:27], v[136:139], v[200:203], v[24:27]
	v_mfma_f32_16x16x32_bf16 v[24:27], v[140:143], v[204:207], v[24:27]
	v_mfma_f32_16x16x32_bf16 v[16:19], v[128:131], v[208:211], v[16:19]
	v_mfma_f32_16x16x32_bf16 v[16:19], v[132:135], v[212:215], v[16:19]
	v_mfma_f32_16x16x32_bf16 v[8:11], v[136:139], v[208:211], v[8:11]
	v_mfma_f32_16x16x32_bf16 v[8:11], v[140:143], v[212:215], v[8:11]
	v_mfma_f32_16x16x32_bf16 v[52:55], v[144:147], v[160:163], v[52:55]
	v_mfma_f32_16x16x32_bf16 v[52:55], v[148:151], v[180:183], v[52:55]
	v_mfma_f32_16x16x32_bf16 v[44:47], v[152:155], v[160:163], v[44:47]
	v_mfma_f32_16x16x32_bf16 v[44:47], v[156:159], v[180:183], v[44:47]
	v_mfma_f32_16x16x32_bf16 v[36:39], v[144:147], v[184:187], v[36:39]
	v_mfma_f32_16x16x32_bf16 v[36:39], v[148:151], v[188:191], v[36:39]
	v_mfma_f32_16x16x32_bf16 v[28:31], v[152:155], v[184:187], v[28:31]
	v_mfma_f32_16x16x32_bf16 v[28:31], v[156:159], v[188:191], v[28:31]
	v_mfma_f32_16x16x32_bf16 v[20:23], v[144:147], v[200:203], v[20:23]
	v_mfma_f32_16x16x32_bf16 v[20:23], v[148:151], v[204:207], v[20:23]
	v_mfma_f32_16x16x32_bf16 v[12:15], v[152:155], v[200:203], v[12:15]
	v_mfma_f32_16x16x32_bf16 v[12:15], v[156:159], v[204:207], v[12:15]
	v_mfma_f32_16x16x32_bf16 v[4:7], v[144:147], v[208:211], v[4:7]
	v_mfma_f32_16x16x32_bf16 v[4:7], v[148:151], v[212:215], v[4:7]
	s_setprio 3
	s_barrier
	v_mfma_f32_16x16x32_bf16 v[0:3], v[152:155], v[208:211], v[0:3]
	v_mfma_f32_16x16x32_bf16 v[0:3], v[156:159], v[212:215], v[0:3]
	s_setprio 0
.Lzj_11_1:
	s_add_i32 s46, 0, 0x18000
	s_add_i32 s47, 0, 0x1c000
	v_add_u32_e32 v140, s46, v195
	v_add_u32_e32 v156, s47, v195
	ds_read_b128 v[128:131], v140
	ds_read_b128 v[132:135], v140 offset:1024
	ds_read_b128 v[136:139], v140 offset:2048
	ds_read_b128 v[140:143], v140 offset:3072
	ds_read_b128 v[144:147], v156
	ds_read_b128 v[148:151], v156 offset:1024
	ds_read_b128 v[152:155], v156 offset:2048
	ds_read_b128 v[156:159], v156 offset:3072
	s_add_u32 s20, s20, 0xb0000
	s_addc_u32 s21, s21, 0
	s_mov_b32 m0, s27
	v_lshl_add_u64 v[222:223], s[20:21], 0, v[164:165]
	ds_read_b128 v[160:163], v199 offset:32768
	ds_read_b128 v[180:183], v199 offset:33792
	ds_read_b128 v[184:187], v199 offset:34816
	ds_read_b128 v[188:191], v199 offset:35840
	ds_read_b128 v[200:203], v199 offset:36864
	ds_read_b128 v[204:207], v199 offset:37888
	ds_read_b128 v[208:211], v199 offset:38912
	ds_read_b128 v[212:215], v199 offset:39936
	global_load_lds_dwordx4 v[222:223], off
	v_lshl_add_u64 v[222:223], s[20:21], 0, v[168:169]
	s_mov_b32 m0, s28
	s_nop 0
	global_load_lds_dwordx4 v[222:223], off
	s_waitcnt vmcnt(8)
	s_waitcnt lgkmcnt(0)
	s_barrier
	s_setprio 1
	v_mfma_f32_16x16x32_bf16 v[124:127], v[128:131], v[160:163], v[124:127]
	v_mfma_f32_16x16x32_bf16 v[124:127], v[132:135], v[180:183], v[124:127]
	v_mfma_f32_16x16x32_bf16 v[120:123], v[136:139], v[160:163], v[120:123]
	v_mfma_f32_16x16x32_bf16 v[120:123], v[140:143], v[180:183], v[120:123]
	v_mfma_f32_16x16x32_bf16 v[108:111], v[128:131], v[184:187], v[108:111]
	v_mfma_f32_16x16x32_bf16 v[108:111], v[132:135], v[188:191], v[108:111]
	v_mfma_f32_16x16x32_bf16 v[104:107], v[136:139], v[184:187], v[104:107]
	v_mfma_f32_16x16x32_bf16 v[104:107], v[140:143], v[188:191], v[104:107]
	v_mfma_f32_16x16x32_bf16 v[96:99], v[128:131], v[200:203], v[96:99]
	v_mfma_f32_16x16x32_bf16 v[96:99], v[132:135], v[204:207], v[96:99]
	v_mfma_f32_16x16x32_bf16 v[88:91], v[136:139], v[200:203], v[88:91]
	v_mfma_f32_16x16x32_bf16 v[88:91], v[140:143], v[204:207], v[88:91]
	v_mfma_f32_16x16x32_bf16 v[80:83], v[128:131], v[208:211], v[80:83]
	v_mfma_f32_16x16x32_bf16 v[80:83], v[132:135], v[212:215], v[80:83]
	v_mfma_f32_16x16x32_bf16 v[72:75], v[136:139], v[208:211], v[72:75]
	v_mfma_f32_16x16x32_bf16 v[72:75], v[140:143], v[212:215], v[72:75]
	v_mfma_f32_16x16x32_bf16 v[116:119], v[144:147], v[160:163], v[116:119]
	v_mfma_f32_16x16x32_bf16 v[116:119], v[148:151], v[180:183], v[116:119]
	v_mfma_f32_16x16x32_bf16 v[112:115], v[152:155], v[160:163], v[112:115]
	v_mfma_f32_16x16x32_bf16 v[112:115], v[156:159], v[180:183], v[112:115]
	v_mfma_f32_16x16x32_bf16 v[100:103], v[144:147], v[184:187], v[100:103]
	v_mfma_f32_16x16x32_bf16 v[100:103], v[148:151], v[188:191], v[100:103]
	v_mfma_f32_16x16x32_bf16 v[92:95], v[152:155], v[184:187], v[92:95]
	v_mfma_f32_16x16x32_bf16 v[92:95], v[156:159], v[188:191], v[92:95]
	v_mfma_f32_16x16x32_bf16 v[84:87], v[144:147], v[200:203], v[84:87]
	v_mfma_f32_16x16x32_bf16 v[84:87], v[148:151], v[204:207], v[84:87]
	v_mfma_f32_16x16x32_bf16 v[76:79], v[152:155], v[200:203], v[76:79]
	v_mfma_f32_16x16x32_bf16 v[76:79], v[156:159], v[204:207], v[76:79]
	v_mfma_f32_16x16x32_bf16 v[68:71], v[144:147], v[208:211], v[68:71]
	v_mfma_f32_16x16x32_bf16 v[68:71], v[148:151], v[212:215], v[68:71]
	s_setprio 3
	s_barrier
	v_mfma_f32_16x16x32_bf16 v[64:67], v[152:155], v[208:211], v[64:67]
	v_mfma_f32_16x16x32_bf16 v[64:67], v[156:159], v[212:215], v[64:67]
	s_setprio 0
	s_add_i32 s20, s46, s24
	v_lshl_add_u64 v[192:193], v[192:193], 0, s[8:9]
	s_mov_b32 m0, s20
	ds_read_b128 v[160:163], v199 offset:49152
	ds_read_b128 v[180:183], v199 offset:50176
	ds_read_b128 v[184:187], v199 offset:51200
	ds_read_b128 v[188:191], v199 offset:52224
	ds_read_b128 v[200:203], v199 offset:53248
	ds_read_b128 v[204:207], v199 offset:54272
	ds_read_b128 v[208:211], v199 offset:55296
	ds_read_b128 v[212:215], v199 offset:56320
	global_load_lds_dwordx4 v[192:193], off
	s_add_i32 m0, s20, 0x2000
	s_add_u32 s18, s18, 0xb0080
	v_lshl_add_u64 v[192:193], v[216:217], 0, s[8:9]
	s_addc_u32 s19, s19, 0
	s_add_i32 s20, s47, s24
	global_load_lds_dwordx4 v[192:193], off
	v_lshl_add_u64 v[192:193], s[18:19], 0, v[166:167]
	s_mov_b32 m0, s20
	s_nop 0
	global_load_lds_dwordx4 v[192:193], off
	v_lshl_add_u64 v[192:193], s[18:19], 0, v[170:171]
	s_add_i32 m0, s20, 0x2000
	s_nop 0
	global_load_lds_dwordx4 v[192:193], off
	v_lshl_add_u64 v[192:193], v[218:219], 0, s[8:9]
	s_mov_b32 m0, s33
	s_nop 0
	global_load_lds_dwordx4 v[192:193], off
	v_lshl_add_u64 v[192:193], v[220:221], 0, s[8:9]
	s_mov_b32 m0, s35
	s_nop 0
	global_load_lds_dwordx4 v[192:193], off
	s_waitcnt vmcnt(8)
	s_waitcnt lgkmcnt(0)
	s_barrier
	s_setprio 1
	v_mfma_f32_16x16x32_bf16 v[60:63], v[128:131], v[160:163], v[60:63]
	v_mfma_f32_16x16x32_bf16 v[60:63], v[132:135], v[180:183], v[60:63]
	v_mfma_f32_16x16x32_bf16 v[56:59], v[136:139], v[160:163], v[56:59]
	v_mfma_f32_16x16x32_bf16 v[56:59], v[140:143], v[180:183], v[56:59]
	v_mfma_f32_16x16x32_bf16 v[48:51], v[128:131], v[184:187], v[48:51]
	v_mfma_f32_16x16x32_bf16 v[48:51], v[132:135], v[188:191], v[48:51]
	v_mfma_f32_16x16x32_bf16 v[40:43], v[136:139], v[184:187], v[40:43]
	v_mfma_f32_16x16x32_bf16 v[40:43], v[140:143], v[188:191], v[40:43]
	v_mfma_f32_16x16x32_bf16 v[32:35], v[128:131], v[200:203], v[32:35]
	v_mfma_f32_16x16x32_bf16 v[32:35], v[132:135], v[204:207], v[32:35]
	v_mfma_f32_16x16x32_bf16 v[24:27], v[136:139], v[200:203], v[24:27]
	v_mfma_f32_16x16x32_bf16 v[24:27], v[140:143], v[204:207], v[24:27]
	v_mfma_f32_16x16x32_bf16 v[16:19], v[128:131], v[208:211], v[16:19]
	v_mfma_f32_16x16x32_bf16 v[16:19], v[132:135], v[212:215], v[16:19]
	v_mfma_f32_16x16x32_bf16 v[8:11], v[136:139], v[208:211], v[8:11]
	v_mfma_f32_16x16x32_bf16 v[8:11], v[140:143], v[212:215], v[8:11]
	v_mfma_f32_16x16x32_bf16 v[52:55], v[144:147], v[160:163], v[52:55]
	v_mfma_f32_16x16x32_bf16 v[52:55], v[148:151], v[180:183], v[52:55]
	v_mfma_f32_16x16x32_bf16 v[44:47], v[152:155], v[160:163], v[44:47]
	v_mfma_f32_16x16x32_bf16 v[44:47], v[156:159], v[180:183], v[44:47]
	v_mfma_f32_16x16x32_bf16 v[36:39], v[144:147], v[184:187], v[36:39]
	v_mfma_f32_16x16x32_bf16 v[36:39], v[148:151], v[188:191], v[36:39]
	v_mfma_f32_16x16x32_bf16 v[28:31], v[152:155], v[184:187], v[28:31]
	v_mfma_f32_16x16x32_bf16 v[28:31], v[156:159], v[188:191], v[28:31]
	v_mfma_f32_16x16x32_bf16 v[20:23], v[144:147], v[200:203], v[20:23]
	v_mfma_f32_16x16x32_bf16 v[20:23], v[148:151], v[204:207], v[20:23]
	v_mfma_f32_16x16x32_bf16 v[12:15], v[152:155], v[200:203], v[12:15]
	v_mfma_f32_16x16x32_bf16 v[12:15], v[156:159], v[204:207], v[12:15]
	v_mfma_f32_16x16x32_bf16 v[4:7], v[144:147], v[208:211], v[4:7]
	v_mfma_f32_16x16x32_bf16 v[4:7], v[148:151], v[212:215], v[4:7]
	s_setprio 3
	s_barrier
	v_mfma_f32_16x16x32_bf16 v[0:3], v[152:155], v[208:211], v[0:3]
	v_mfma_f32_16x16x32_bf16 v[0:3], v[156:159], v[212:215], v[0:3]
	s_setprio 0
	s_add_i32 s45, s45, 2
	s_add_u32 s16, s16, 0x100
	s_addc_u32 s17, s17, 0
	s_add_u32 s43, s43, 0x100
	s_addc_u32 s44, s44, 0
	s_cmp_gt_u32 s45, 41
	s_cbranch_scc0 .LBB0_2341
	s_branch .Lzskip_11
.Lzv_11_0:
	v_mfma_f32_16x16x32_bf16 v[124:127], v[128:131], v[160:163], 0
	v_mfma_f32_16x16x32_bf16 v[124:127], v[132:135], v[180:183], v[124:127]
	v_mfma_f32_16x16x32_bf16 v[120:123], v[136:139], v[160:163], 0
	v_mfma_f32_16x16x32_bf16 v[120:123], v[140:143], v[180:183], v[120:123]
	v_mfma_f32_16x16x32_bf16 v[108:111], v[128:131], v[184:187], 0
	v_mfma_f32_16x16x32_bf16 v[108:111], v[132:135], v[188:191], v[108:111]
	v_mfma_f32_16x16x32_bf16 v[104:107], v[136:139], v[184:187], 0
	v_mfma_f32_16x16x32_bf16 v[104:107], v[140:143], v[188:191], v[104:107]
	v_mfma_f32_16x16x32_bf16 v[96:99], v[128:131], v[200:203], 0
	v_mfma_f32_16x16x32_bf16 v[96:99], v[132:135], v[204:207], v[96:99]
	v_mfma_f32_16x16x32_bf16 v[88:91], v[136:139], v[200:203], 0
	v_mfma_f32_16x16x32_bf16 v[88:91], v[140:143], v[204:207], v[88:91]
	v_mfma_f32_16x16x32_bf16 v[80:83], v[128:131], v[208:211], 0
	v_mfma_f32_16x16x32_bf16 v[80:83], v[132:135], v[212:215], v[80:83]
	v_mfma_f32_16x16x32_bf16 v[72:75], v[136:139], v[208:211], 0
	v_mfma_f32_16x16x32_bf16 v[72:75], v[140:143], v[212:215], v[72:75]
	v_mfma_f32_16x16x32_bf16 v[116:119], v[144:147], v[160:163], 0
	v_mfma_f32_16x16x32_bf16 v[116:119], v[148:151], v[180:183], v[116:119]
	v_mfma_f32_16x16x32_bf16 v[112:115], v[152:155], v[160:163], 0
	v_mfma_f32_16x16x32_bf16 v[112:115], v[156:159], v[180:183], v[112:115]
	v_mfma_f32_16x16x32_bf16 v[100:103], v[144:147], v[184:187], 0
	v_mfma_f32_16x16x32_bf16 v[100:103], v[148:151], v[188:191], v[100:103]
	v_mfma_f32_16x16x32_bf16 v[92:95], v[152:155], v[184:187], 0
	v_mfma_f32_16x16x32_bf16 v[92:95], v[156:159], v[188:191], v[92:95]
	v_mfma_f32_16x16x32_bf16 v[84:87], v[144:147], v[200:203], 0
	v_mfma_f32_16x16x32_bf16 v[84:87], v[148:151], v[204:207], v[84:87]
	v_mfma_f32_16x16x32_bf16 v[76:79], v[152:155], v[200:203], 0
	v_mfma_f32_16x16x32_bf16 v[76:79], v[156:159], v[204:207], v[76:79]
	v_mfma_f32_16x16x32_bf16 v[68:71], v[144:147], v[208:211], 0
	v_mfma_f32_16x16x32_bf16 v[68:71], v[148:151], v[212:215], v[68:71]
	s_setprio 3
	s_barrier
	v_mfma_f32_16x16x32_bf16 v[64:67], v[152:155], v[208:211], 0
	v_mfma_f32_16x16x32_bf16 v[64:67], v[156:159], v[212:215], v[64:67]
	s_setprio 0
	s_branch .Lzj_11_0
.Lzv_11_1:
	v_mfma_f32_16x16x32_bf16 v[60:63], v[128:131], v[160:163], 0
	v_mfma_f32_16x16x32_bf16 v[60:63], v[132:135], v[180:183], v[60:63]
	v_mfma_f32_16x16x32_bf16 v[56:59], v[136:139], v[160:163], 0
	v_mfma_f32_16x16x32_bf16 v[56:59], v[140:143], v[180:183], v[56:59]
	v_mfma_f32_16x16x32_bf16 v[48:51], v[128:131], v[184:187], 0
	v_mfma_f32_16x16x32_bf16 v[48:51], v[132:135], v[188:191], v[48:51]
	v_mfma_f32_16x16x32_bf16 v[40:43], v[136:139], v[184:187], 0
	v_mfma_f32_16x16x32_bf16 v[40:43], v[140:143], v[188:191], v[40:43]
	v_mfma_f32_16x16x32_bf16 v[32:35], v[128:131], v[200:203], 0
	v_mfma_f32_16x16x32_bf16 v[32:35], v[132:135], v[204:207], v[32:35]
	v_mfma_f32_16x16x32_bf16 v[24:27], v[136:139], v[200:203], 0
	v_mfma_f32_16x16x32_bf16 v[24:27], v[140:143], v[204:207], v[24:27]
	v_mfma_f32_16x16x32_bf16 v[16:19], v[128:131], v[208:211], 0
	v_mfma_f32_16x16x32_bf16 v[16:19], v[132:135], v[212:215], v[16:19]
	v_mfma_f32_16x16x32_bf16 v[8:11], v[136:139], v[208:211], 0
	v_mfma_f32_16x16x32_bf16 v[8:11], v[140:143], v[212:215], v[8:11]
	v_mfma_f32_16x16x32_bf16 v[52:55], v[144:147], v[160:163], 0
	v_mfma_f32_16x16x32_bf16 v[52:55], v[148:151], v[180:183], v[52:55]
	v_mfma_f32_16x16x32_bf16 v[44:47], v[152:155], v[160:163], 0
	v_mfma_f32_16x16x32_bf16 v[44:47], v[156:159], v[180:183], v[44:47]
	v_mfma_f32_16x16x32_bf16 v[36:39], v[144:147], v[184:187], 0
	v_mfma_f32_16x16x32_bf16 v[36:39], v[148:151], v[188:191], v[36:39]
	v_mfma_f32_16x16x32_bf16 v[28:31], v[152:155], v[184:187], 0
	v_mfma_f32_16x16x32_bf16 v[28:31], v[156:159], v[188:191], v[28:31]
	v_mfma_f32_16x16x32_bf16 v[20:23], v[144:147], v[200:203], 0
	v_mfma_f32_16x16x32_bf16 v[20:23], v[148:151], v[204:207], v[20:23]
	v_mfma_f32_16x16x32_bf16 v[12:15], v[152:155], v[200:203], 0
	v_mfma_f32_16x16x32_bf16 v[12:15], v[156:159], v[204:207], v[12:15]
	v_mfma_f32_16x16x32_bf16 v[4:7], v[144:147], v[208:211], 0
	v_mfma_f32_16x16x32_bf16 v[4:7], v[148:151], v[212:215], v[4:7]
	s_setprio 3
	s_barrier
	v_mfma_f32_16x16x32_bf16 v[0:3], v[152:155], v[208:211], 0
	v_mfma_f32_16x16x32_bf16 v[0:3], v[156:159], v[212:215], v[0:3]
	s_setprio 0
	s_branch .Lzj_11_1
.Lzskip_11:
	s_and_b64 vcc, exec, s[10:11]
	s_cbranch_vccz .LBB0_2344
	s_barrier
